# dropped 36 redundant post-barrier lgkmcnt(0) waits in the GEMM K-loops (already drained before the barrier)
# speedup vs baseline: 1.0054x; 1.0054x over previous
; #define PG8_STAGE(bufoff, gbase, voff) do { _Pragma("unroll") for (int _i = 0; _i < 2; ++_i) \
;         __builtin_amdgcn_global_load_lds((const unsigned*)((const char*)(gbase) + (voff)[_i]), (LAS unsigned*)(lds + (bufoff) + ldsw + _i * 8192), 16, 0, 0); } while (0)
; #define PG8_WAIT_V(n) asm volatile("s_waitcnt vmcnt(" #n ")" ::: "memory")
; #define PG8_WAIT_L(n) asm volatile("s_waitcnt lgkmcnt(" #n ")" ::: "memory")
; #define PG8_BAR __builtin_amdgcn_s_barrier()
; #define PG8_SCHED __builtin_amdgcn_sched_barrier(0)
; template <bool F8 = false, class Epi, class Sched>
; __device__ __forceinline__ void gemm_phase(LAS unsigned char* lds, const int lda, const int ldb, const int K, const Sched& S, const Epi& E) {
;     ...
;             const bool last = (t == nt - 2);
;             const char* a1 = cA + (size_t)(t + 1) * kstep;
;             const char* a2 = last ? nA : cA + (size_t)(t + 2) * kstep; const char* b2 = last ? nB : cB + (size_t)(t + 2) * kstep;
;             const char* a3 = a2 + kstep; const char* b3 = b2 + kstep;
;             PG8_LDB(B0, 0, 0); PG8_LDB(B1, 0, 1); PG8_SCHED; PG8_LDA(At, 0, 0); PG8_STAGE(PG8_SA(1, 1), a1 + hstepA, voffA);
;             PG8_WAIT_V(8); PG8_WAIT_L(0); PG8_BAR; PG8_MMA(0, 0, At, B0); PG8_MMA(0, 1, At, B1); PG8_BAR; PG8_SCHED;
;             PG8_LDA(At, 0, 1); PG8_STAGE(PG8_SB(0, 0), b2, voffB); PG8_STAGE(PG8_SB(0, 1), b2 + hstepB, voffB); PG8_STAGE(PG8_SA(0, 0), a2, voffA);
;             PG8_WAIT_V(8); PG8_WAIT_L(0); PG8_BAR; PG8_MMA(1, 0, At, B0); PG8_MMA(1, 1, At, B1); PG8_BAR; PG8_SCHED;
.LBB0_242:
	s_add_u32 s29, s72, 0xfff80080
	s_addc_u32 s30, s73, -1
	s_add_i32 s31, 0, 0x10000
	s_cmp_eq_u32 s28, 28
	s_cselect_b32 s75, s5, s30
	s_cselect_b32 s74, s13, s29
	s_cselect_b32 s53, s11, vcc_hi
	s_cselect_b32 s52, s15, vcc_lo
	s_add_i32 s29, 0, 0x14000
	v_add_u32_e32 v158, s31, v147
	v_add_u32_e32 v174, s29, v147
	ds_read_b128 v[142:145], v158
	ds_read_b128 v[150:153], v158 offset:1024
	ds_read_b128 v[154:157], v158 offset:2048
	ds_read_b128 v[158:161], v158 offset:3072
	ds_read_b128 v[162:165], v174
	ds_read_b128 v[166:169], v174 offset:1024
	ds_read_b128 v[170:173], v174 offset:2048
	ds_read_b128 v[174:177], v174 offset:3072
	v_lshl_add_u64 v[194:195], s[72:73], 0, v[136:137]
	s_add_i32 m0, s26, 0xc000
	ds_read_b128 v[178:181], v149
	ds_read_b128 v[182:185], v149 offset:1024
	ds_read_b128 v[186:189], v149 offset:2048
	ds_read_b128 v[190:193], v149 offset:3072
	ds_read_b128 v[202:205], v149 offset:4096
	ds_read_b128 v[206:209], v149 offset:5120
	ds_read_b128 v[210:213], v149 offset:6144
	ds_read_b128 v[214:217], v149 offset:7168
	global_load_lds_dwordx4 v[194:195], off
	v_lshl_add_u64 v[194:195], s[72:73], 0, v[138:139]
	s_add_i32 m0, s26, 0xe000
	s_nop 0
	global_load_lds_dwordx4 v[194:195], off
	s_waitcnt vmcnt(8)
	s_waitcnt lgkmcnt(0)
	s_barrier
	s_setprio 1
	v_mfma_f32_16x16x32_bf16 v[126:129], v[142:145], v[178:181], v[126:129]
	v_mfma_f32_16x16x32_bf16 v[122:125], v[154:157], v[178:181], v[122:125]
	v_mfma_f32_16x16x32_bf16 v[114:117], v[142:145], v[186:189], v[114:117]
	v_mfma_f32_16x16x32_bf16 v[106:109], v[154:157], v[186:189], v[106:109]
	v_mfma_f32_16x16x32_bf16 v[98:101], v[142:145], v[202:205], v[98:101]
	v_mfma_f32_16x16x32_bf16 v[90:93], v[154:157], v[202:205], v[90:93]
	v_mfma_f32_16x16x32_bf16 v[82:85], v[142:145], v[210:213], v[82:85]
	v_mfma_f32_16x16x32_bf16 v[74:77], v[154:157], v[210:213], v[74:77]
	v_mfma_f32_16x16x32_bf16 v[126:129], v[150:153], v[182:185], v[126:129]
	v_mfma_f32_16x16x32_bf16 v[122:125], v[158:161], v[182:185], v[122:125]
	v_mfma_f32_16x16x32_bf16 v[114:117], v[150:153], v[190:193], v[114:117]
	v_mfma_f32_16x16x32_bf16 v[106:109], v[158:161], v[190:193], v[106:109]
	v_mfma_f32_16x16x32_bf16 v[98:101], v[150:153], v[206:209], v[98:101]
	v_mfma_f32_16x16x32_bf16 v[90:93], v[158:161], v[206:209], v[90:93]
	v_mfma_f32_16x16x32_bf16 v[82:85], v[150:153], v[214:217], v[82:85]
	v_mfma_f32_16x16x32_bf16 v[74:77], v[158:161], v[214:217], v[74:77]
	s_setprio 0
	s_setprio 1
	v_mfma_f32_16x16x32_bf16 v[118:121], v[162:165], v[178:181], v[118:121]
	v_mfma_f32_16x16x32_bf16 v[110:113], v[170:173], v[178:181], v[110:113]
	v_mfma_f32_16x16x32_bf16 v[102:105], v[162:165], v[186:189], v[102:105]
	v_mfma_f32_16x16x32_bf16 v[94:97], v[170:173], v[186:189], v[94:97]
	v_mfma_f32_16x16x32_bf16 v[86:89], v[162:165], v[202:205], v[86:89]
	v_mfma_f32_16x16x32_bf16 v[78:81], v[170:173], v[202:205], v[78:81]
	v_mfma_f32_16x16x32_bf16 v[70:73], v[162:165], v[210:213], v[70:73]
	v_mfma_f32_16x16x32_bf16 v[66:69], v[170:173], v[210:213], v[66:69]
	v_mfma_f32_16x16x32_bf16 v[118:121], v[166:169], v[182:185], v[118:121]
	v_mfma_f32_16x16x32_bf16 v[110:113], v[174:177], v[182:185], v[110:113]
	v_mfma_f32_16x16x32_bf16 v[102:105], v[166:169], v[190:193], v[102:105]
	v_mfma_f32_16x16x32_bf16 v[94:97], v[174:177], v[190:193], v[94:97]
	v_mfma_f32_16x16x32_bf16 v[86:89], v[166:169], v[206:209], v[86:89]
	v_mfma_f32_16x16x32_bf16 v[78:81], v[174:177], v[206:209], v[78:81]
	v_mfma_f32_16x16x32_bf16 v[70:73], v[166:169], v[214:217], v[70:73]
	v_mfma_f32_16x16x32_bf16 v[66:69], v[174:177], v[214:217], v[66:69]
	s_setprio 0
	s_barrier
	s_add_i32 s30, s31, s25
	v_lshl_add_u64 v[194:195], s[52:53], 0, v[0:1]
	s_mov_b32 m0, s30
	ds_read_b128 v[178:181], v149 offset:16384
	ds_read_b128 v[182:185], v149 offset:17408
	ds_read_b128 v[186:189], v149 offset:18432
	ds_read_b128 v[190:193], v149 offset:19456
	ds_read_b128 v[202:205], v149 offset:20480
	ds_read_b128 v[206:209], v149 offset:21504
	ds_read_b128 v[210:213], v149 offset:22528
	ds_read_b128 v[214:217], v149 offset:23552
	global_load_lds_dwordx4 v[194:195], off
	s_add_i32 m0, s30, 0x2000
	s_add_u32 s30, s52, 0x80000
	v_lshl_add_u64 v[218:219], s[52:53], 0, v[134:135]
	s_addc_u32 s31, s53, 0
	s_add_i32 s29, s29, s25
	global_load_lds_dwordx4 v[218:219], off
	v_lshl_add_u64 v[220:221], s[30:31], 0, v[0:1]
	s_mov_b32 m0, s29
	v_lshl_add_u64 v[222:223], s[74:75], 0, v[132:133]
	global_load_lds_dwordx4 v[220:221], off
	v_lshl_add_u64 v[220:221], s[30:31], 0, v[134:135]
	s_add_i32 m0, s29, 0x2000
	s_nop 0
	global_load_lds_dwordx4 v[220:221], off
	v_lshl_add_u64 v[220:221], s[74:75], 0, v[130:131]
	s_mov_b32 m0, s26
	s_nop 0
	global_load_lds_dwordx4 v[220:221], off
	s_mov_b32 m0, s27
	s_nop 0
	global_load_lds_dwordx4 v[222:223], off
	s_waitcnt vmcnt(8)
	s_waitcnt lgkmcnt(0)
	s_barrier
; #define PG8_STAGE(bufoff, gbase, voff) do { _Pragma("unroll") for (int _i = 0; _i < 2; ++_i) \
;         __builtin_amdgcn_global_load_lds((const unsigned*)((const char*)(gbase) + (voff)[_i]), (LAS unsigned*)(lds + (bufoff) + ldsw + _i * 8192), 16, 0, 0); } while (0)
; #define PG8_WAIT_V(n) asm volatile("s_waitcnt vmcnt(" #n ")" ::: "memory")
; #define PG8_WAIT_L(n) asm volatile("s_waitcnt lgkmcnt(" #n ")" ::: "memory")
; #define PG8_BAR __builtin_amdgcn_s_barrier()
; #define PG8_SCHED __builtin_amdgcn_sched_barrier(0)
; template <bool F8 = false, class Epi, class Sched>
; __device__ __forceinline__ void gemm_phase(LAS unsigned char* lds, const int lda, const int ldb, const int K, const Sched& S, const Epi& E) {
;     ...
;             PG8_WAIT_V(8); PG8_WAIT_L(0); PG8_BAR; PG8_MMA(1, 0, At, B0); PG8_MMA(1, 1, At, B1); PG8_BAR; PG8_SCHED;
;             PG8_LDB(B0, 1, 0); PG8_LDB(B1, 1, 1); PG8_SCHED; PG8_LDA(At, 1, 0); PG8_STAGE(PG8_SA(0, 1), a2 + hstepA, voffA);
;             PG8_WAIT_V(8); PG8_WAIT_L(0); PG8_BAR; PG8_MMA(0, 0, At, B0); PG8_MMA(0, 1, At, B1); PG8_BAR; PG8_SCHED;
	s_setprio 1
	v_mfma_f32_16x16x32_bf16 v[62:65], v[142:145], v[178:181], v[62:65]
	v_mfma_f32_16x16x32_bf16 v[58:61], v[154:157], v[178:181], v[58:61]
	v_mfma_f32_16x16x32_bf16 v[50:53], v[142:145], v[186:189], v[50:53]
	v_mfma_f32_16x16x32_bf16 v[42:45], v[154:157], v[186:189], v[42:45]
	v_mfma_f32_16x16x32_bf16 v[34:37], v[142:145], v[202:205], v[34:37]
	v_mfma_f32_16x16x32_bf16 v[26:29], v[154:157], v[202:205], v[26:29]
	v_mfma_f32_16x16x32_bf16 v[18:21], v[142:145], v[210:213], v[18:21]
	v_mfma_f32_16x16x32_bf16 v[10:13], v[154:157], v[210:213], v[10:13]
	v_mfma_f32_16x16x32_bf16 v[62:65], v[150:153], v[182:185], v[62:65]
	v_mfma_f32_16x16x32_bf16 v[58:61], v[158:161], v[182:185], v[58:61]
	v_mfma_f32_16x16x32_bf16 v[50:53], v[150:153], v[190:193], v[50:53]
	v_mfma_f32_16x16x32_bf16 v[42:45], v[158:161], v[190:193], v[42:45]
	v_mfma_f32_16x16x32_bf16 v[34:37], v[150:153], v[206:209], v[34:37]
	v_mfma_f32_16x16x32_bf16 v[26:29], v[158:161], v[206:209], v[26:29]
	v_mfma_f32_16x16x32_bf16 v[18:21], v[150:153], v[214:217], v[18:21]
	v_mfma_f32_16x16x32_bf16 v[10:13], v[158:161], v[214:217], v[10:13]
	s_setprio 0
	s_setprio 1
	v_mfma_f32_16x16x32_bf16 v[54:57], v[162:165], v[178:181], v[54:57]
	v_mfma_f32_16x16x32_bf16 v[46:49], v[170:173], v[178:181], v[46:49]
	v_mfma_f32_16x16x32_bf16 v[38:41], v[162:165], v[186:189], v[38:41]
	v_mfma_f32_16x16x32_bf16 v[30:33], v[170:173], v[186:189], v[30:33]
	v_mfma_f32_16x16x32_bf16 v[22:25], v[162:165], v[202:205], v[22:25]
	v_mfma_f32_16x16x32_bf16 v[14:17], v[170:173], v[202:205], v[14:17]
	v_mfma_f32_16x16x32_bf16 v[6:9], v[162:165], v[210:213], v[6:9]
	v_mfma_f32_16x16x32_bf16 v[2:5], v[170:173], v[210:213], v[2:5]
	v_mfma_f32_16x16x32_bf16 v[54:57], v[166:169], v[182:185], v[54:57]
	v_mfma_f32_16x16x32_bf16 v[46:49], v[174:177], v[182:185], v[46:49]
	v_mfma_f32_16x16x32_bf16 v[38:41], v[166:169], v[190:193], v[38:41]
	v_mfma_f32_16x16x32_bf16 v[30:33], v[174:177], v[190:193], v[30:33]
	v_mfma_f32_16x16x32_bf16 v[22:25], v[166:169], v[206:209], v[22:25]
	v_mfma_f32_16x16x32_bf16 v[14:17], v[174:177], v[206:209], v[14:17]
	v_mfma_f32_16x16x32_bf16 v[6:9], v[166:169], v[214:217], v[6:9]
	v_mfma_f32_16x16x32_bf16 v[2:5], v[174:177], v[214:217], v[2:5]
	s_setprio 0
	s_barrier
	s_add_i32 s29, 0, 0x18000
	s_add_i32 s33, 0, 0x1c000
	v_add_u32_e32 v158, s29, v147
	v_add_u32_e32 v174, s33, v147
	ds_read_b128 v[142:145], v158
	ds_read_b128 v[150:153], v158 offset:1024
	ds_read_b128 v[154:157], v158 offset:2048
	ds_read_b128 v[158:161], v158 offset:3072
	ds_read_b128 v[162:165], v174
	ds_read_b128 v[166:169], v174 offset:1024
	ds_read_b128 v[170:173], v174 offset:2048
	ds_read_b128 v[174:177], v174 offset:3072
	s_add_u32 s30, s74, 0x80000
	s_addc_u32 s31, s75, 0
	s_mov_b32 m0, s56
	v_lshl_add_u64 v[224:225], s[30:31], 0, v[130:131]
	ds_read_b128 v[178:181], v149 offset:32768
	ds_read_b128 v[182:185], v149 offset:33792
	ds_read_b128 v[186:189], v149 offset:34816
	ds_read_b128 v[190:193], v149 offset:35840
	ds_read_b128 v[202:205], v149 offset:36864
	ds_read_b128 v[206:209], v149 offset:37888
	ds_read_b128 v[210:213], v149 offset:38912
	ds_read_b128 v[214:217], v149 offset:39936
	global_load_lds_dwordx4 v[224:225], off
	v_lshl_add_u64 v[224:225], s[30:31], 0, v[132:133]
	s_mov_b32 m0, s57
	s_nop 0
	global_load_lds_dwordx4 v[224:225], off
	s_waitcnt vmcnt(8)
	s_waitcnt lgkmcnt(0)
	s_barrier
	s_setprio 1
	v_mfma_f32_16x16x32_bf16 v[126:129], v[142:145], v[178:181], v[126:129]
	v_mfma_f32_16x16x32_bf16 v[122:125], v[154:157], v[178:181], v[122:125]
	v_mfma_f32_16x16x32_bf16 v[114:117], v[142:145], v[186:189], v[114:117]
	v_mfma_f32_16x16x32_bf16 v[106:109], v[154:157], v[186:189], v[106:109]
	v_mfma_f32_16x16x32_bf16 v[98:101], v[142:145], v[202:205], v[98:101]
	v_mfma_f32_16x16x32_bf16 v[90:93], v[154:157], v[202:205], v[90:93]
	v_mfma_f32_16x16x32_bf16 v[82:85], v[142:145], v[210:213], v[82:85]
	v_mfma_f32_16x16x32_bf16 v[74:77], v[154:157], v[210:213], v[74:77]
	v_mfma_f32_16x16x32_bf16 v[126:129], v[150:153], v[182:185], v[126:129]
	v_mfma_f32_16x16x32_bf16 v[122:125], v[158:161], v[182:185], v[122:125]
	v_mfma_f32_16x16x32_bf16 v[114:117], v[150:153], v[190:193], v[114:117]
	v_mfma_f32_16x16x32_bf16 v[106:109], v[158:161], v[190:193], v[106:109]
	v_mfma_f32_16x16x32_bf16 v[98:101], v[150:153], v[206:209], v[98:101]
	v_mfma_f32_16x16x32_bf16 v[90:93], v[158:161], v[206:209], v[90:93]
	v_mfma_f32_16x16x32_bf16 v[82:85], v[150:153], v[214:217], v[82:85]
	v_mfma_f32_16x16x32_bf16 v[74:77], v[158:161], v[214:217], v[74:77]
	s_setprio 0
	s_setprio 1
	v_mfma_f32_16x16x32_bf16 v[118:121], v[162:165], v[178:181], v[118:121]
	v_mfma_f32_16x16x32_bf16 v[110:113], v[170:173], v[178:181], v[110:113]
	v_mfma_f32_16x16x32_bf16 v[102:105], v[162:165], v[186:189], v[102:105]
	v_mfma_f32_16x16x32_bf16 v[94:97], v[170:173], v[186:189], v[94:97]
	v_mfma_f32_16x16x32_bf16 v[86:89], v[162:165], v[202:205], v[86:89]
	v_mfma_f32_16x16x32_bf16 v[78:81], v[170:173], v[202:205], v[78:81]
	v_mfma_f32_16x16x32_bf16 v[70:73], v[162:165], v[210:213], v[70:73]
	v_mfma_f32_16x16x32_bf16 v[66:69], v[170:173], v[210:213], v[66:69]
	v_mfma_f32_16x16x32_bf16 v[118:121], v[166:169], v[182:185], v[118:121]
	v_mfma_f32_16x16x32_bf16 v[110:113], v[174:177], v[182:185], v[110:113]
	v_mfma_f32_16x16x32_bf16 v[102:105], v[166:169], v[190:193], v[102:105]
	v_mfma_f32_16x16x32_bf16 v[94:97], v[174:177], v[190:193], v[94:97]
	v_mfma_f32_16x16x32_bf16 v[86:89], v[166:169], v[206:209], v[86:89]
	v_mfma_f32_16x16x32_bf16 v[78:81], v[174:177], v[206:209], v[78:81]
	v_mfma_f32_16x16x32_bf16 v[70:73], v[166:169], v[214:217], v[70:73]
	v_mfma_f32_16x16x32_bf16 v[66:69], v[174:177], v[214:217], v[66:69]
	s_setprio 0
	s_barrier
; #define PG8_STAGE(bufoff, gbase, voff) do { _Pragma("unroll") for (int _i = 0; _i < 2; ++_i) \
;         __builtin_amdgcn_global_load_lds((const unsigned*)((const char*)(gbase) + (voff)[_i]), (LAS unsigned*)(lds + (bufoff) + ldsw + _i * 8192), 16, 0, 0); } while (0)
; #define PG8_WAIT_V(n) asm volatile("s_waitcnt vmcnt(" #n ")" ::: "memory")
; #define PG8_WAIT_L(n) asm volatile("s_waitcnt lgkmcnt(" #n ")" ::: "memory")
; #define PG8_BAR __builtin_amdgcn_s_barrier()
; #define PG8_SCHED __builtin_amdgcn_sched_barrier(0)
; template <bool F8 = false, class Epi, class Sched>
; __device__ __forceinline__ void gemm_phase(LAS unsigned char* lds, const int lda, const int ldb, const int K, const Sched& S, const Epi& E) {
;     ...
;             PG8_LDA(At, 1, 1); PG8_STAGE(PG8_SB(1, 0), b3, voffB); PG8_STAGE(PG8_SB(1, 1), b3 + hstepB, voffB); PG8_STAGE(PG8_SA(1, 0), a3, voffA);
;             PG8_WAIT_V(8); PG8_WAIT_L(0); PG8_BAR; PG8_MMA(1, 0, At, B0); PG8_MMA(1, 1, At, B1); PG8_BAR; PG8_SCHED;
;         }
;         if (wr == 0) PG8_BAR;
	s_add_i32 s29, s29, s25
	v_lshl_add_u64 v[194:195], v[194:195], 0, s[40:41]
	s_mov_b32 m0, s29
	ds_read_b128 v[178:181], v149 offset:49152
	ds_read_b128 v[182:185], v149 offset:50176
	ds_read_b128 v[186:189], v149 offset:51200
	ds_read_b128 v[190:193], v149 offset:52224
	ds_read_b128 v[202:205], v149 offset:53248
	ds_read_b128 v[206:209], v149 offset:54272
	ds_read_b128 v[210:213], v149 offset:55296
	ds_read_b128 v[214:217], v149 offset:56320
	global_load_lds_dwordx4 v[194:195], off
	s_add_i32 m0, s29, 0x2000
	s_add_u32 s30, s52, 0x80080
	v_lshl_add_u64 v[194:195], v[218:219], 0, s[40:41]
	s_addc_u32 s31, s53, 0
	s_add_i32 s29, s33, s25
	global_load_lds_dwordx4 v[194:195], off
	v_lshl_add_u64 v[194:195], s[30:31], 0, v[0:1]
	s_mov_b32 m0, s29
	s_nop 0
	global_load_lds_dwordx4 v[194:195], off
	v_lshl_add_u64 v[194:195], s[30:31], 0, v[134:135]
	s_add_i32 m0, s29, 0x2000
	s_nop 0
	global_load_lds_dwordx4 v[194:195], off
	v_lshl_add_u64 v[194:195], v[220:221], 0, s[40:41]
	s_mov_b32 m0, s94
	s_nop 0
	global_load_lds_dwordx4 v[194:195], off
	v_lshl_add_u64 v[194:195], v[222:223], 0, s[40:41]
	s_mov_b32 m0, s95
	s_nop 0
	global_load_lds_dwordx4 v[194:195], off
	s_waitcnt vmcnt(8)
	s_waitcnt lgkmcnt(0)
	s_barrier
	s_setprio 1
	v_mfma_f32_16x16x32_bf16 v[62:65], v[142:145], v[178:181], v[62:65]
	v_mfma_f32_16x16x32_bf16 v[58:61], v[154:157], v[178:181], v[58:61]
	v_mfma_f32_16x16x32_bf16 v[50:53], v[142:145], v[186:189], v[50:53]
	v_mfma_f32_16x16x32_bf16 v[42:45], v[154:157], v[186:189], v[42:45]
	v_mfma_f32_16x16x32_bf16 v[34:37], v[142:145], v[202:205], v[34:37]
	v_mfma_f32_16x16x32_bf16 v[26:29], v[154:157], v[202:205], v[26:29]
	v_mfma_f32_16x16x32_bf16 v[18:21], v[142:145], v[210:213], v[18:21]
	v_mfma_f32_16x16x32_bf16 v[10:13], v[154:157], v[210:213], v[10:13]
	v_mfma_f32_16x16x32_bf16 v[62:65], v[150:153], v[182:185], v[62:65]
	v_mfma_f32_16x16x32_bf16 v[58:61], v[158:161], v[182:185], v[58:61]
	v_mfma_f32_16x16x32_bf16 v[50:53], v[150:153], v[190:193], v[50:53]
	v_mfma_f32_16x16x32_bf16 v[42:45], v[158:161], v[190:193], v[42:45]
	v_mfma_f32_16x16x32_bf16 v[34:37], v[150:153], v[206:209], v[34:37]
	v_mfma_f32_16x16x32_bf16 v[26:29], v[158:161], v[206:209], v[26:29]
	v_mfma_f32_16x16x32_bf16 v[18:21], v[150:153], v[214:217], v[18:21]
	v_mfma_f32_16x16x32_bf16 v[10:13], v[158:161], v[214:217], v[10:13]
	s_setprio 0
	s_setprio 1
	v_mfma_f32_16x16x32_bf16 v[54:57], v[162:165], v[178:181], v[54:57]
	v_mfma_f32_16x16x32_bf16 v[46:49], v[170:173], v[178:181], v[46:49]
	v_mfma_f32_16x16x32_bf16 v[38:41], v[162:165], v[186:189], v[38:41]
	v_mfma_f32_16x16x32_bf16 v[30:33], v[170:173], v[186:189], v[30:33]
	v_mfma_f32_16x16x32_bf16 v[22:25], v[162:165], v[202:205], v[22:25]
	v_mfma_f32_16x16x32_bf16 v[14:17], v[170:173], v[202:205], v[14:17]
	v_mfma_f32_16x16x32_bf16 v[6:9], v[162:165], v[210:213], v[6:9]
	v_mfma_f32_16x16x32_bf16 v[2:5], v[170:173], v[210:213], v[2:5]
	v_mfma_f32_16x16x32_bf16 v[54:57], v[166:169], v[182:185], v[54:57]
	v_mfma_f32_16x16x32_bf16 v[46:49], v[174:177], v[182:185], v[46:49]
	v_mfma_f32_16x16x32_bf16 v[38:41], v[166:169], v[190:193], v[38:41]
	v_mfma_f32_16x16x32_bf16 v[30:33], v[174:177], v[190:193], v[30:33]
	v_mfma_f32_16x16x32_bf16 v[22:25], v[166:169], v[206:209], v[22:25]
	v_mfma_f32_16x16x32_bf16 v[14:17], v[174:177], v[206:209], v[14:17]
	v_mfma_f32_16x16x32_bf16 v[6:9], v[166:169], v[214:217], v[6:9]
	v_mfma_f32_16x16x32_bf16 v[2:5], v[174:177], v[214:217], v[2:5]
	s_setprio 0
	s_barrier
	s_add_i32 s28, s28, 2
	s_add_u32 s72, s72, 0x100
	s_addc_u32 s73, s73, 0
	s_add_u32 vcc_lo, vcc_lo, 0x100
	s_addc_u32 vcc_hi, vcc_hi, 0
	s_cmp_gt_u32 s28, 29
	s_cbranch_scc0 .LBB0_242
	s_and_b64 vcc, exec, s[8:9]
	s_cbranch_vccz .LBB0_245
	s_barrier

; #define PG8_STAGE(bufoff, gbase, voff) do { _Pragma("unroll") for (int _i = 0; _i < 2; ++_i) \
;         __builtin_amdgcn_global_load_lds((const unsigned*)((const char*)(gbase) + (voff)[_i]), (LAS unsigned*)(lds + (bufoff) + ldsw + _i * 8192), 16, 0, 0); } while (0)
; #define PG8_WAIT_V(n) asm volatile("s_waitcnt vmcnt(" #n ")" ::: "memory")
; #define PG8_WAIT_L(n) asm volatile("s_waitcnt lgkmcnt(" #n ")" ::: "memory")
; #define PG8_BAR __builtin_amdgcn_s_barrier()
; #define PG8_SCHED __builtin_amdgcn_sched_barrier(0)
; template <bool F8 = false, class Epi, class Sched>
; __device__ __forceinline__ void gemm_phase(LAS unsigned char* lds, const int lda, const int ldb, const int K, const Sched& S, const Epi& E) {
;     ...
;             const bool last = (t == nt - 2);
;             const char* a1 = cA + (size_t)(t + 1) * kstep;
;             const char* a2 = last ? nA : cA + (size_t)(t + 2) * kstep; const char* b2 = last ? nB : cB + (size_t)(t + 2) * kstep;
;             const char* a3 = a2 + kstep; const char* b3 = b2 + kstep;
;             PG8_LDB(B0, 0, 0); PG8_LDB(B1, 0, 1); PG8_SCHED; PG8_LDA(At, 0, 0); PG8_STAGE(PG8_SA(1, 1), a1 + hstepA, voffA);
;             PG8_WAIT_V(8); PG8_WAIT_L(0); PG8_BAR; PG8_MMA(0, 0, At, B0); PG8_MMA(0, 1, At, B1); PG8_BAR; PG8_SCHED;
;             PG8_LDA(At, 0, 1); PG8_STAGE(PG8_SB(0, 0), b2, voffB); PG8_STAGE(PG8_SB(0, 1), b2 + hstepB, voffB); PG8_STAGE(PG8_SA(0, 0), a2, voffA);
;             PG8_WAIT_V(8); PG8_WAIT_L(0); PG8_BAR; PG8_MMA(1, 0, At, B0); PG8_MMA(1, 1, At, B1); PG8_BAR; PG8_SCHED;
.LBB0_292:
	s_add_u32 s29, s72, 0xfffc0080
	s_addc_u32 s30, s73, -1
	s_add_i32 s28, 0, 0x10000
	s_cmp_eq_u32 s97, 12
	s_cselect_b32 s53, s11, s30
	s_cselect_b32 s52, s13, s29
	s_cselect_b32 vcc_hi, s9, s19
	s_cselect_b32 vcc_lo, s96, s18
	s_add_i32 s29, 0, 0x14000
	v_add_u32_e32 v2, s28, v177
	v_add_u32_e32 v14, s29, v177
	ds_read_b128 v[18:21], v2
	ds_read_b128 v[22:25], v2 offset:1024
	ds_read_b128 v[26:29], v2 offset:2048
	ds_read_b128 v[30:33], v2 offset:3072
	ds_read_b128 v[2:5], v14
	ds_read_b128 v[6:9], v14 offset:1024
	ds_read_b128 v[10:13], v14 offset:2048
	ds_read_b128 v[14:17], v14 offset:3072
	v_lshl_add_u64 v[210:211], s[72:73], 0, v[164:165]
	s_add_i32 m0, s15, 0xc000
	ds_read_b128 v[168:171], v179
	ds_read_b128 v[172:175], v179 offset:1024
	ds_read_b128 v[180:183], v179 offset:2048
	ds_read_b128 v[184:187], v179 offset:3072
	ds_read_b128 v[188:191], v179 offset:4096
	ds_read_b128 v[192:195], v179 offset:5120
	ds_read_b128 v[202:205], v179 offset:6144
	ds_read_b128 v[206:209], v179 offset:7168
	global_load_lds_dwordx4 v[210:211], off
	v_lshl_add_u64 v[210:211], s[72:73], 0, v[166:167]
	s_add_i32 m0, s15, 0xe000
	s_nop 0
	global_load_lds_dwordx4 v[210:211], off
	s_waitcnt vmcnt(8)
	s_waitcnt lgkmcnt(0)
	s_barrier
	s_setprio 1
	v_mfma_scale_f32_16x16x128_f8f6f4 v[158:161], v[18:25], v[168:175], v[158:161], v236, v236 op_sel_hi:[0,0,0]
	v_mfma_scale_f32_16x16x128_f8f6f4 v[154:157], v[26:33], v[168:175], v[154:157], v236, v236 op_sel_hi:[0,0,0]
	v_mfma_scale_f32_16x16x128_f8f6f4 v[150:153], v[18:25], v[180:187], v[150:153], v236, v236 op_sel_hi:[0,0,0]
	v_mfma_scale_f32_16x16x128_f8f6f4 v[142:145], v[26:33], v[180:187], v[142:145], v236, v236 op_sel_hi:[0,0,0]
	v_mfma_scale_f32_16x16x128_f8f6f4 v[134:137], v[18:25], v[188:195], v[134:137], v236, v236 op_sel_hi:[0,0,0]
	v_mfma_scale_f32_16x16x128_f8f6f4 v[126:129], v[26:33], v[188:195], v[126:129], v236, v236 op_sel_hi:[0,0,0]
	v_mfma_scale_f32_16x16x128_f8f6f4 v[118:121], v[18:25], v[202:209], v[118:121], v236, v236 op_sel_hi:[0,0,0]
	v_mfma_scale_f32_16x16x128_f8f6f4 v[110:113], v[26:33], v[202:209], v[110:113], v236, v236 op_sel_hi:[0,0,0]
	s_setprio 0
	s_setprio 1
	v_mfma_scale_f32_16x16x128_f8f6f4 v[146:149], v[2:9], v[168:175], v[146:149], v236, v236 op_sel_hi:[0,0,0]
	v_mfma_scale_f32_16x16x128_f8f6f4 v[138:141], v[10:17], v[168:175], v[138:141], v236, v236 op_sel_hi:[0,0,0]
	v_mfma_scale_f32_16x16x128_f8f6f4 v[130:133], v[2:9], v[180:187], v[130:133], v236, v236 op_sel_hi:[0,0,0]
	v_mfma_scale_f32_16x16x128_f8f6f4 v[122:125], v[10:17], v[180:187], v[122:125], v236, v236 op_sel_hi:[0,0,0]
	v_mfma_scale_f32_16x16x128_f8f6f4 v[114:117], v[2:9], v[188:195], v[114:117], v236, v236 op_sel_hi:[0,0,0]
	v_mfma_scale_f32_16x16x128_f8f6f4 v[106:109], v[10:17], v[188:195], v[106:109], v236, v236 op_sel_hi:[0,0,0]
	v_mfma_scale_f32_16x16x128_f8f6f4 v[102:105], v[2:9], v[202:209], v[102:105], v236, v236 op_sel_hi:[0,0,0]
	v_mfma_scale_f32_16x16x128_f8f6f4 v[98:101], v[10:17], v[202:209], v[98:101], v236, v236 op_sel_hi:[0,0,0]
	s_setprio 0
	s_barrier
	s_add_i32 s28, s28, s24
	v_lshl_add_u64 v[168:169], vcc, 0, v[0:1]
	s_mov_b32 m0, s28
	ds_read_b128 v[180:183], v179 offset:16384
	ds_read_b128 v[184:187], v179 offset:17408
	ds_read_b128 v[188:191], v179 offset:18432
	ds_read_b128 v[192:195], v179 offset:19456
	ds_read_b128 v[202:205], v179 offset:20480
	ds_read_b128 v[206:209], v179 offset:21504
	ds_read_b128 v[210:213], v179 offset:22528
	ds_read_b128 v[214:217], v179 offset:23552
	global_load_lds_dwordx4 v[168:169], off
	s_add_i32 m0, s28, 0x2000
	s_add_u32 s30, vcc_lo, 0x40000
	v_lshl_add_u64 v[170:171], vcc, 0, v[162:163]
	s_addc_u32 s31, vcc_hi, 0
	s_add_i32 s28, s29, s24
	global_load_lds_dwordx4 v[170:171], off
	v_lshl_add_u64 v[172:173], s[30:31], 0, v[0:1]
	s_mov_b32 m0, s28
	v_lshl_add_u64 v[174:175], s[52:53], 0, v[162:163]
	global_load_lds_dwordx4 v[172:173], off
	v_lshl_add_u64 v[172:173], s[30:31], 0, v[162:163]
	s_add_i32 m0, s28, 0x2000
	s_nop 0
	global_load_lds_dwordx4 v[172:173], off
	v_lshl_add_u64 v[172:173], s[52:53], 0, v[0:1]
	s_mov_b32 m0, s15
	s_nop 0
	global_load_lds_dwordx4 v[172:173], off
	s_mov_b32 m0, s26
	s_nop 0
	global_load_lds_dwordx4 v[174:175], off
	s_waitcnt vmcnt(8)
	s_waitcnt lgkmcnt(0)
	s_barrier
	s_setprio 1
	v_mfma_scale_f32_16x16x128_f8f6f4 v[94:97], v[18:25], v[180:187], v[94:97], v236, v236 op_sel_hi:[0,0,0]
	v_mfma_scale_f32_16x16x128_f8f6f4 v[90:93], v[26:33], v[180:187], v[90:93], v236, v236 op_sel_hi:[0,0,0]
	v_mfma_scale_f32_16x16x128_f8f6f4 v[86:89], v[18:25], v[188:195], v[86:89], v236, v236 op_sel_hi:[0,0,0]
	v_mfma_scale_f32_16x16x128_f8f6f4 v[78:81], v[26:33], v[188:195], v[78:81], v236, v236 op_sel_hi:[0,0,0]
	v_mfma_scale_f32_16x16x128_f8f6f4 v[70:73], v[18:25], v[202:209], v[70:73], v236, v236 op_sel_hi:[0,0,0]
	v_mfma_scale_f32_16x16x128_f8f6f4 v[62:65], v[26:33], v[202:209], v[62:65], v236, v236 op_sel_hi:[0,0,0]
	v_mfma_scale_f32_16x16x128_f8f6f4 v[54:57], v[18:25], v[210:217], v[54:57], v236, v236 op_sel_hi:[0,0,0]
	v_mfma_scale_f32_16x16x128_f8f6f4 v[46:49], v[26:33], v[210:217], v[46:49], v236, v236 op_sel_hi:[0,0,0]
	s_setprio 0
	s_setprio 1
	v_mfma_scale_f32_16x16x128_f8f6f4 v[82:85], v[2:9], v[180:187], v[82:85], v236, v236 op_sel_hi:[0,0,0]
	v_mfma_scale_f32_16x16x128_f8f6f4 v[74:77], v[10:17], v[180:187], v[74:77], v236, v236 op_sel_hi:[0,0,0]
	v_mfma_scale_f32_16x16x128_f8f6f4 v[66:69], v[2:9], v[188:195], v[66:69], v236, v236 op_sel_hi:[0,0,0]
	v_mfma_scale_f32_16x16x128_f8f6f4 v[58:61], v[10:17], v[188:195], v[58:61], v236, v236 op_sel_hi:[0,0,0]
	v_mfma_scale_f32_16x16x128_f8f6f4 v[50:53], v[2:9], v[202:209], v[50:53], v236, v236 op_sel_hi:[0,0,0]
	v_mfma_scale_f32_16x16x128_f8f6f4 v[42:45], v[10:17], v[202:209], v[42:45], v236, v236 op_sel_hi:[0,0,0]
	v_mfma_scale_f32_16x16x128_f8f6f4 v[38:41], v[2:9], v[210:217], v[38:41], v236, v236 op_sel_hi:[0,0,0]
	v_mfma_scale_f32_16x16x128_f8f6f4 v[34:37], v[10:17], v[210:217], v[34:37], v236, v236 op_sel_hi:[0,0,0]
	s_setprio 0
	s_barrier
; #define PG8_STAGE(bufoff, gbase, voff) do { _Pragma("unroll") for (int _i = 0; _i < 2; ++_i) \
;         __builtin_amdgcn_global_load_lds((const unsigned*)((const char*)(gbase) + (voff)[_i]), (LAS unsigned*)(lds + (bufoff) + ldsw + _i * 8192), 16, 0, 0); } while (0)
; #define PG8_WAIT_V(n) asm volatile("s_waitcnt vmcnt(" #n ")" ::: "memory")
; #define PG8_WAIT_L(n) asm volatile("s_waitcnt lgkmcnt(" #n ")" ::: "memory")
; #define PG8_BAR __builtin_amdgcn_s_barrier()
; #define PG8_SCHED __builtin_amdgcn_sched_barrier(0)
; template <bool F8 = false, class Epi, class Sched>
; __device__ __forceinline__ void gemm_phase(LAS unsigned char* lds, const int lda, const int ldb, const int K, const Sched& S, const Epi& E) {
;     ...
;             PG8_LDB(B0, 1, 0); PG8_LDB(B1, 1, 1); PG8_SCHED; PG8_LDA(At, 1, 0); PG8_STAGE(PG8_SA(0, 1), a2 + hstepA, voffA);
;             PG8_WAIT_V(8); PG8_WAIT_L(0); PG8_BAR; PG8_MMA(0, 0, At, B0); PG8_MMA(0, 1, At, B1); PG8_BAR; PG8_SCHED;
;             PG8_LDA(At, 1, 1); PG8_STAGE(PG8_SB(1, 0), b3, voffB); PG8_STAGE(PG8_SB(1, 1), b3 + hstepB, voffB); PG8_STAGE(PG8_SA(1, 0), a3, voffA);
;             PG8_WAIT_V(8); PG8_WAIT_L(0); PG8_BAR; PG8_MMA(1, 0, At, B0); PG8_MMA(1, 1, At, B1); PG8_BAR; PG8_SCHED;
;         }
;         if (wr == 0) PG8_BAR;
	s_add_i32 s30, 0, 0x18000
	s_add_i32 s31, 0, 0x1c000
	v_add_u32_e32 v14, s30, v177
	v_add_u32_e32 v30, s31, v177
	ds_read_b128 v[2:5], v14
	ds_read_b128 v[6:9], v14 offset:1024
	ds_read_b128 v[10:13], v14 offset:2048
	ds_read_b128 v[14:17], v14 offset:3072
	ds_read_b128 v[18:21], v30
	ds_read_b128 v[22:25], v30 offset:1024
	ds_read_b128 v[26:29], v30 offset:2048
	ds_read_b128 v[30:33], v30 offset:3072
	s_add_u32 s28, s52, 0x40000
	s_addc_u32 s29, s53, 0
	s_mov_b32 m0, s27
	v_lshl_add_u64 v[218:219], s[28:29], 0, v[0:1]
	ds_read_b128 v[180:183], v179 offset:32768
	ds_read_b128 v[184:187], v179 offset:33792
	ds_read_b128 v[188:191], v179 offset:34816
	ds_read_b128 v[192:195], v179 offset:35840
	ds_read_b128 v[202:205], v179 offset:36864
	ds_read_b128 v[206:209], v179 offset:37888
	ds_read_b128 v[210:213], v179 offset:38912
	ds_read_b128 v[214:217], v179 offset:39936
	global_load_lds_dwordx4 v[218:219], off
	v_lshl_add_u64 v[218:219], s[28:29], 0, v[162:163]
	s_mov_b32 m0, s56
	s_nop 0
	global_load_lds_dwordx4 v[218:219], off
	s_waitcnt vmcnt(8)
	s_waitcnt lgkmcnt(0)
	s_barrier
	s_setprio 1
	v_mfma_scale_f32_16x16x128_f8f6f4 v[158:161], v[2:9], v[180:187], v[158:161], v236, v236 op_sel_hi:[0,0,0]
	v_mfma_scale_f32_16x16x128_f8f6f4 v[154:157], v[10:17], v[180:187], v[154:157], v236, v236 op_sel_hi:[0,0,0]
	v_mfma_scale_f32_16x16x128_f8f6f4 v[150:153], v[2:9], v[188:195], v[150:153], v236, v236 op_sel_hi:[0,0,0]
	v_mfma_scale_f32_16x16x128_f8f6f4 v[142:145], v[10:17], v[188:195], v[142:145], v236, v236 op_sel_hi:[0,0,0]
	v_mfma_scale_f32_16x16x128_f8f6f4 v[134:137], v[2:9], v[202:209], v[134:137], v236, v236 op_sel_hi:[0,0,0]
	v_mfma_scale_f32_16x16x128_f8f6f4 v[126:129], v[10:17], v[202:209], v[126:129], v236, v236 op_sel_hi:[0,0,0]
	v_mfma_scale_f32_16x16x128_f8f6f4 v[118:121], v[2:9], v[210:217], v[118:121], v236, v236 op_sel_hi:[0,0,0]
	v_mfma_scale_f32_16x16x128_f8f6f4 v[110:113], v[10:17], v[210:217], v[110:113], v236, v236 op_sel_hi:[0,0,0]
	s_setprio 0
	s_setprio 1
	v_mfma_scale_f32_16x16x128_f8f6f4 v[146:149], v[18:25], v[180:187], v[146:149], v236, v236 op_sel_hi:[0,0,0]
	v_mfma_scale_f32_16x16x128_f8f6f4 v[138:141], v[26:33], v[180:187], v[138:141], v236, v236 op_sel_hi:[0,0,0]
	v_mfma_scale_f32_16x16x128_f8f6f4 v[130:133], v[18:25], v[188:195], v[130:133], v236, v236 op_sel_hi:[0,0,0]
	v_mfma_scale_f32_16x16x128_f8f6f4 v[122:125], v[26:33], v[188:195], v[122:125], v236, v236 op_sel_hi:[0,0,0]
	v_mfma_scale_f32_16x16x128_f8f6f4 v[114:117], v[18:25], v[202:209], v[114:117], v236, v236 op_sel_hi:[0,0,0]
	v_mfma_scale_f32_16x16x128_f8f6f4 v[106:109], v[26:33], v[202:209], v[106:109], v236, v236 op_sel_hi:[0,0,0]
	v_mfma_scale_f32_16x16x128_f8f6f4 v[102:105], v[18:25], v[210:217], v[102:105], v236, v236 op_sel_hi:[0,0,0]
	v_mfma_scale_f32_16x16x128_f8f6f4 v[98:101], v[26:33], v[210:217], v[98:101], v236, v236 op_sel_hi:[0,0,0]
	s_setprio 0
	s_barrier
	s_add_i32 s28, s30, s24
	v_lshl_add_u64 v[168:169], v[168:169], 0, s[40:41]
	s_mov_b32 m0, s28
	ds_read_b128 v[180:183], v179 offset:49152
	ds_read_b128 v[184:187], v179 offset:50176
	ds_read_b128 v[188:191], v179 offset:51200
	ds_read_b128 v[192:195], v179 offset:52224
	ds_read_b128 v[202:205], v179 offset:53248
	ds_read_b128 v[206:209], v179 offset:54272
	ds_read_b128 v[210:213], v179 offset:55296
	ds_read_b128 v[214:217], v179 offset:56320
	global_load_lds_dwordx4 v[168:169], off
	s_add_i32 m0, s28, 0x2000
	s_add_u32 s28, vcc_lo, 0x40080
	v_lshl_add_u64 v[168:169], v[170:171], 0, s[40:41]
	s_addc_u32 s29, vcc_hi, 0
	s_add_i32 s30, s31, s24
	global_load_lds_dwordx4 v[168:169], off
	v_lshl_add_u64 v[168:169], s[28:29], 0, v[0:1]
	s_mov_b32 m0, s30
	s_nop 0
	global_load_lds_dwordx4 v[168:169], off
	v_lshl_add_u64 v[168:169], s[28:29], 0, v[162:163]
	s_add_i32 m0, s30, 0x2000
	s_nop 0
	global_load_lds_dwordx4 v[168:169], off
	v_lshl_add_u64 v[168:169], v[172:173], 0, s[40:41]
	s_mov_b32 m0, s57
	s_nop 0
	global_load_lds_dwordx4 v[168:169], off
	v_lshl_add_u64 v[168:169], v[174:175], 0, s[40:41]
	s_mov_b32 m0, s94
	s_nop 0
	global_load_lds_dwordx4 v[168:169], off
	s_waitcnt vmcnt(8)
	s_waitcnt lgkmcnt(0)
	s_barrier
	s_setprio 1
	v_mfma_scale_f32_16x16x128_f8f6f4 v[94:97], v[2:9], v[180:187], v[94:97], v236, v236 op_sel_hi:[0,0,0]
	v_mfma_scale_f32_16x16x128_f8f6f4 v[90:93], v[10:17], v[180:187], v[90:93], v236, v236 op_sel_hi:[0,0,0]
	v_mfma_scale_f32_16x16x128_f8f6f4 v[86:89], v[2:9], v[188:195], v[86:89], v236, v236 op_sel_hi:[0,0,0]
	v_mfma_scale_f32_16x16x128_f8f6f4 v[78:81], v[10:17], v[188:195], v[78:81], v236, v236 op_sel_hi:[0,0,0]
	v_mfma_scale_f32_16x16x128_f8f6f4 v[70:73], v[2:9], v[202:209], v[70:73], v236, v236 op_sel_hi:[0,0,0]
	v_mfma_scale_f32_16x16x128_f8f6f4 v[62:65], v[10:17], v[202:209], v[62:65], v236, v236 op_sel_hi:[0,0,0]
	v_mfma_scale_f32_16x16x128_f8f6f4 v[54:57], v[2:9], v[210:217], v[54:57], v236, v236 op_sel_hi:[0,0,0]
	v_mfma_scale_f32_16x16x128_f8f6f4 v[46:49], v[10:17], v[210:217], v[46:49], v236, v236 op_sel_hi:[0,0,0]
	s_setprio 0
	s_setprio 1
	v_mfma_scale_f32_16x16x128_f8f6f4 v[82:85], v[18:25], v[180:187], v[82:85], v236, v236 op_sel_hi:[0,0,0]
	v_mfma_scale_f32_16x16x128_f8f6f4 v[74:77], v[26:33], v[180:187], v[74:77], v236, v236 op_sel_hi:[0,0,0]
	v_mfma_scale_f32_16x16x128_f8f6f4 v[66:69], v[18:25], v[188:195], v[66:69], v236, v236 op_sel_hi:[0,0,0]
	v_mfma_scale_f32_16x16x128_f8f6f4 v[58:61], v[26:33], v[188:195], v[58:61], v236, v236 op_sel_hi:[0,0,0]
	v_mfma_scale_f32_16x16x128_f8f6f4 v[50:53], v[18:25], v[202:209], v[50:53], v236, v236 op_sel_hi:[0,0,0]
	v_mfma_scale_f32_16x16x128_f8f6f4 v[42:45], v[26:33], v[202:209], v[42:45], v236, v236 op_sel_hi:[0,0,0]
	v_mfma_scale_f32_16x16x128_f8f6f4 v[38:41], v[18:25], v[210:217], v[38:41], v236, v236 op_sel_hi:[0,0,0]
	v_mfma_scale_f32_16x16x128_f8f6f4 v[34:37], v[26:33], v[210:217], v[34:37], v236, v236 op_sel_hi:[0,0,0]
	s_setprio 0
	s_barrier
	s_add_i32 s97, s97, 2
	s_add_u32 s72, s72, 0x100
	s_addc_u32 s73, s73, 0
	s_add_u32 s18, s18, 0x100
	s_addc_u32 s19, s19, 0
	s_cmp_gt_u32 s97, 13
	s_cbranch_scc0 .LBB0_292
	s_and_b64 vcc, exec, s[6:7]
	v_readlane_b32 s97, v249, 23
	s_cbranch_vccz .LBB0_295
	s_barrier

; #define PG8_STAGE(bufoff, gbase, voff) do { _Pragma("unroll") for (int _i = 0; _i < 2; ++_i) \
;         __builtin_amdgcn_global_load_lds((const unsigned*)((const char*)(gbase) + (voff)[_i]), (LAS unsigned*)(lds + (bufoff) + ldsw + _i * 8192), 16, 0, 0); } while (0)
; #define PG8_WAIT_V(n) asm volatile("s_waitcnt vmcnt(" #n ")" ::: "memory")
; #define PG8_WAIT_L(n) asm volatile("s_waitcnt lgkmcnt(" #n ")" ::: "memory")
; #define PG8_BAR __builtin_amdgcn_s_barrier()
; #define PG8_SCHED __builtin_amdgcn_sched_barrier(0)
; template <bool F8 = false, class Epi, class Sched>
; __device__ __forceinline__ void gemm_phase(LAS unsigned char* lds, const int lda, const int ldb, const int K, const Sched& S, const Epi& E) {
;     ...
;             const bool last = (t == nt - 2);
;             const char* a1 = cA + (size_t)(t + 1) * kstep;
;             const char* a2 = last ? nA : cA + (size_t)(t + 2) * kstep; const char* b2 = last ? nB : cB + (size_t)(t + 2) * kstep;
;             const char* a3 = a2 + kstep; const char* b3 = b2 + kstep;
;             PG8_LDB(B0, 0, 0); PG8_LDB(B1, 0, 1); PG8_SCHED; PG8_LDA(At, 0, 0); PG8_STAGE(PG8_SA(1, 1), a1 + hstepA, voffA);
;             PG8_WAIT_V(8); PG8_WAIT_L(0); PG8_BAR; PG8_MMA(0, 0, At, B0); PG8_MMA(0, 1, At, B1); PG8_BAR; PG8_SCHED;
;             PG8_LDA(At, 0, 1); PG8_STAGE(PG8_SB(0, 0), b2, voffB); PG8_STAGE(PG8_SB(0, 1), b2 + hstepB, voffB); PG8_STAGE(PG8_SA(0, 0), a2, voffA);
;             PG8_WAIT_V(8); PG8_WAIT_L(0); PG8_BAR; PG8_MMA(1, 0, At, B0); PG8_MMA(1, 1, At, B1); PG8_BAR; PG8_SCHED;
.LBB0_436:
	s_add_u32 s20, s18, 0x100
	s_addc_u32 s21, s19, 0
	s_add_i32 s30, 0, 0x10000
	s_cmp_eq_u32 s29, 4
	s_cselect_b32 s73, s15, s21
	s_cselect_b32 s72, s14, s20
	v_add_u32_e32 v140, s30, v143
	s_cselect_b32 s53, s17, s28
	s_cselect_b32 s52, s16, s11
	s_add_i32 s31, 0, 0x14000
	ds_read_b128 v[146:149], v140
	ds_read_b128 v[150:153], v140 offset:1024
	ds_read_b128 v[154:157], v140 offset:2048
	ds_read_b128 v[158:161], v140 offset:3072
	v_add_u32_e32 v140, s31, v143
	ds_read_b128 v[162:165], v140
	ds_read_b128 v[166:169], v140 offset:1024
	ds_read_b128 v[170:173], v140 offset:2048
	ds_read_b128 v[174:177], v140 offset:3072
	v_lshl_add_u64 v[140:141], s[18:19], 0, v[136:137]
	s_add_i32 m0, s13, 0xc000
	ds_read_b128 v[178:181], v145
	ds_read_b128 v[182:185], v145 offset:1024
	ds_read_b128 v[186:189], v145 offset:2048
	ds_read_b128 v[190:193], v145 offset:3072
	ds_read_b128 v[202:205], v145 offset:4096
	ds_read_b128 v[206:209], v145 offset:5120
	ds_read_b128 v[210:213], v145 offset:6144
	ds_read_b128 v[214:217], v145 offset:7168
	global_load_lds_dwordx4 v[140:141], off
	v_lshl_add_u64 v[140:141], s[18:19], 0, v[138:139]
	s_add_i32 m0, s13, 0xe000
	s_nop 0
	global_load_lds_dwordx4 v[140:141], off
	s_waitcnt vmcnt(8)
	s_waitcnt lgkmcnt(0)
	s_barrier
	s_setprio 1
	v_mfma_f32_16x16x32_bf16 v[126:129], v[146:149], v[178:181], v[126:129]
	v_mfma_f32_16x16x32_bf16 v[122:125], v[154:157], v[178:181], v[122:125]
	v_mfma_f32_16x16x32_bf16 v[118:121], v[146:149], v[186:189], v[118:121]
	v_mfma_f32_16x16x32_bf16 v[110:113], v[154:157], v[186:189], v[110:113]
	v_mfma_f32_16x16x32_bf16 v[102:105], v[146:149], v[202:205], v[102:105]
	v_mfma_f32_16x16x32_bf16 v[94:97], v[154:157], v[202:205], v[94:97]
	v_mfma_f32_16x16x32_bf16 v[86:89], v[146:149], v[210:213], v[86:89]
	v_mfma_f32_16x16x32_bf16 v[78:81], v[154:157], v[210:213], v[78:81]
	v_mfma_f32_16x16x32_bf16 v[126:129], v[150:153], v[182:185], v[126:129]
	v_mfma_f32_16x16x32_bf16 v[122:125], v[158:161], v[182:185], v[122:125]
	v_mfma_f32_16x16x32_bf16 v[118:121], v[150:153], v[190:193], v[118:121]
	v_mfma_f32_16x16x32_bf16 v[110:113], v[158:161], v[190:193], v[110:113]
	v_mfma_f32_16x16x32_bf16 v[102:105], v[150:153], v[206:209], v[102:105]
	v_mfma_f32_16x16x32_bf16 v[94:97], v[158:161], v[206:209], v[94:97]
	v_mfma_f32_16x16x32_bf16 v[86:89], v[150:153], v[214:217], v[86:89]
	v_mfma_f32_16x16x32_bf16 v[78:81], v[158:161], v[214:217], v[78:81]
	s_setprio 0
	s_setprio 1
	v_mfma_f32_16x16x32_bf16 v[114:117], v[162:165], v[178:181], v[114:117]
	v_mfma_f32_16x16x32_bf16 v[106:109], v[170:173], v[178:181], v[106:109]
	v_mfma_f32_16x16x32_bf16 v[98:101], v[162:165], v[186:189], v[98:101]
	v_mfma_f32_16x16x32_bf16 v[90:93], v[170:173], v[186:189], v[90:93]
	v_mfma_f32_16x16x32_bf16 v[82:85], v[162:165], v[202:205], v[82:85]
	v_mfma_f32_16x16x32_bf16 v[74:77], v[170:173], v[202:205], v[74:77]
	v_mfma_f32_16x16x32_bf16 v[70:73], v[162:165], v[210:213], v[70:73]
	v_mfma_f32_16x16x32_bf16 v[66:69], v[170:173], v[210:213], v[66:69]
	v_mfma_f32_16x16x32_bf16 v[114:117], v[166:169], v[182:185], v[114:117]
	v_mfma_f32_16x16x32_bf16 v[106:109], v[174:177], v[182:185], v[106:109]
	v_mfma_f32_16x16x32_bf16 v[98:101], v[166:169], v[190:193], v[98:101]
	v_mfma_f32_16x16x32_bf16 v[90:93], v[174:177], v[190:193], v[90:93]
	v_mfma_f32_16x16x32_bf16 v[82:85], v[166:169], v[206:209], v[82:85]
	v_mfma_f32_16x16x32_bf16 v[74:77], v[174:177], v[206:209], v[74:77]
	v_mfma_f32_16x16x32_bf16 v[70:73], v[166:169], v[214:217], v[70:73]
	v_mfma_f32_16x16x32_bf16 v[66:69], v[174:177], v[214:217], v[66:69]
	s_setprio 0
	s_barrier
	s_add_i32 s18, s30, s24
	v_lshl_add_u64 v[140:141], s[52:53], 0, v[0:1]
	s_mov_b32 m0, s18
	ds_read_b128 v[178:181], v145 offset:16384
	ds_read_b128 v[182:185], v145 offset:17408
	ds_read_b128 v[186:189], v145 offset:18432
	ds_read_b128 v[190:193], v145 offset:19456
	ds_read_b128 v[202:205], v145 offset:20480
	ds_read_b128 v[206:209], v145 offset:21504
	ds_read_b128 v[210:213], v145 offset:22528
	ds_read_b128 v[214:217], v145 offset:23552
	global_load_lds_dwordx4 v[140:141], off
	s_add_i32 m0, s18, 0x2000
	s_add_u32 s18, s52, 0x20000
	v_lshl_add_u64 v[194:195], s[52:53], 0, v[134:135]
	s_addc_u32 s19, s53, 0
	s_add_i32 s30, s31, s24
	global_load_lds_dwordx4 v[194:195], off
	v_lshl_add_u64 v[218:219], s[18:19], 0, v[0:1]
	s_mov_b32 m0, s30
	v_lshl_add_u64 v[220:221], s[72:73], 0, v[132:133]
	global_load_lds_dwordx4 v[218:219], off
	v_lshl_add_u64 v[218:219], s[18:19], 0, v[134:135]
	s_add_i32 m0, s30, 0x2000
	s_nop 0
	global_load_lds_dwordx4 v[218:219], off
	v_lshl_add_u64 v[218:219], s[72:73], 0, v[130:131]
	s_mov_b32 m0, s13
	s_nop 0
	global_load_lds_dwordx4 v[218:219], off
	s_mov_b32 m0, s25
	s_nop 0
	global_load_lds_dwordx4 v[220:221], off
	s_waitcnt vmcnt(8)
	s_waitcnt lgkmcnt(0)
	s_barrier
; #define PG8_STAGE(bufoff, gbase, voff) do { _Pragma("unroll") for (int _i = 0; _i < 2; ++_i) \
;         __builtin_amdgcn_global_load_lds((const unsigned*)((const char*)(gbase) + (voff)[_i]), (LAS unsigned*)(lds + (bufoff) + ldsw + _i * 8192), 16, 0, 0); } while (0)
; #define PG8_WAIT_V(n) asm volatile("s_waitcnt vmcnt(" #n ")" ::: "memory")
; #define PG8_WAIT_L(n) asm volatile("s_waitcnt lgkmcnt(" #n ")" ::: "memory")
; #define PG8_BAR __builtin_amdgcn_s_barrier()
; #define PG8_SCHED __builtin_amdgcn_sched_barrier(0)
; template <bool F8 = false, class Epi, class Sched>
; __device__ __forceinline__ void gemm_phase(LAS unsigned char* lds, const int lda, const int ldb, const int K, const Sched& S, const Epi& E) {
;     ...
;             PG8_LDB(B0, 0, 0); PG8_LDB(B1, 0, 1); PG8_SCHED; PG8_LDA(At, 0, 0); PG8_STAGE(PG8_SA(1, 1), a1 + hstepA, voffA);
;             PG8_WAIT_V(8); PG8_WAIT_L(0); PG8_BAR; PG8_MMA(0, 0, At, B0); PG8_MMA(0, 1, At, B1); PG8_BAR; PG8_SCHED;
;             PG8_LDA(At, 0, 1); PG8_STAGE(PG8_SB(0, 0), b2, voffB); PG8_STAGE(PG8_SB(0, 1), b2 + hstepB, voffB); PG8_STAGE(PG8_SA(0, 0), a2, voffA);
;             PG8_WAIT_V(8); PG8_WAIT_L(0); PG8_BAR; PG8_MMA(1, 0, At, B0); PG8_MMA(1, 1, At, B1); PG8_BAR; PG8_SCHED;
;             PG8_LDB(B0, 1, 0); PG8_LDB(B1, 1, 1); PG8_SCHED; PG8_LDA(At, 1, 0); PG8_STAGE(PG8_SA(0, 1), a2 + hstepA, voffA);
;             PG8_WAIT_V(8); PG8_WAIT_L(0); PG8_BAR; PG8_MMA(0, 0, At, B0); PG8_MMA(0, 1, At, B1); PG8_BAR; PG8_SCHED;
;             PG8_LDA(At, 1, 1); PG8_STAGE(PG8_SB(1, 0), b3, voffB); PG8_STAGE(PG8_SB(1, 1), b3 + hstepB, voffB); PG8_STAGE(PG8_SA(1, 0), a3, voffA);
;             PG8_WAIT_V(8); PG8_WAIT_L(0); PG8_BAR; PG8_MMA(1, 0, At, B0); PG8_MMA(1, 1, At, B1); PG8_BAR; PG8_SCHED;
	s_setprio 1
	v_mfma_f32_16x16x32_bf16 v[62:65], v[146:149], v[178:181], v[62:65]
	v_mfma_f32_16x16x32_bf16 v[58:61], v[154:157], v[178:181], v[58:61]
	v_mfma_f32_16x16x32_bf16 v[54:57], v[146:149], v[186:189], v[54:57]
	v_mfma_f32_16x16x32_bf16 v[46:49], v[154:157], v[186:189], v[46:49]
	v_mfma_f32_16x16x32_bf16 v[38:41], v[146:149], v[202:205], v[38:41]
	v_mfma_f32_16x16x32_bf16 v[30:33], v[154:157], v[202:205], v[30:33]
	v_mfma_f32_16x16x32_bf16 v[22:25], v[146:149], v[210:213], v[22:25]
	v_mfma_f32_16x16x32_bf16 v[14:17], v[154:157], v[210:213], v[14:17]
	v_mfma_f32_16x16x32_bf16 v[62:65], v[150:153], v[182:185], v[62:65]
	v_mfma_f32_16x16x32_bf16 v[58:61], v[158:161], v[182:185], v[58:61]
	v_mfma_f32_16x16x32_bf16 v[54:57], v[150:153], v[190:193], v[54:57]
	v_mfma_f32_16x16x32_bf16 v[46:49], v[158:161], v[190:193], v[46:49]
	v_mfma_f32_16x16x32_bf16 v[38:41], v[150:153], v[206:209], v[38:41]
	v_mfma_f32_16x16x32_bf16 v[30:33], v[158:161], v[206:209], v[30:33]
	v_mfma_f32_16x16x32_bf16 v[22:25], v[150:153], v[214:217], v[22:25]
	v_mfma_f32_16x16x32_bf16 v[14:17], v[158:161], v[214:217], v[14:17]
	s_setprio 0
	s_setprio 1
	v_mfma_f32_16x16x32_bf16 v[50:53], v[162:165], v[178:181], v[50:53]
	v_mfma_f32_16x16x32_bf16 v[42:45], v[170:173], v[178:181], v[42:45]
	v_mfma_f32_16x16x32_bf16 v[34:37], v[162:165], v[186:189], v[34:37]
	v_mfma_f32_16x16x32_bf16 v[26:29], v[170:173], v[186:189], v[26:29]
	v_mfma_f32_16x16x32_bf16 v[18:21], v[162:165], v[202:205], v[18:21]
	v_mfma_f32_16x16x32_bf16 v[10:13], v[170:173], v[202:205], v[10:13]
	v_mfma_f32_16x16x32_bf16 v[6:9], v[162:165], v[210:213], v[6:9]
	v_mfma_f32_16x16x32_bf16 v[2:5], v[170:173], v[210:213], v[2:5]
	v_mfma_f32_16x16x32_bf16 v[50:53], v[166:169], v[182:185], v[50:53]
	v_mfma_f32_16x16x32_bf16 v[42:45], v[174:177], v[182:185], v[42:45]
	v_mfma_f32_16x16x32_bf16 v[34:37], v[166:169], v[190:193], v[34:37]
	v_mfma_f32_16x16x32_bf16 v[26:29], v[174:177], v[190:193], v[26:29]
	v_mfma_f32_16x16x32_bf16 v[18:21], v[166:169], v[206:209], v[18:21]
	v_mfma_f32_16x16x32_bf16 v[10:13], v[174:177], v[206:209], v[10:13]
	v_mfma_f32_16x16x32_bf16 v[6:9], v[166:169], v[214:217], v[6:9]
	v_mfma_f32_16x16x32_bf16 v[2:5], v[174:177], v[214:217], v[2:5]
	s_setprio 0
	s_barrier
	s_add_i32 s30, 0, 0x18000
	s_add_i32 s31, 0, 0x1c000
	v_add_u32_e32 v158, s30, v143
	v_add_u32_e32 v174, s31, v143
	ds_read_b128 v[146:149], v158
	ds_read_b128 v[150:153], v158 offset:1024
	ds_read_b128 v[154:157], v158 offset:2048
	ds_read_b128 v[158:161], v158 offset:3072
	ds_read_b128 v[162:165], v174
	ds_read_b128 v[166:169], v174 offset:1024
	ds_read_b128 v[170:173], v174 offset:2048
	ds_read_b128 v[174:177], v174 offset:3072
	s_add_u32 s18, s72, 0x2e4000
	s_addc_u32 s19, s73, 0
	s_mov_b32 m0, s26
	v_lshl_add_u64 v[222:223], s[18:19], 0, v[130:131]
	ds_read_b128 v[178:181], v145 offset:32768
	ds_read_b128 v[182:185], v145 offset:33792
	ds_read_b128 v[186:189], v145 offset:34816
	ds_read_b128 v[190:193], v145 offset:35840
	ds_read_b128 v[202:205], v145 offset:36864
	ds_read_b128 v[206:209], v145 offset:37888
	ds_read_b128 v[210:213], v145 offset:38912
	ds_read_b128 v[214:217], v145 offset:39936
	global_load_lds_dwordx4 v[222:223], off
	v_lshl_add_u64 v[222:223], s[18:19], 0, v[132:133]
	s_mov_b32 m0, s27
	s_nop 0
	global_load_lds_dwordx4 v[222:223], off
	s_waitcnt vmcnt(8)
	s_waitcnt lgkmcnt(0)
	s_barrier
	s_setprio 1
	v_mfma_f32_16x16x32_bf16 v[126:129], v[146:149], v[178:181], v[126:129]
	v_mfma_f32_16x16x32_bf16 v[122:125], v[154:157], v[178:181], v[122:125]
	v_mfma_f32_16x16x32_bf16 v[118:121], v[146:149], v[186:189], v[118:121]
	v_mfma_f32_16x16x32_bf16 v[110:113], v[154:157], v[186:189], v[110:113]
	v_mfma_f32_16x16x32_bf16 v[102:105], v[146:149], v[202:205], v[102:105]
	v_mfma_f32_16x16x32_bf16 v[94:97], v[154:157], v[202:205], v[94:97]
	v_mfma_f32_16x16x32_bf16 v[86:89], v[146:149], v[210:213], v[86:89]
	v_mfma_f32_16x16x32_bf16 v[78:81], v[154:157], v[210:213], v[78:81]
	v_mfma_f32_16x16x32_bf16 v[126:129], v[150:153], v[182:185], v[126:129]
	v_mfma_f32_16x16x32_bf16 v[122:125], v[158:161], v[182:185], v[122:125]
	v_mfma_f32_16x16x32_bf16 v[118:121], v[150:153], v[190:193], v[118:121]
	v_mfma_f32_16x16x32_bf16 v[110:113], v[158:161], v[190:193], v[110:113]
	v_mfma_f32_16x16x32_bf16 v[102:105], v[150:153], v[206:209], v[102:105]
	v_mfma_f32_16x16x32_bf16 v[94:97], v[158:161], v[206:209], v[94:97]
	v_mfma_f32_16x16x32_bf16 v[86:89], v[150:153], v[214:217], v[86:89]
	v_mfma_f32_16x16x32_bf16 v[78:81], v[158:161], v[214:217], v[78:81]
	s_setprio 0
	s_setprio 1
	v_mfma_f32_16x16x32_bf16 v[114:117], v[162:165], v[178:181], v[114:117]
	v_mfma_f32_16x16x32_bf16 v[106:109], v[170:173], v[178:181], v[106:109]
	v_mfma_f32_16x16x32_bf16 v[98:101], v[162:165], v[186:189], v[98:101]
	v_mfma_f32_16x16x32_bf16 v[90:93], v[170:173], v[186:189], v[90:93]
	v_mfma_f32_16x16x32_bf16 v[82:85], v[162:165], v[202:205], v[82:85]
	v_mfma_f32_16x16x32_bf16 v[74:77], v[170:173], v[202:205], v[74:77]
	v_mfma_f32_16x16x32_bf16 v[70:73], v[162:165], v[210:213], v[70:73]
	v_mfma_f32_16x16x32_bf16 v[66:69], v[170:173], v[210:213], v[66:69]
	v_mfma_f32_16x16x32_bf16 v[114:117], v[166:169], v[182:185], v[114:117]
	v_mfma_f32_16x16x32_bf16 v[106:109], v[174:177], v[182:185], v[106:109]
	v_mfma_f32_16x16x32_bf16 v[98:101], v[166:169], v[190:193], v[98:101]
	v_mfma_f32_16x16x32_bf16 v[90:93], v[174:177], v[190:193], v[90:93]
	v_mfma_f32_16x16x32_bf16 v[82:85], v[166:169], v[206:209], v[82:85]
	v_mfma_f32_16x16x32_bf16 v[74:77], v[174:177], v[206:209], v[74:77]
	v_mfma_f32_16x16x32_bf16 v[70:73], v[166:169], v[214:217], v[70:73]
	v_mfma_f32_16x16x32_bf16 v[66:69], v[174:177], v[214:217], v[66:69]
	s_setprio 0
	s_barrier
; #define PG8_STAGE(bufoff, gbase, voff) do { _Pragma("unroll") for (int _i = 0; _i < 2; ++_i) \
;         __builtin_amdgcn_global_load_lds((const unsigned*)((const char*)(gbase) + (voff)[_i]), (LAS unsigned*)(lds + (bufoff) + ldsw + _i * 8192), 16, 0, 0); } while (0)
; #define PG8_WAIT_V(n) asm volatile("s_waitcnt vmcnt(" #n ")" ::: "memory")
; #define PG8_WAIT_L(n) asm volatile("s_waitcnt lgkmcnt(" #n ")" ::: "memory")
; #define PG8_BAR __builtin_amdgcn_s_barrier()
; #define PG8_SCHED __builtin_amdgcn_sched_barrier(0)
; template <bool F8 = false, class Epi, class Sched>
; __device__ __forceinline__ void gemm_phase(LAS unsigned char* lds, const int lda, const int ldb, const int K, const Sched& S, const Epi& E) {
;     ...
;             PG8_LDB(B0, 1, 0); PG8_LDB(B1, 1, 1); PG8_SCHED; PG8_LDA(At, 1, 0); PG8_STAGE(PG8_SA(0, 1), a2 + hstepA, voffA);
;             PG8_WAIT_V(8); PG8_WAIT_L(0); PG8_BAR; PG8_MMA(0, 0, At, B0); PG8_MMA(0, 1, At, B1); PG8_BAR; PG8_SCHED;
;             PG8_LDA(At, 1, 1); PG8_STAGE(PG8_SB(1, 0), b3, voffB); PG8_STAGE(PG8_SB(1, 1), b3 + hstepB, voffB); PG8_STAGE(PG8_SA(1, 0), a3, voffA);
;             PG8_WAIT_V(8); PG8_WAIT_L(0); PG8_BAR; PG8_MMA(1, 0, At, B0); PG8_MMA(1, 1, At, B1); PG8_BAR; PG8_SCHED;
;         }
;         if (wr == 0) PG8_BAR;
;         E(acc, cur, wr, wc, fr, fq);
;         if (!has_next) break;
	s_add_i32 s18, s30, s24
	v_lshl_add_u64 v[140:141], v[140:141], 0, s[40:41]
	s_mov_b32 m0, s18
	ds_read_b128 v[178:181], v145 offset:49152
	ds_read_b128 v[182:185], v145 offset:50176
	ds_read_b128 v[186:189], v145 offset:51200
	ds_read_b128 v[190:193], v145 offset:52224
	ds_read_b128 v[202:205], v145 offset:53248
	ds_read_b128 v[206:209], v145 offset:54272
	ds_read_b128 v[210:213], v145 offset:55296
	ds_read_b128 v[214:217], v145 offset:56320
	global_load_lds_dwordx4 v[140:141], off
	s_add_i32 m0, s18, 0x2000
	s_add_u32 s18, s52, 0x20080
	v_lshl_add_u64 v[140:141], v[194:195], 0, s[40:41]
	s_addc_u32 s19, s53, 0
	s_add_i32 s30, s31, s24
	global_load_lds_dwordx4 v[140:141], off
	v_lshl_add_u64 v[140:141], s[18:19], 0, v[0:1]
	s_mov_b32 m0, s30
	s_nop 0
	global_load_lds_dwordx4 v[140:141], off
	v_lshl_add_u64 v[140:141], s[18:19], 0, v[134:135]
	s_add_i32 m0, s30, 0x2000
	s_nop 0
	global_load_lds_dwordx4 v[140:141], off
	v_lshl_add_u64 v[140:141], v[218:219], 0, s[40:41]
	s_mov_b32 m0, s44
	s_nop 0
	global_load_lds_dwordx4 v[140:141], off
	v_lshl_add_u64 v[140:141], v[220:221], 0, s[40:41]
	s_mov_b32 m0, s56
	s_nop 0
	global_load_lds_dwordx4 v[140:141], off
	s_waitcnt vmcnt(8)
	s_waitcnt lgkmcnt(0)
	s_barrier
	s_setprio 1
	v_mfma_f32_16x16x32_bf16 v[62:65], v[146:149], v[178:181], v[62:65]
	v_mfma_f32_16x16x32_bf16 v[58:61], v[154:157], v[178:181], v[58:61]
	v_mfma_f32_16x16x32_bf16 v[54:57], v[146:149], v[186:189], v[54:57]
	v_mfma_f32_16x16x32_bf16 v[46:49], v[154:157], v[186:189], v[46:49]
	v_mfma_f32_16x16x32_bf16 v[38:41], v[146:149], v[202:205], v[38:41]
	v_mfma_f32_16x16x32_bf16 v[30:33], v[154:157], v[202:205], v[30:33]
	v_mfma_f32_16x16x32_bf16 v[22:25], v[146:149], v[210:213], v[22:25]
	v_mfma_f32_16x16x32_bf16 v[14:17], v[154:157], v[210:213], v[14:17]
	v_mfma_f32_16x16x32_bf16 v[62:65], v[150:153], v[182:185], v[62:65]
	v_mfma_f32_16x16x32_bf16 v[58:61], v[158:161], v[182:185], v[58:61]
	v_mfma_f32_16x16x32_bf16 v[54:57], v[150:153], v[190:193], v[54:57]
	v_mfma_f32_16x16x32_bf16 v[46:49], v[158:161], v[190:193], v[46:49]
	v_mfma_f32_16x16x32_bf16 v[38:41], v[150:153], v[206:209], v[38:41]
	v_mfma_f32_16x16x32_bf16 v[30:33], v[158:161], v[206:209], v[30:33]
	v_mfma_f32_16x16x32_bf16 v[22:25], v[150:153], v[214:217], v[22:25]
	v_mfma_f32_16x16x32_bf16 v[14:17], v[158:161], v[214:217], v[14:17]
	s_setprio 0
	s_setprio 1
	v_mfma_f32_16x16x32_bf16 v[50:53], v[162:165], v[178:181], v[50:53]
	v_mfma_f32_16x16x32_bf16 v[42:45], v[170:173], v[178:181], v[42:45]
	v_mfma_f32_16x16x32_bf16 v[34:37], v[162:165], v[186:189], v[34:37]
	v_mfma_f32_16x16x32_bf16 v[26:29], v[170:173], v[186:189], v[26:29]
	v_mfma_f32_16x16x32_bf16 v[18:21], v[162:165], v[202:205], v[18:21]
	v_mfma_f32_16x16x32_bf16 v[10:13], v[170:173], v[202:205], v[10:13]
	v_mfma_f32_16x16x32_bf16 v[6:9], v[162:165], v[210:213], v[6:9]
	v_mfma_f32_16x16x32_bf16 v[2:5], v[170:173], v[210:213], v[2:5]
	v_mfma_f32_16x16x32_bf16 v[50:53], v[166:169], v[182:185], v[50:53]
	v_mfma_f32_16x16x32_bf16 v[42:45], v[174:177], v[182:185], v[42:45]
	v_mfma_f32_16x16x32_bf16 v[34:37], v[166:169], v[190:193], v[34:37]
	v_mfma_f32_16x16x32_bf16 v[26:29], v[174:177], v[190:193], v[26:29]
	v_mfma_f32_16x16x32_bf16 v[18:21], v[166:169], v[206:209], v[18:21]
	v_mfma_f32_16x16x32_bf16 v[10:13], v[174:177], v[206:209], v[10:13]
	v_mfma_f32_16x16x32_bf16 v[6:9], v[166:169], v[214:217], v[6:9]
	v_mfma_f32_16x16x32_bf16 v[2:5], v[174:177], v[214:217], v[2:5]
	s_setprio 0
	s_barrier
	s_add_i32 s29, s29, 2
	s_add_u32 s11, s11, 0x100
	s_addc_u32 s28, s28, 0
	s_cmp_gt_u32 s29, 5
	s_mov_b64 s[18:19], s[20:21]
	s_cbranch_scc0 .LBB0_436
	s_and_b64 vcc, exec, s[8:9]
	s_cbranch_vccz .LBB0_439
	s_barrier

;     __device__ __forceinline__ const char* ptrA(const Unit& u) const { return (u.sub ? A1 : A0) + (size_t)u.pm * aT; }
;     __device__ __forceinline__ const char* ptrB(const Unit& u) const { return (u.sub ? B1 : B0) + (size_t)u.pn * bT; }
;     __device__ __forceinline__ bool next(int i, Unit& u) const { const int L = i * G + c; if (L >= 256) return false; u.sub = L & 3; const int t = L >> 2; u.pm = 64 + (t >> 3); u.pn = t & 7; return true; }
; #define PG8_STAGE(bufoff, gbase, voff) do { _Pragma("unroll") for (int _i = 0; _i < 2; ++_i) \
;         __builtin_amdgcn_global_load_lds((const unsigned*)((const char*)(gbase) + (voff)[_i]), (LAS unsigned*)(lds + (bufoff) + ldsw + _i * 8192), 16, 0, 0); } while (0)
; #define PG8_WAIT_V(n) asm volatile("s_waitcnt vmcnt(" #n ")" ::: "memory")
; #define PG8_WAIT_L(n) asm volatile("s_waitcnt lgkmcnt(" #n ")" ::: "memory")
; #define PG8_BAR __builtin_amdgcn_s_barrier()
; #define PG8_SCHED __builtin_amdgcn_sched_barrier(0)
; template <bool F8 = false, class Epi, class Sched>
; __device__ __forceinline__ void gemm_phase(LAS unsigned char* lds, const int lda, const int ldb, const int K, const Sched& S, const Epi& E) {
;     ...
;         const bool has_next = S.next(ui + 1, nxt);
;         const char* nA = has_next ? S.ptrA(nxt) : cA; const char* nB = has_next ? S.ptrB(nxt) : cB;
;         for (int t = 0; t < nt; t += 2) {
;             const bool last = (t == nt - 2);
;             const char* a1 = cA + (size_t)(t + 1) * kstep;
;             const char* a2 = last ? nA : cA + (size_t)(t + 2) * kstep; const char* b2 = last ? nB : cB + (size_t)(t + 2) * kstep;
;             const char* a3 = a2 + kstep; const char* b3 = b2 + kstep;
;             PG8_LDB(B0, 0, 0); PG8_LDB(B1, 0, 1); PG8_SCHED; PG8_LDA(At, 0, 0); PG8_STAGE(PG8_SA(1, 1), a1 + hstepA, voffA);
;             PG8_WAIT_V(8); PG8_WAIT_L(0); PG8_BAR; PG8_MMA(0, 0, At, B0); PG8_MMA(0, 1, At, B1); PG8_BAR; PG8_SCHED;
;             PG8_LDA(At, 0, 1); PG8_STAGE(PG8_SB(0, 0), b2, voffB); PG8_STAGE(PG8_SB(0, 1), b2 + hstepB, voffB); PG8_STAGE(PG8_SA(0, 0), a2, voffA);
;             PG8_WAIT_V(8); PG8_WAIT_L(0); PG8_BAR; PG8_MMA(1, 0, At, B0); PG8_MMA(1, 1, At, B1); PG8_BAR; PG8_SCHED;
.LBB0_690:
	s_add_u32 s52, s18, 0x100
	s_addc_u32 s53, s19, 0
	s_add_i32 s29, 0, 0x10000
	s_cmp_eq_u32 s28, 12
	s_cselect_b32 s75, s21, s53
	s_cselect_b32 s74, s20, s52
	s_cselect_b32 s73, s11, s17
	s_cselect_b32 s72, s10, s15
	s_add_i32 s30, 0, 0x14000
	v_add_u32_e32 v142, s29, v245
	v_add_u32_e32 v158, s30, v245
	ds_read_b128 v[130:133], v142
	ds_read_b128 v[134:137], v142 offset:1024
	ds_read_b128 v[138:141], v142 offset:2048
	ds_read_b128 v[142:145], v142 offset:3072
	ds_read_b128 v[146:149], v158
	ds_read_b128 v[150:153], v158 offset:1024
	ds_read_b128 v[154:157], v158 offset:2048
	ds_read_b128 v[158:161], v158 offset:3072
	v_lshl_add_u64 v[194:195], s[18:19], 0, v[208:209]
	s_add_i32 m0, s95, 0xc000
	ds_read_b128 v[162:165], v247
	ds_read_b128 v[166:169], v247 offset:1024
	ds_read_b128 v[170:173], v247 offset:2048
	ds_read_b128 v[174:177], v247 offset:3072
	ds_read_b128 v[178:181], v247 offset:4096
	ds_read_b128 v[182:185], v247 offset:5120
	ds_read_b128 v[186:189], v247 offset:6144
	ds_read_b128 v[190:193], v247 offset:7168
	global_load_lds_dwordx4 v[194:195], off
	v_lshl_add_u64 v[194:195], s[18:19], 0, v[210:211]
	s_add_i32 m0, s95, 0xe000
	s_nop 0
	global_load_lds_dwordx4 v[194:195], off
	s_waitcnt vmcnt(8)
	s_waitcnt lgkmcnt(0)
	s_barrier
	s_setprio 1
	v_mfma_f32_16x16x32_bf16 v[126:129], v[130:133], v[162:165], v[126:129]
	v_mfma_f32_16x16x32_bf16 v[122:125], v[138:141], v[162:165], v[122:125]
	v_mfma_f32_16x16x32_bf16 v[110:113], v[130:133], v[170:173], v[110:113]
	v_mfma_f32_16x16x32_bf16 v[106:109], v[138:141], v[170:173], v[106:109]
	v_mfma_f32_16x16x32_bf16 v[94:97], v[130:133], v[178:181], v[94:97]
	v_mfma_f32_16x16x32_bf16 v[90:93], v[138:141], v[178:181], v[90:93]
	v_mfma_f32_16x16x32_bf16 v[78:81], v[130:133], v[186:189], v[78:81]
	v_mfma_f32_16x16x32_bf16 v[74:77], v[138:141], v[186:189], v[74:77]
	v_mfma_f32_16x16x32_bf16 v[126:129], v[134:137], v[166:169], v[126:129]
	v_mfma_f32_16x16x32_bf16 v[122:125], v[142:145], v[166:169], v[122:125]
	v_mfma_f32_16x16x32_bf16 v[110:113], v[134:137], v[174:177], v[110:113]
	v_mfma_f32_16x16x32_bf16 v[106:109], v[142:145], v[174:177], v[106:109]
	v_mfma_f32_16x16x32_bf16 v[94:97], v[134:137], v[182:185], v[94:97]
	v_mfma_f32_16x16x32_bf16 v[90:93], v[142:145], v[182:185], v[90:93]
	v_mfma_f32_16x16x32_bf16 v[78:81], v[134:137], v[190:193], v[78:81]
	v_mfma_f32_16x16x32_bf16 v[74:77], v[142:145], v[190:193], v[74:77]
	s_setprio 0
	s_setprio 1
	v_mfma_f32_16x16x32_bf16 v[118:121], v[146:149], v[162:165], v[118:121]
	v_mfma_f32_16x16x32_bf16 v[114:117], v[154:157], v[162:165], v[114:117]
	v_mfma_f32_16x16x32_bf16 v[102:105], v[146:149], v[170:173], v[102:105]
	v_mfma_f32_16x16x32_bf16 v[98:101], v[154:157], v[170:173], v[98:101]
	v_mfma_f32_16x16x32_bf16 v[86:89], v[146:149], v[178:181], v[86:89]
	v_mfma_f32_16x16x32_bf16 v[82:85], v[154:157], v[178:181], v[82:85]
	v_mfma_f32_16x16x32_bf16 v[70:73], v[146:149], v[186:189], v[70:73]
	v_mfma_f32_16x16x32_bf16 v[66:69], v[154:157], v[186:189], v[66:69]
	v_mfma_f32_16x16x32_bf16 v[118:121], v[150:153], v[166:169], v[118:121]
	v_mfma_f32_16x16x32_bf16 v[114:117], v[158:161], v[166:169], v[114:117]
	v_mfma_f32_16x16x32_bf16 v[102:105], v[150:153], v[174:177], v[102:105]
	v_mfma_f32_16x16x32_bf16 v[98:101], v[158:161], v[174:177], v[98:101]
	v_mfma_f32_16x16x32_bf16 v[86:89], v[150:153], v[182:185], v[86:89]
	v_mfma_f32_16x16x32_bf16 v[82:85], v[158:161], v[182:185], v[82:85]
	v_mfma_f32_16x16x32_bf16 v[70:73], v[150:153], v[190:193], v[70:73]
	v_mfma_f32_16x16x32_bf16 v[66:69], v[158:161], v[190:193], v[66:69]
	s_setprio 0
	s_barrier
	s_add_i32 s18, s29, s94
	v_lshl_add_u64 v[194:195], s[72:73], 0, v[0:1]
	s_mov_b32 m0, s18
	ds_read_b128 v[162:165], v247 offset:16384
	ds_read_b128 v[166:169], v247 offset:17408
	ds_read_b128 v[170:173], v247 offset:18432
	ds_read_b128 v[174:177], v247 offset:19456
	ds_read_b128 v[178:181], v247 offset:20480
	ds_read_b128 v[182:185], v247 offset:21504
	ds_read_b128 v[186:189], v247 offset:22528
	ds_read_b128 v[190:193], v247 offset:23552
	global_load_lds_dwordx4 v[194:195], off
	s_add_i32 m0, s18, 0x2000
	s_add_u32 s18, s72, 0x40000
	v_lshl_add_u64 v[212:213], s[72:73], 0, v[206:207]
	s_addc_u32 s19, s73, 0
	s_add_i32 s29, s30, s94
	global_load_lds_dwordx4 v[212:213], off
	v_lshl_add_u64 v[214:215], s[18:19], 0, v[0:1]
	s_mov_b32 m0, s29
	v_lshl_add_u64 v[216:217], s[74:75], 0, v[204:205]
	global_load_lds_dwordx4 v[214:215], off
	v_lshl_add_u64 v[214:215], s[18:19], 0, v[206:207]
	s_add_i32 m0, s29, 0x2000
	s_nop 0
	global_load_lds_dwordx4 v[214:215], off
	v_lshl_add_u64 v[214:215], s[74:75], 0, v[202:203]
	s_mov_b32 m0, s95
	s_nop 0
	global_load_lds_dwordx4 v[214:215], off
	s_mov_b32 m0, s96
	s_nop 0
	global_load_lds_dwordx4 v[216:217], off
	s_waitcnt vmcnt(8)
	s_waitcnt lgkmcnt(0)
	s_barrier
; #define PG8_STAGE(bufoff, gbase, voff) do { _Pragma("unroll") for (int _i = 0; _i < 2; ++_i) \
;         __builtin_amdgcn_global_load_lds((const unsigned*)((const char*)(gbase) + (voff)[_i]), (LAS unsigned*)(lds + (bufoff) + ldsw + _i * 8192), 16, 0, 0); } while (0)
; #define PG8_WAIT_V(n) asm volatile("s_waitcnt vmcnt(" #n ")" ::: "memory")
; #define PG8_WAIT_L(n) asm volatile("s_waitcnt lgkmcnt(" #n ")" ::: "memory")
; #define PG8_BAR __builtin_amdgcn_s_barrier()
; #define PG8_SCHED __builtin_amdgcn_sched_barrier(0)
; template <bool F8 = false, class Epi, class Sched>
; __device__ __forceinline__ void gemm_phase(LAS unsigned char* lds, const int lda, const int ldb, const int K, const Sched& S, const Epi& E) {
;     ...
;             PG8_WAIT_V(8); PG8_WAIT_L(0); PG8_BAR; PG8_MMA(0, 0, At, B0); PG8_MMA(0, 1, At, B1); PG8_BAR; PG8_SCHED;
;             PG8_LDA(At, 0, 1); PG8_STAGE(PG8_SB(0, 0), b2, voffB); PG8_STAGE(PG8_SB(0, 1), b2 + hstepB, voffB); PG8_STAGE(PG8_SA(0, 0), a2, voffA);
;             PG8_WAIT_V(8); PG8_WAIT_L(0); PG8_BAR; PG8_MMA(1, 0, At, B0); PG8_MMA(1, 1, At, B1); PG8_BAR; PG8_SCHED;
;             PG8_LDB(B0, 1, 0); PG8_LDB(B1, 1, 1); PG8_SCHED; PG8_LDA(At, 1, 0); PG8_STAGE(PG8_SA(0, 1), a2 + hstepA, voffA);
;             PG8_WAIT_V(8); PG8_WAIT_L(0); PG8_BAR; PG8_MMA(0, 0, At, B0); PG8_MMA(0, 1, At, B1); PG8_BAR; PG8_SCHED;
;             PG8_LDA(At, 1, 1); PG8_STAGE(PG8_SB(1, 0), b3, voffB); PG8_STAGE(PG8_SB(1, 1), b3 + hstepB, voffB); PG8_STAGE(PG8_SA(1, 0), a3, voffA);
;             PG8_WAIT_V(8); PG8_WAIT_L(0); PG8_BAR; PG8_MMA(1, 0, At, B0); PG8_MMA(1, 1, At, B1); PG8_BAR; PG8_SCHED;
	s_setprio 1
	v_mfma_f32_16x16x32_bf16 v[62:65], v[130:133], v[162:165], v[62:65]
	v_mfma_f32_16x16x32_bf16 v[58:61], v[138:141], v[162:165], v[58:61]
	v_mfma_f32_16x16x32_bf16 v[46:49], v[130:133], v[170:173], v[46:49]
	v_mfma_f32_16x16x32_bf16 v[42:45], v[138:141], v[170:173], v[42:45]
	v_mfma_f32_16x16x32_bf16 v[30:33], v[130:133], v[178:181], v[30:33]
	v_mfma_f32_16x16x32_bf16 v[26:29], v[138:141], v[178:181], v[26:29]
	v_mfma_f32_16x16x32_bf16 v[14:17], v[130:133], v[186:189], v[14:17]
	v_mfma_f32_16x16x32_bf16 v[10:13], v[138:141], v[186:189], v[10:13]
	v_mfma_f32_16x16x32_bf16 v[62:65], v[134:137], v[166:169], v[62:65]
	v_mfma_f32_16x16x32_bf16 v[58:61], v[142:145], v[166:169], v[58:61]
	v_mfma_f32_16x16x32_bf16 v[46:49], v[134:137], v[174:177], v[46:49]
	v_mfma_f32_16x16x32_bf16 v[42:45], v[142:145], v[174:177], v[42:45]
	v_mfma_f32_16x16x32_bf16 v[30:33], v[134:137], v[182:185], v[30:33]
	v_mfma_f32_16x16x32_bf16 v[26:29], v[142:145], v[182:185], v[26:29]
	v_mfma_f32_16x16x32_bf16 v[14:17], v[134:137], v[190:193], v[14:17]
	v_mfma_f32_16x16x32_bf16 v[10:13], v[142:145], v[190:193], v[10:13]
	s_setprio 0
	s_setprio 1
	v_mfma_f32_16x16x32_bf16 v[54:57], v[146:149], v[162:165], v[54:57]
	v_mfma_f32_16x16x32_bf16 v[50:53], v[154:157], v[162:165], v[50:53]
	v_mfma_f32_16x16x32_bf16 v[38:41], v[146:149], v[170:173], v[38:41]
	v_mfma_f32_16x16x32_bf16 v[34:37], v[154:157], v[170:173], v[34:37]
	v_mfma_f32_16x16x32_bf16 v[22:25], v[146:149], v[178:181], v[22:25]
	v_mfma_f32_16x16x32_bf16 v[18:21], v[154:157], v[178:181], v[18:21]
	v_mfma_f32_16x16x32_bf16 v[6:9], v[146:149], v[186:189], v[6:9]
	v_mfma_f32_16x16x32_bf16 v[2:5], v[154:157], v[186:189], v[2:5]
	v_mfma_f32_16x16x32_bf16 v[54:57], v[150:153], v[166:169], v[54:57]
	v_mfma_f32_16x16x32_bf16 v[50:53], v[158:161], v[166:169], v[50:53]
	v_mfma_f32_16x16x32_bf16 v[38:41], v[150:153], v[174:177], v[38:41]
	v_mfma_f32_16x16x32_bf16 v[34:37], v[158:161], v[174:177], v[34:37]
	v_mfma_f32_16x16x32_bf16 v[22:25], v[150:153], v[182:185], v[22:25]
	v_mfma_f32_16x16x32_bf16 v[18:21], v[158:161], v[182:185], v[18:21]
	v_mfma_f32_16x16x32_bf16 v[6:9], v[150:153], v[190:193], v[6:9]
	v_mfma_f32_16x16x32_bf16 v[2:5], v[158:161], v[190:193], v[2:5]
	s_setprio 0
	s_barrier
	s_add_i32 s29, 0, 0x18000
	s_add_i32 s30, 0, 0x1c000
	v_add_u32_e32 v142, s29, v245
	v_add_u32_e32 v158, s30, v245
	ds_read_b128 v[130:133], v142
	ds_read_b128 v[134:137], v142 offset:1024
	ds_read_b128 v[138:141], v142 offset:2048
	ds_read_b128 v[142:145], v142 offset:3072
	ds_read_b128 v[146:149], v158
	ds_read_b128 v[150:153], v158 offset:1024
	ds_read_b128 v[154:157], v158 offset:2048
	ds_read_b128 v[158:161], v158 offset:3072
	s_add_u32 s18, s74, 0xc0000
	s_addc_u32 s19, s75, 0
	s_mov_b32 m0, s97
	v_lshl_add_u64 v[218:219], s[18:19], 0, v[202:203]
	ds_read_b128 v[162:165], v247 offset:32768
	ds_read_b128 v[166:169], v247 offset:33792
	ds_read_b128 v[170:173], v247 offset:34816
	ds_read_b128 v[174:177], v247 offset:35840
	ds_read_b128 v[178:181], v247 offset:36864
	ds_read_b128 v[182:185], v247 offset:37888
	ds_read_b128 v[186:189], v247 offset:38912
	ds_read_b128 v[190:193], v247 offset:39936
	global_load_lds_dwordx4 v[218:219], off
	v_lshl_add_u64 v[218:219], s[18:19], 0, v[204:205]
	s_mov_b32 m0, s56
	s_nop 0
	global_load_lds_dwordx4 v[218:219], off
	s_waitcnt vmcnt(8)
	s_waitcnt lgkmcnt(0)
	s_barrier
	s_setprio 1
	v_mfma_f32_16x16x32_bf16 v[126:129], v[130:133], v[162:165], v[126:129]
	v_mfma_f32_16x16x32_bf16 v[122:125], v[138:141], v[162:165], v[122:125]
	v_mfma_f32_16x16x32_bf16 v[110:113], v[130:133], v[170:173], v[110:113]
	v_mfma_f32_16x16x32_bf16 v[106:109], v[138:141], v[170:173], v[106:109]
	v_mfma_f32_16x16x32_bf16 v[94:97], v[130:133], v[178:181], v[94:97]
	v_mfma_f32_16x16x32_bf16 v[90:93], v[138:141], v[178:181], v[90:93]
	v_mfma_f32_16x16x32_bf16 v[78:81], v[130:133], v[186:189], v[78:81]
	v_mfma_f32_16x16x32_bf16 v[74:77], v[138:141], v[186:189], v[74:77]
	v_mfma_f32_16x16x32_bf16 v[126:129], v[134:137], v[166:169], v[126:129]
	v_mfma_f32_16x16x32_bf16 v[122:125], v[142:145], v[166:169], v[122:125]
	v_mfma_f32_16x16x32_bf16 v[110:113], v[134:137], v[174:177], v[110:113]
	v_mfma_f32_16x16x32_bf16 v[106:109], v[142:145], v[174:177], v[106:109]
	v_mfma_f32_16x16x32_bf16 v[94:97], v[134:137], v[182:185], v[94:97]
	v_mfma_f32_16x16x32_bf16 v[90:93], v[142:145], v[182:185], v[90:93]
	v_mfma_f32_16x16x32_bf16 v[78:81], v[134:137], v[190:193], v[78:81]
	v_mfma_f32_16x16x32_bf16 v[74:77], v[142:145], v[190:193], v[74:77]
	s_setprio 0
	s_setprio 1
	v_mfma_f32_16x16x32_bf16 v[118:121], v[146:149], v[162:165], v[118:121]
	v_mfma_f32_16x16x32_bf16 v[114:117], v[154:157], v[162:165], v[114:117]
	v_mfma_f32_16x16x32_bf16 v[102:105], v[146:149], v[170:173], v[102:105]
	v_mfma_f32_16x16x32_bf16 v[98:101], v[154:157], v[170:173], v[98:101]
	v_mfma_f32_16x16x32_bf16 v[86:89], v[146:149], v[178:181], v[86:89]
	v_mfma_f32_16x16x32_bf16 v[82:85], v[154:157], v[178:181], v[82:85]
	v_mfma_f32_16x16x32_bf16 v[70:73], v[146:149], v[186:189], v[70:73]
	v_mfma_f32_16x16x32_bf16 v[66:69], v[154:157], v[186:189], v[66:69]
	v_mfma_f32_16x16x32_bf16 v[118:121], v[150:153], v[166:169], v[118:121]
	v_mfma_f32_16x16x32_bf16 v[114:117], v[158:161], v[166:169], v[114:117]
	v_mfma_f32_16x16x32_bf16 v[102:105], v[150:153], v[174:177], v[102:105]
	v_mfma_f32_16x16x32_bf16 v[98:101], v[158:161], v[174:177], v[98:101]
	v_mfma_f32_16x16x32_bf16 v[86:89], v[150:153], v[182:185], v[86:89]
	v_mfma_f32_16x16x32_bf16 v[82:85], v[158:161], v[182:185], v[82:85]
	v_mfma_f32_16x16x32_bf16 v[70:73], v[150:153], v[190:193], v[70:73]
	v_mfma_f32_16x16x32_bf16 v[66:69], v[158:161], v[190:193], v[66:69]
	s_setprio 0
	s_barrier
; #define PG8_STAGE(bufoff, gbase, voff) do { _Pragma("unroll") for (int _i = 0; _i < 2; ++_i) \
;         __builtin_amdgcn_global_load_lds((const unsigned*)((const char*)(gbase) + (voff)[_i]), (LAS unsigned*)(lds + (bufoff) + ldsw + _i * 8192), 16, 0, 0); } while (0)
; #define PG8_WAIT_V(n) asm volatile("s_waitcnt vmcnt(" #n ")" ::: "memory")
; #define PG8_WAIT_L(n) asm volatile("s_waitcnt lgkmcnt(" #n ")" ::: "memory")
; #define PG8_BAR __builtin_amdgcn_s_barrier()
; #define PG8_SCHED __builtin_amdgcn_sched_barrier(0)
; template <bool F8 = false, class Epi, class Sched>
; __device__ __forceinline__ void gemm_phase(LAS unsigned char* lds, const int lda, const int ldb, const int K, const Sched& S, const Epi& E) {
;     ...
;             PG8_LDB(B0, 1, 0); PG8_LDB(B1, 1, 1); PG8_SCHED; PG8_LDA(At, 1, 0); PG8_STAGE(PG8_SA(0, 1), a2 + hstepA, voffA);
;             PG8_WAIT_V(8); PG8_WAIT_L(0); PG8_BAR; PG8_MMA(0, 0, At, B0); PG8_MMA(0, 1, At, B1); PG8_BAR; PG8_SCHED;
;             PG8_LDA(At, 1, 1); PG8_STAGE(PG8_SB(1, 0), b3, voffB); PG8_STAGE(PG8_SB(1, 1), b3 + hstepB, voffB); PG8_STAGE(PG8_SA(1, 0), a3, voffA);
;             PG8_WAIT_V(8); PG8_WAIT_L(0); PG8_BAR; PG8_MMA(1, 0, At, B0); PG8_MMA(1, 1, At, B1); PG8_BAR; PG8_SCHED;
;         }
;         if (wr == 0) PG8_BAR;
;         E(acc, cur, wr, wc, fr, fq);
;         if (!has_next) break;
	s_add_i32 s18, s29, s94
	v_lshl_add_u64 v[194:195], v[194:195], 0, s[40:41]
	s_mov_b32 m0, s18
	ds_read_b128 v[162:165], v247 offset:49152
	ds_read_b128 v[166:169], v247 offset:50176
	ds_read_b128 v[170:173], v247 offset:51200
	ds_read_b128 v[174:177], v247 offset:52224
	ds_read_b128 v[178:181], v247 offset:53248
	ds_read_b128 v[182:185], v247 offset:54272
	ds_read_b128 v[186:189], v247 offset:55296
	ds_read_b128 v[190:193], v247 offset:56320
	global_load_lds_dwordx4 v[194:195], off
	s_add_i32 m0, s18, 0x2000
	s_add_u32 s18, s72, 0x40080
	v_lshl_add_u64 v[194:195], v[212:213], 0, s[40:41]
	s_addc_u32 s19, s73, 0
	s_add_i32 s29, s30, s94
	global_load_lds_dwordx4 v[194:195], off
	v_lshl_add_u64 v[194:195], s[18:19], 0, v[0:1]
	s_mov_b32 m0, s29
	s_nop 0
	global_load_lds_dwordx4 v[194:195], off
	v_lshl_add_u64 v[194:195], s[18:19], 0, v[206:207]
	s_add_i32 m0, s29, 0x2000
	s_nop 0
	global_load_lds_dwordx4 v[194:195], off
	v_lshl_add_u64 v[194:195], v[214:215], 0, s[40:41]
	s_mov_b32 m0, s57
	s_nop 0
	global_load_lds_dwordx4 v[194:195], off
	v_lshl_add_u64 v[194:195], v[216:217], 0, s[40:41]
	s_mov_b32 m0, s24
	s_nop 0
	global_load_lds_dwordx4 v[194:195], off
	s_waitcnt vmcnt(8)
	s_waitcnt lgkmcnt(0)
	s_barrier
	s_setprio 1
	v_mfma_f32_16x16x32_bf16 v[62:65], v[130:133], v[162:165], v[62:65]
	v_mfma_f32_16x16x32_bf16 v[58:61], v[138:141], v[162:165], v[58:61]
	v_mfma_f32_16x16x32_bf16 v[46:49], v[130:133], v[170:173], v[46:49]
	v_mfma_f32_16x16x32_bf16 v[42:45], v[138:141], v[170:173], v[42:45]
	v_mfma_f32_16x16x32_bf16 v[30:33], v[130:133], v[178:181], v[30:33]
	v_mfma_f32_16x16x32_bf16 v[26:29], v[138:141], v[178:181], v[26:29]
	v_mfma_f32_16x16x32_bf16 v[14:17], v[130:133], v[186:189], v[14:17]
	v_mfma_f32_16x16x32_bf16 v[10:13], v[138:141], v[186:189], v[10:13]
	v_mfma_f32_16x16x32_bf16 v[62:65], v[134:137], v[166:169], v[62:65]
	v_mfma_f32_16x16x32_bf16 v[58:61], v[142:145], v[166:169], v[58:61]
	v_mfma_f32_16x16x32_bf16 v[46:49], v[134:137], v[174:177], v[46:49]
	v_mfma_f32_16x16x32_bf16 v[42:45], v[142:145], v[174:177], v[42:45]
	v_mfma_f32_16x16x32_bf16 v[30:33], v[134:137], v[182:185], v[30:33]
	v_mfma_f32_16x16x32_bf16 v[26:29], v[142:145], v[182:185], v[26:29]
	v_mfma_f32_16x16x32_bf16 v[14:17], v[134:137], v[190:193], v[14:17]
	v_mfma_f32_16x16x32_bf16 v[10:13], v[142:145], v[190:193], v[10:13]
	s_setprio 0
	s_setprio 1
	v_mfma_f32_16x16x32_bf16 v[54:57], v[146:149], v[162:165], v[54:57]
	v_mfma_f32_16x16x32_bf16 v[50:53], v[154:157], v[162:165], v[50:53]
	v_mfma_f32_16x16x32_bf16 v[38:41], v[146:149], v[170:173], v[38:41]
	v_mfma_f32_16x16x32_bf16 v[34:37], v[154:157], v[170:173], v[34:37]
	v_mfma_f32_16x16x32_bf16 v[22:25], v[146:149], v[178:181], v[22:25]
	v_mfma_f32_16x16x32_bf16 v[18:21], v[154:157], v[178:181], v[18:21]
	v_mfma_f32_16x16x32_bf16 v[6:9], v[146:149], v[186:189], v[6:9]
	v_mfma_f32_16x16x32_bf16 v[2:5], v[154:157], v[186:189], v[2:5]
	v_mfma_f32_16x16x32_bf16 v[54:57], v[150:153], v[166:169], v[54:57]
	v_mfma_f32_16x16x32_bf16 v[50:53], v[158:161], v[166:169], v[50:53]
	v_mfma_f32_16x16x32_bf16 v[38:41], v[150:153], v[174:177], v[38:41]
	v_mfma_f32_16x16x32_bf16 v[34:37], v[158:161], v[174:177], v[34:37]
	v_mfma_f32_16x16x32_bf16 v[22:25], v[150:153], v[182:185], v[22:25]
	v_mfma_f32_16x16x32_bf16 v[18:21], v[158:161], v[182:185], v[18:21]
	v_mfma_f32_16x16x32_bf16 v[6:9], v[150:153], v[190:193], v[6:9]
	v_mfma_f32_16x16x32_bf16 v[2:5], v[158:161], v[190:193], v[2:5]
	s_setprio 0
	s_barrier
	s_add_i32 s28, s28, 2
	s_add_u32 s15, s15, 0x100
	s_addc_u32 s17, s17, 0
	s_cmp_gt_u32 s28, 13
	s_mov_b64 s[18:19], s[52:53]
	s_cbranch_scc0 .LBB0_690
	s_and_b64 vcc, exec, s[12:13]
	s_cbranch_vccz .LBB0_693
	s_barrier

;     __device__ __forceinline__ const char* ptrA(const Unit& u) const { return (u.sub ? A1 : A0) + (size_t)u.pm * aT; }
;     __device__ __forceinline__ const char* ptrB(const Unit& u) const { return (u.sub ? B1 : B0) + (size_t)u.pn * bT; }
;     __device__ __forceinline__ bool next(int i, Unit& u) const { const int L = i * G + c; if (L >= 256) return false; u.sub = L & 3; const int t = L >> 2; u.pm = 64 + (t >> 3); u.pn = t & 7; return true; }
; #define PG8_STAGE(bufoff, gbase, voff) do { _Pragma("unroll") for (int _i = 0; _i < 2; ++_i) \
;         __builtin_amdgcn_global_load_lds((const unsigned*)((const char*)(gbase) + (voff)[_i]), (LAS unsigned*)(lds + (bufoff) + ldsw + _i * 8192), 16, 0, 0); } while (0)
; #define PG8_WAIT_V(n) asm volatile("s_waitcnt vmcnt(" #n ")" ::: "memory")
; #define PG8_WAIT_L(n) asm volatile("s_waitcnt lgkmcnt(" #n ")" ::: "memory")
; #define PG8_BAR __builtin_amdgcn_s_barrier()
; #define PG8_SCHED __builtin_amdgcn_sched_barrier(0)
; template <bool F8 = false, class Epi, class Sched>
; __device__ __forceinline__ void gemm_phase(LAS unsigned char* lds, const int lda, const int ldb, const int K, const Sched& S, const Epi& E) {
;     ...
;         const bool has_next = S.next(ui + 1, nxt);
;         const char* nA = has_next ? S.ptrA(nxt) : cA; const char* nB = has_next ? S.ptrB(nxt) : cB;
;         for (int t = 0; t < nt; t += 2) {
;             const bool last = (t == nt - 2);
;             const char* a1 = cA + (size_t)(t + 1) * kstep;
;             const char* a2 = last ? nA : cA + (size_t)(t + 2) * kstep; const char* b2 = last ? nB : cB + (size_t)(t + 2) * kstep;
;             const char* a3 = a2 + kstep; const char* b3 = b2 + kstep;
;             PG8_LDB(B0, 0, 0); PG8_LDB(B1, 0, 1); PG8_SCHED; PG8_LDA(At, 0, 0); PG8_STAGE(PG8_SA(1, 1), a1 + hstepA, voffA);
;             PG8_WAIT_V(8); PG8_WAIT_L(0); PG8_BAR; PG8_MMA(0, 0, At, B0); PG8_MMA(0, 1, At, B1); PG8_BAR; PG8_SCHED;
;             PG8_LDA(At, 0, 1); PG8_STAGE(PG8_SB(0, 0), b2, voffB); PG8_STAGE(PG8_SB(0, 1), b2 + hstepB, voffB); PG8_STAGE(PG8_SA(0, 0), a2, voffA);
;             PG8_WAIT_V(8); PG8_WAIT_L(0); PG8_BAR; PG8_MMA(1, 0, At, B0); PG8_MMA(1, 1, At, B1); PG8_BAR; PG8_SCHED;
.LBB0_807:
	s_add_u32 s20, s18, 0xfff80080
	s_addc_u32 s21, s19, -1
	s_add_i32 s29, 0, 0x10000
	s_cmp_eq_u32 s28, 28
	s_cselect_b32 s53, s11, s21
	s_cselect_b32 s52, s75, s20
	v_add_u32_e32 v140, s29, v143
	s_cselect_b32 s21, s9, s96
	s_cselect_b32 s20, s94, s95
	s_add_i32 s33, 0, 0x14000
	ds_read_b128 v[146:149], v140
	ds_read_b128 v[150:153], v140 offset:1024
	ds_read_b128 v[154:157], v140 offset:2048
	ds_read_b128 v[158:161], v140 offset:3072
	v_add_u32_e32 v140, s33, v143
	ds_read_b128 v[162:165], v140
	ds_read_b128 v[166:169], v140 offset:1024
	ds_read_b128 v[170:173], v140 offset:2048
	ds_read_b128 v[174:177], v140 offset:3072
	v_lshl_add_u64 v[140:141], s[18:19], 0, v[136:137]
	s_add_i32 m0, s25, 0xc000
	ds_read_b128 v[178:181], v145
	ds_read_b128 v[182:185], v145 offset:1024
	ds_read_b128 v[186:189], v145 offset:2048
	ds_read_b128 v[190:193], v145 offset:3072
	ds_read_b128 v[202:205], v145 offset:4096
	ds_read_b128 v[206:209], v145 offset:5120
	ds_read_b128 v[210:213], v145 offset:6144
	ds_read_b128 v[214:217], v145 offset:7168
	global_load_lds_dwordx4 v[140:141], off
	v_lshl_add_u64 v[140:141], s[18:19], 0, v[138:139]
	s_add_i32 m0, s25, 0xe000
	s_nop 0
	global_load_lds_dwordx4 v[140:141], off
	s_waitcnt vmcnt(8)
	s_waitcnt lgkmcnt(0)
	s_barrier
	s_setprio 1
	v_mfma_f32_16x16x32_bf16 v[126:129], v[146:149], v[178:181], v[126:129]
	v_mfma_f32_16x16x32_bf16 v[122:125], v[154:157], v[178:181], v[122:125]
	v_mfma_f32_16x16x32_bf16 v[118:121], v[146:149], v[186:189], v[118:121]
	v_mfma_f32_16x16x32_bf16 v[110:113], v[154:157], v[186:189], v[110:113]
	v_mfma_f32_16x16x32_bf16 v[102:105], v[146:149], v[202:205], v[102:105]
	v_mfma_f32_16x16x32_bf16 v[94:97], v[154:157], v[202:205], v[94:97]
	v_mfma_f32_16x16x32_bf16 v[86:89], v[146:149], v[210:213], v[86:89]
	v_mfma_f32_16x16x32_bf16 v[78:81], v[154:157], v[210:213], v[78:81]
	v_mfma_f32_16x16x32_bf16 v[126:129], v[150:153], v[182:185], v[126:129]
	v_mfma_f32_16x16x32_bf16 v[122:125], v[158:161], v[182:185], v[122:125]
	v_mfma_f32_16x16x32_bf16 v[118:121], v[150:153], v[190:193], v[118:121]
	v_mfma_f32_16x16x32_bf16 v[110:113], v[158:161], v[190:193], v[110:113]
	v_mfma_f32_16x16x32_bf16 v[102:105], v[150:153], v[206:209], v[102:105]
	v_mfma_f32_16x16x32_bf16 v[94:97], v[158:161], v[206:209], v[94:97]
	v_mfma_f32_16x16x32_bf16 v[86:89], v[150:153], v[214:217], v[86:89]
	v_mfma_f32_16x16x32_bf16 v[78:81], v[158:161], v[214:217], v[78:81]
	s_setprio 0
	s_setprio 1
	v_mfma_f32_16x16x32_bf16 v[114:117], v[162:165], v[178:181], v[114:117]
	v_mfma_f32_16x16x32_bf16 v[106:109], v[170:173], v[178:181], v[106:109]
	v_mfma_f32_16x16x32_bf16 v[98:101], v[162:165], v[186:189], v[98:101]
	v_mfma_f32_16x16x32_bf16 v[90:93], v[170:173], v[186:189], v[90:93]
	v_mfma_f32_16x16x32_bf16 v[82:85], v[162:165], v[202:205], v[82:85]
	v_mfma_f32_16x16x32_bf16 v[74:77], v[170:173], v[202:205], v[74:77]
	v_mfma_f32_16x16x32_bf16 v[70:73], v[162:165], v[210:213], v[70:73]
	v_mfma_f32_16x16x32_bf16 v[66:69], v[170:173], v[210:213], v[66:69]
	v_mfma_f32_16x16x32_bf16 v[114:117], v[166:169], v[182:185], v[114:117]
	v_mfma_f32_16x16x32_bf16 v[106:109], v[174:177], v[182:185], v[106:109]
	v_mfma_f32_16x16x32_bf16 v[98:101], v[166:169], v[190:193], v[98:101]
	v_mfma_f32_16x16x32_bf16 v[90:93], v[174:177], v[190:193], v[90:93]
	v_mfma_f32_16x16x32_bf16 v[82:85], v[166:169], v[206:209], v[82:85]
	v_mfma_f32_16x16x32_bf16 v[74:77], v[174:177], v[206:209], v[74:77]
	v_mfma_f32_16x16x32_bf16 v[70:73], v[166:169], v[214:217], v[70:73]
	v_mfma_f32_16x16x32_bf16 v[66:69], v[174:177], v[214:217], v[66:69]
	s_setprio 0
	s_barrier
	s_add_i32 s29, s29, s24
	v_lshl_add_u64 v[140:141], s[20:21], 0, v[0:1]
	s_mov_b32 m0, s29
	ds_read_b128 v[178:181], v145 offset:16384
	ds_read_b128 v[182:185], v145 offset:17408
	ds_read_b128 v[186:189], v145 offset:18432
	ds_read_b128 v[190:193], v145 offset:19456
	ds_read_b128 v[202:205], v145 offset:20480
	ds_read_b128 v[206:209], v145 offset:21504
	ds_read_b128 v[210:213], v145 offset:22528
	ds_read_b128 v[214:217], v145 offset:23552
	global_load_lds_dwordx4 v[140:141], off
	s_add_i32 m0, s29, 0x2000
	s_add_u32 s30, s20, 0x80000
	v_lshl_add_u64 v[194:195], s[20:21], 0, v[130:131]
	s_addc_u32 s31, s21, 0
	s_add_i32 s29, s33, s24
	global_load_lds_dwordx4 v[194:195], off
	v_lshl_add_u64 v[218:219], s[30:31], 0, v[0:1]
	s_mov_b32 m0, s29
	v_lshl_add_u64 v[220:221], s[52:53], 0, v[132:133]
	global_load_lds_dwordx4 v[218:219], off
	v_lshl_add_u64 v[218:219], s[30:31], 0, v[130:131]
	s_add_i32 m0, s29, 0x2000
	s_nop 0
	global_load_lds_dwordx4 v[218:219], off
	v_lshl_add_u64 v[218:219], s[52:53], 0, v[134:135]
	s_mov_b32 m0, s25
	s_nop 0
	global_load_lds_dwordx4 v[218:219], off
	s_mov_b32 m0, s26
	s_nop 0
	global_load_lds_dwordx4 v[220:221], off
	s_waitcnt vmcnt(8)
	s_waitcnt lgkmcnt(0)
	s_barrier
; #define PG8_STAGE(bufoff, gbase, voff) do { _Pragma("unroll") for (int _i = 0; _i < 2; ++_i) \
;         __builtin_amdgcn_global_load_lds((const unsigned*)((const char*)(gbase) + (voff)[_i]), (LAS unsigned*)(lds + (bufoff) + ldsw + _i * 8192), 16, 0, 0); } while (0)
; #define PG8_WAIT_V(n) asm volatile("s_waitcnt vmcnt(" #n ")" ::: "memory")
; #define PG8_WAIT_L(n) asm volatile("s_waitcnt lgkmcnt(" #n ")" ::: "memory")
; #define PG8_BAR __builtin_amdgcn_s_barrier()
; #define PG8_SCHED __builtin_amdgcn_sched_barrier(0)
; template <bool F8 = false, class Epi, class Sched>
; __device__ __forceinline__ void gemm_phase(LAS unsigned char* lds, const int lda, const int ldb, const int K, const Sched& S, const Epi& E) {
;     ...
;             PG8_WAIT_V(8); PG8_WAIT_L(0); PG8_BAR; PG8_MMA(0, 0, At, B0); PG8_MMA(0, 1, At, B1); PG8_BAR; PG8_SCHED;
;             PG8_LDA(At, 0, 1); PG8_STAGE(PG8_SB(0, 0), b2, voffB); PG8_STAGE(PG8_SB(0, 1), b2 + hstepB, voffB); PG8_STAGE(PG8_SA(0, 0), a2, voffA);
;             PG8_WAIT_V(8); PG8_WAIT_L(0); PG8_BAR; PG8_MMA(1, 0, At, B0); PG8_MMA(1, 1, At, B1); PG8_BAR; PG8_SCHED;
;             PG8_LDB(B0, 1, 0); PG8_LDB(B1, 1, 1); PG8_SCHED; PG8_LDA(At, 1, 0); PG8_STAGE(PG8_SA(0, 1), a2 + hstepA, voffA);
;             PG8_WAIT_V(8); PG8_WAIT_L(0); PG8_BAR; PG8_MMA(0, 0, At, B0); PG8_MMA(0, 1, At, B1); PG8_BAR; PG8_SCHED;
;             PG8_LDA(At, 1, 1); PG8_STAGE(PG8_SB(1, 0), b3, voffB); PG8_STAGE(PG8_SB(1, 1), b3 + hstepB, voffB); PG8_STAGE(PG8_SA(1, 0), a3, voffA);
;             PG8_WAIT_V(8); PG8_WAIT_L(0); PG8_BAR; PG8_MMA(1, 0, At, B0); PG8_MMA(1, 1, At, B1); PG8_BAR; PG8_SCHED;
	s_setprio 1
	v_mfma_f32_16x16x32_bf16 v[62:65], v[146:149], v[178:181], v[62:65]
	v_mfma_f32_16x16x32_bf16 v[58:61], v[154:157], v[178:181], v[58:61]
	v_mfma_f32_16x16x32_bf16 v[54:57], v[146:149], v[186:189], v[54:57]
	v_mfma_f32_16x16x32_bf16 v[46:49], v[154:157], v[186:189], v[46:49]
	v_mfma_f32_16x16x32_bf16 v[38:41], v[146:149], v[202:205], v[38:41]
	v_mfma_f32_16x16x32_bf16 v[30:33], v[154:157], v[202:205], v[30:33]
	v_mfma_f32_16x16x32_bf16 v[22:25], v[146:149], v[210:213], v[22:25]
	v_mfma_f32_16x16x32_bf16 v[14:17], v[154:157], v[210:213], v[14:17]
	v_mfma_f32_16x16x32_bf16 v[62:65], v[150:153], v[182:185], v[62:65]
	v_mfma_f32_16x16x32_bf16 v[58:61], v[158:161], v[182:185], v[58:61]
	v_mfma_f32_16x16x32_bf16 v[54:57], v[150:153], v[190:193], v[54:57]
	v_mfma_f32_16x16x32_bf16 v[46:49], v[158:161], v[190:193], v[46:49]
	v_mfma_f32_16x16x32_bf16 v[38:41], v[150:153], v[206:209], v[38:41]
	v_mfma_f32_16x16x32_bf16 v[30:33], v[158:161], v[206:209], v[30:33]
	v_mfma_f32_16x16x32_bf16 v[22:25], v[150:153], v[214:217], v[22:25]
	v_mfma_f32_16x16x32_bf16 v[14:17], v[158:161], v[214:217], v[14:17]
	s_setprio 0
	s_setprio 1
	v_mfma_f32_16x16x32_bf16 v[50:53], v[162:165], v[178:181], v[50:53]
	v_mfma_f32_16x16x32_bf16 v[42:45], v[170:173], v[178:181], v[42:45]
	v_mfma_f32_16x16x32_bf16 v[34:37], v[162:165], v[186:189], v[34:37]
	v_mfma_f32_16x16x32_bf16 v[26:29], v[170:173], v[186:189], v[26:29]
	v_mfma_f32_16x16x32_bf16 v[18:21], v[162:165], v[202:205], v[18:21]
	v_mfma_f32_16x16x32_bf16 v[10:13], v[170:173], v[202:205], v[10:13]
	v_mfma_f32_16x16x32_bf16 v[6:9], v[162:165], v[210:213], v[6:9]
	v_mfma_f32_16x16x32_bf16 v[2:5], v[170:173], v[210:213], v[2:5]
	v_mfma_f32_16x16x32_bf16 v[50:53], v[166:169], v[182:185], v[50:53]
	v_mfma_f32_16x16x32_bf16 v[42:45], v[174:177], v[182:185], v[42:45]
	v_mfma_f32_16x16x32_bf16 v[34:37], v[166:169], v[190:193], v[34:37]
	v_mfma_f32_16x16x32_bf16 v[26:29], v[174:177], v[190:193], v[26:29]
	v_mfma_f32_16x16x32_bf16 v[18:21], v[166:169], v[206:209], v[18:21]
	v_mfma_f32_16x16x32_bf16 v[10:13], v[174:177], v[206:209], v[10:13]
	v_mfma_f32_16x16x32_bf16 v[6:9], v[166:169], v[214:217], v[6:9]
	v_mfma_f32_16x16x32_bf16 v[2:5], v[174:177], v[214:217], v[2:5]
	s_setprio 0
	s_barrier
	s_add_i32 s29, 0, 0x18000
	s_add_i32 s33, 0, 0x1c000
	v_add_u32_e32 v158, s29, v143
	v_add_u32_e32 v174, s33, v143
	ds_read_b128 v[146:149], v158
	ds_read_b128 v[150:153], v158 offset:1024
	ds_read_b128 v[154:157], v158 offset:2048
	ds_read_b128 v[158:161], v158 offset:3072
	ds_read_b128 v[162:165], v174
	ds_read_b128 v[166:169], v174 offset:1024
	ds_read_b128 v[170:173], v174 offset:2048
	ds_read_b128 v[174:177], v174 offset:3072
	s_add_u32 s30, s52, 0x80000
	s_addc_u32 s31, s53, 0
	s_mov_b32 m0, s27
	v_lshl_add_u64 v[222:223], s[30:31], 0, v[134:135]
	ds_read_b128 v[178:181], v145 offset:32768
	ds_read_b128 v[182:185], v145 offset:33792
	ds_read_b128 v[186:189], v145 offset:34816
	ds_read_b128 v[190:193], v145 offset:35840
	ds_read_b128 v[202:205], v145 offset:36864
	ds_read_b128 v[206:209], v145 offset:37888
	ds_read_b128 v[210:213], v145 offset:38912
	ds_read_b128 v[214:217], v145 offset:39936
	global_load_lds_dwordx4 v[222:223], off
	v_lshl_add_u64 v[222:223], s[30:31], 0, v[132:133]
	s_mov_b32 m0, s44
	s_nop 0
	global_load_lds_dwordx4 v[222:223], off
	s_waitcnt vmcnt(8)
	s_waitcnt lgkmcnt(0)
	s_barrier
	s_setprio 1
	v_mfma_f32_16x16x32_bf16 v[126:129], v[146:149], v[178:181], v[126:129]
	v_mfma_f32_16x16x32_bf16 v[122:125], v[154:157], v[178:181], v[122:125]
	v_mfma_f32_16x16x32_bf16 v[118:121], v[146:149], v[186:189], v[118:121]
	v_mfma_f32_16x16x32_bf16 v[110:113], v[154:157], v[186:189], v[110:113]
	v_mfma_f32_16x16x32_bf16 v[102:105], v[146:149], v[202:205], v[102:105]
	v_mfma_f32_16x16x32_bf16 v[94:97], v[154:157], v[202:205], v[94:97]
	v_mfma_f32_16x16x32_bf16 v[86:89], v[146:149], v[210:213], v[86:89]
	v_mfma_f32_16x16x32_bf16 v[78:81], v[154:157], v[210:213], v[78:81]
	v_mfma_f32_16x16x32_bf16 v[126:129], v[150:153], v[182:185], v[126:129]
	v_mfma_f32_16x16x32_bf16 v[122:125], v[158:161], v[182:185], v[122:125]
	v_mfma_f32_16x16x32_bf16 v[118:121], v[150:153], v[190:193], v[118:121]
	v_mfma_f32_16x16x32_bf16 v[110:113], v[158:161], v[190:193], v[110:113]
	v_mfma_f32_16x16x32_bf16 v[102:105], v[150:153], v[206:209], v[102:105]
	v_mfma_f32_16x16x32_bf16 v[94:97], v[158:161], v[206:209], v[94:97]
	v_mfma_f32_16x16x32_bf16 v[86:89], v[150:153], v[214:217], v[86:89]
	v_mfma_f32_16x16x32_bf16 v[78:81], v[158:161], v[214:217], v[78:81]
	s_setprio 0
	s_setprio 1
	v_mfma_f32_16x16x32_bf16 v[114:117], v[162:165], v[178:181], v[114:117]
	v_mfma_f32_16x16x32_bf16 v[106:109], v[170:173], v[178:181], v[106:109]
	v_mfma_f32_16x16x32_bf16 v[98:101], v[162:165], v[186:189], v[98:101]
	v_mfma_f32_16x16x32_bf16 v[90:93], v[170:173], v[186:189], v[90:93]
	v_mfma_f32_16x16x32_bf16 v[82:85], v[162:165], v[202:205], v[82:85]
	v_mfma_f32_16x16x32_bf16 v[74:77], v[170:173], v[202:205], v[74:77]
	v_mfma_f32_16x16x32_bf16 v[70:73], v[162:165], v[210:213], v[70:73]
	v_mfma_f32_16x16x32_bf16 v[66:69], v[170:173], v[210:213], v[66:69]
	v_mfma_f32_16x16x32_bf16 v[114:117], v[166:169], v[182:185], v[114:117]
	v_mfma_f32_16x16x32_bf16 v[106:109], v[174:177], v[182:185], v[106:109]
	v_mfma_f32_16x16x32_bf16 v[98:101], v[166:169], v[190:193], v[98:101]
	v_mfma_f32_16x16x32_bf16 v[90:93], v[174:177], v[190:193], v[90:93]
	v_mfma_f32_16x16x32_bf16 v[82:85], v[166:169], v[206:209], v[82:85]
	v_mfma_f32_16x16x32_bf16 v[74:77], v[174:177], v[206:209], v[74:77]
	v_mfma_f32_16x16x32_bf16 v[70:73], v[166:169], v[214:217], v[70:73]
	v_mfma_f32_16x16x32_bf16 v[66:69], v[174:177], v[214:217], v[66:69]
	s_setprio 0
	s_barrier
; #define PG8_STAGE(bufoff, gbase, voff) do { _Pragma("unroll") for (int _i = 0; _i < 2; ++_i) \
;         __builtin_amdgcn_global_load_lds((const unsigned*)((const char*)(gbase) + (voff)[_i]), (LAS unsigned*)(lds + (bufoff) + ldsw + _i * 8192), 16, 0, 0); } while (0)
; #define PG8_WAIT_V(n) asm volatile("s_waitcnt vmcnt(" #n ")" ::: "memory")
; #define PG8_WAIT_L(n) asm volatile("s_waitcnt lgkmcnt(" #n ")" ::: "memory")
; #define PG8_BAR __builtin_amdgcn_s_barrier()
; #define PG8_SCHED __builtin_amdgcn_sched_barrier(0)
; template <bool F8 = false, class Epi, class Sched>
; __device__ __forceinline__ void gemm_phase(LAS unsigned char* lds, const int lda, const int ldb, const int K, const Sched& S, const Epi& E) {
;     ...
;             PG8_LDB(B0, 1, 0); PG8_LDB(B1, 1, 1); PG8_SCHED; PG8_LDA(At, 1, 0); PG8_STAGE(PG8_SA(0, 1), a2 + hstepA, voffA);
;             PG8_WAIT_V(8); PG8_WAIT_L(0); PG8_BAR; PG8_MMA(0, 0, At, B0); PG8_MMA(0, 1, At, B1); PG8_BAR; PG8_SCHED;
;             PG8_LDA(At, 1, 1); PG8_STAGE(PG8_SB(1, 0), b3, voffB); PG8_STAGE(PG8_SB(1, 1), b3 + hstepB, voffB); PG8_STAGE(PG8_SA(1, 0), a3, voffA);
;             PG8_WAIT_V(8); PG8_WAIT_L(0); PG8_BAR; PG8_MMA(1, 0, At, B0); PG8_MMA(1, 1, At, B1); PG8_BAR; PG8_SCHED;
;         }
;         if (wr == 0) PG8_BAR;
;         E(acc, cur, wr, wc, fr, fq);
;         if (!has_next) break;
	s_add_i32 s29, s29, s24
	v_lshl_add_u64 v[140:141], v[140:141], 0, s[40:41]
	s_mov_b32 m0, s29
	ds_read_b128 v[178:181], v145 offset:49152
	ds_read_b128 v[182:185], v145 offset:50176
	ds_read_b128 v[186:189], v145 offset:51200
	ds_read_b128 v[190:193], v145 offset:52224
	ds_read_b128 v[202:205], v145 offset:53248
	ds_read_b128 v[206:209], v145 offset:54272
	ds_read_b128 v[210:213], v145 offset:55296
	ds_read_b128 v[214:217], v145 offset:56320
	global_load_lds_dwordx4 v[140:141], off
	s_add_i32 m0, s29, 0x2000
	s_add_u32 s20, s20, 0x80080
	v_lshl_add_u64 v[140:141], v[194:195], 0, s[40:41]
	s_addc_u32 s21, s21, 0
	s_add_i32 s29, s33, s24
	global_load_lds_dwordx4 v[140:141], off
	v_lshl_add_u64 v[140:141], s[20:21], 0, v[0:1]
	s_mov_b32 m0, s29
	s_nop 0
	global_load_lds_dwordx4 v[140:141], off
	v_lshl_add_u64 v[140:141], s[20:21], 0, v[130:131]
	s_add_i32 m0, s29, 0x2000
	s_nop 0
	global_load_lds_dwordx4 v[140:141], off
	v_lshl_add_u64 v[140:141], v[218:219], 0, s[40:41]
	s_mov_b32 m0, s56
	s_nop 0
	global_load_lds_dwordx4 v[140:141], off
	v_lshl_add_u64 v[140:141], v[220:221], 0, s[40:41]
	s_mov_b32 m0, s57
	s_nop 0
	global_load_lds_dwordx4 v[140:141], off
	s_waitcnt vmcnt(8)
	s_waitcnt lgkmcnt(0)
	s_barrier
	s_setprio 1
	v_mfma_f32_16x16x32_bf16 v[62:65], v[146:149], v[178:181], v[62:65]
	v_mfma_f32_16x16x32_bf16 v[58:61], v[154:157], v[178:181], v[58:61]
	v_mfma_f32_16x16x32_bf16 v[54:57], v[146:149], v[186:189], v[54:57]
	v_mfma_f32_16x16x32_bf16 v[46:49], v[154:157], v[186:189], v[46:49]
	v_mfma_f32_16x16x32_bf16 v[38:41], v[146:149], v[202:205], v[38:41]
	v_mfma_f32_16x16x32_bf16 v[30:33], v[154:157], v[202:205], v[30:33]
	v_mfma_f32_16x16x32_bf16 v[22:25], v[146:149], v[210:213], v[22:25]
	v_mfma_f32_16x16x32_bf16 v[14:17], v[154:157], v[210:213], v[14:17]
	v_mfma_f32_16x16x32_bf16 v[62:65], v[150:153], v[182:185], v[62:65]
	v_mfma_f32_16x16x32_bf16 v[58:61], v[158:161], v[182:185], v[58:61]
	v_mfma_f32_16x16x32_bf16 v[54:57], v[150:153], v[190:193], v[54:57]
	v_mfma_f32_16x16x32_bf16 v[46:49], v[158:161], v[190:193], v[46:49]
	v_mfma_f32_16x16x32_bf16 v[38:41], v[150:153], v[206:209], v[38:41]
	v_mfma_f32_16x16x32_bf16 v[30:33], v[158:161], v[206:209], v[30:33]
	v_mfma_f32_16x16x32_bf16 v[22:25], v[150:153], v[214:217], v[22:25]
	v_mfma_f32_16x16x32_bf16 v[14:17], v[158:161], v[214:217], v[14:17]
	s_setprio 0
	s_setprio 1
	v_mfma_f32_16x16x32_bf16 v[50:53], v[162:165], v[178:181], v[50:53]
	v_mfma_f32_16x16x32_bf16 v[42:45], v[170:173], v[178:181], v[42:45]
	v_mfma_f32_16x16x32_bf16 v[34:37], v[162:165], v[186:189], v[34:37]
	v_mfma_f32_16x16x32_bf16 v[26:29], v[170:173], v[186:189], v[26:29]
	v_mfma_f32_16x16x32_bf16 v[18:21], v[162:165], v[202:205], v[18:21]
	v_mfma_f32_16x16x32_bf16 v[10:13], v[170:173], v[202:205], v[10:13]
	v_mfma_f32_16x16x32_bf16 v[6:9], v[162:165], v[210:213], v[6:9]
	v_mfma_f32_16x16x32_bf16 v[2:5], v[170:173], v[210:213], v[2:5]
	v_mfma_f32_16x16x32_bf16 v[50:53], v[166:169], v[182:185], v[50:53]
	v_mfma_f32_16x16x32_bf16 v[42:45], v[174:177], v[182:185], v[42:45]
	v_mfma_f32_16x16x32_bf16 v[34:37], v[166:169], v[190:193], v[34:37]
	v_mfma_f32_16x16x32_bf16 v[26:29], v[174:177], v[190:193], v[26:29]
	v_mfma_f32_16x16x32_bf16 v[18:21], v[166:169], v[206:209], v[18:21]
	v_mfma_f32_16x16x32_bf16 v[10:13], v[174:177], v[206:209], v[10:13]
	v_mfma_f32_16x16x32_bf16 v[6:9], v[166:169], v[214:217], v[6:9]
	v_mfma_f32_16x16x32_bf16 v[2:5], v[174:177], v[214:217], v[2:5]
	s_setprio 0
	s_barrier
	s_add_i32 s28, s28, 2
	s_add_u32 s18, s18, 0x100
	s_addc_u32 s19, s19, 0
	s_add_u32 s95, s95, 0x100
	s_addc_u32 s96, s96, 0
	s_cmp_gt_u32 s28, 29
	s_cbranch_scc0 .LBB0_807
	s_and_b64 vcc, exec, s[6:7]
	s_cbranch_vccz .LBB0_810
	s_barrier

;     __device__ __forceinline__ const char* ptrA(const Unit& u) const { return (u.sub ? A1 : A0) + (size_t)u.pm * aT; }
;     __device__ __forceinline__ const char* ptrB(const Unit& u) const { return (u.sub ? B1 : B0) + (size_t)u.pn * bT; }
;     __device__ __forceinline__ bool next(int i, Unit& u) const { const int L = i * G + c; if (L >= 256) return false; u.sub = L & 3; const int t = L >> 2; u.pm = 64 + (t >> 3); u.pn = t & 7; return true; }
; #define PG8_STAGE(bufoff, gbase, voff) do { _Pragma("unroll") for (int _i = 0; _i < 2; ++_i) \
;         __builtin_amdgcn_global_load_lds((const unsigned*)((const char*)(gbase) + (voff)[_i]), (LAS unsigned*)(lds + (bufoff) + ldsw + _i * 8192), 16, 0, 0); } while (0)
; #define PG8_WAIT_V(n) asm volatile("s_waitcnt vmcnt(" #n ")" ::: "memory")
; #define PG8_WAIT_L(n) asm volatile("s_waitcnt lgkmcnt(" #n ")" ::: "memory")
; #define PG8_BAR __builtin_amdgcn_s_barrier()
; #define PG8_SCHED __builtin_amdgcn_sched_barrier(0)
; template <bool F8 = false, class Epi, class Sched>
; __device__ __forceinline__ void gemm_phase(LAS unsigned char* lds, const int lda, const int ldb, const int K, const Sched& S, const Epi& E) {
;     ...
;         const bool has_next = S.next(ui + 1, nxt);
;         const char* nA = has_next ? S.ptrA(nxt) : cA; const char* nB = has_next ? S.ptrB(nxt) : cB;
;         for (int t = 0; t < nt; t += 2) {
;             const bool last = (t == nt - 2);
;             const char* a1 = cA + (size_t)(t + 1) * kstep;
;             const char* a2 = last ? nA : cA + (size_t)(t + 2) * kstep; const char* b2 = last ? nB : cB + (size_t)(t + 2) * kstep;
;             const char* a3 = a2 + kstep; const char* b3 = b2 + kstep;
;             PG8_LDB(B0, 0, 0); PG8_LDB(B1, 0, 1); PG8_SCHED; PG8_LDA(At, 0, 0); PG8_STAGE(PG8_SA(1, 1), a1 + hstepA, voffA);
;             PG8_WAIT_V(8); PG8_WAIT_L(0); PG8_BAR; PG8_MMA(0, 0, At, B0); PG8_MMA(0, 1, At, B1); PG8_BAR; PG8_SCHED;
;             PG8_LDA(At, 0, 1); PG8_STAGE(PG8_SB(0, 0), b2, voffB); PG8_STAGE(PG8_SB(0, 1), b2 + hstepB, voffB); PG8_STAGE(PG8_SA(0, 0), a2, voffA);
;             PG8_WAIT_V(8); PG8_WAIT_L(0); PG8_BAR; PG8_MMA(1, 0, At, B0); PG8_MMA(1, 1, At, B1); PG8_BAR; PG8_SCHED;
.LBB0_835:
	s_add_u32 s18, s16, 0xfff80080
	s_addc_u32 s19, s17, -1
	s_add_i32 s29, 0, 0x10000
	s_cmp_eq_u32 s28, 4
	s_cselect_b32 s21, s13, s19
	s_cselect_b32 s20, s12, s18
	v_add_u32_e32 v0, s29, v140
	s_cselect_b32 s19, s75, s96
	s_cselect_b32 s18, s94, s95
	s_add_i32 s33, 0, 0x14000
	ds_read_b128 v[144:147], v0
	ds_read_b128 v[148:151], v0 offset:1024
	ds_read_b128 v[152:155], v0 offset:2048
	ds_read_b128 v[156:159], v0 offset:3072
	v_add_u32_e32 v0, s33, v140
	ds_read_b128 v[160:163], v0
	ds_read_b128 v[164:167], v0 offset:1024
	ds_read_b128 v[168:171], v0 offset:2048
	ds_read_b128 v[172:175], v0 offset:3072
	v_lshl_add_u64 v[138:139], s[16:17], 0, v[134:135]
	s_add_i32 m0, s25, 0xc000
	ds_read_b128 v[176:179], v142
	ds_read_b128 v[180:183], v142 offset:1024
	ds_read_b128 v[184:187], v142 offset:2048
	ds_read_b128 v[188:191], v142 offset:3072
	ds_read_b128 v[192:195], v142 offset:4096
	ds_read_b128 v[202:205], v142 offset:5120
	ds_read_b128 v[206:209], v142 offset:6144
	ds_read_b128 v[210:213], v142 offset:7168
	global_load_lds_dwordx4 v[138:139], off
	v_lshl_add_u64 v[138:139], s[16:17], 0, v[136:137]
	s_add_i32 m0, s25, 0xe000
	s_nop 0
	global_load_lds_dwordx4 v[138:139], off
	s_waitcnt vmcnt(8)
	s_waitcnt lgkmcnt(0)
	s_barrier
	s_setprio 1
	v_mfma_f32_16x16x32_bf16 v[126:129], v[144:147], v[176:179], v[126:129]
	v_mfma_f32_16x16x32_bf16 v[122:125], v[152:155], v[176:179], v[122:125]
	v_mfma_f32_16x16x32_bf16 v[118:121], v[144:147], v[184:187], v[118:121]
	v_mfma_f32_16x16x32_bf16 v[110:113], v[152:155], v[184:187], v[110:113]
	v_mfma_f32_16x16x32_bf16 v[102:105], v[144:147], v[192:195], v[102:105]
	v_mfma_f32_16x16x32_bf16 v[94:97], v[152:155], v[192:195], v[94:97]
	v_mfma_f32_16x16x32_bf16 v[86:89], v[144:147], v[206:209], v[86:89]
	v_mfma_f32_16x16x32_bf16 v[78:81], v[152:155], v[206:209], v[78:81]
	v_mfma_f32_16x16x32_bf16 v[126:129], v[148:151], v[180:183], v[126:129]
	v_mfma_f32_16x16x32_bf16 v[122:125], v[156:159], v[180:183], v[122:125]
	v_mfma_f32_16x16x32_bf16 v[118:121], v[148:151], v[188:191], v[118:121]
	v_mfma_f32_16x16x32_bf16 v[110:113], v[156:159], v[188:191], v[110:113]
	v_mfma_f32_16x16x32_bf16 v[102:105], v[148:151], v[202:205], v[102:105]
	v_mfma_f32_16x16x32_bf16 v[94:97], v[156:159], v[202:205], v[94:97]
	v_mfma_f32_16x16x32_bf16 v[86:89], v[148:151], v[210:213], v[86:89]
	v_mfma_f32_16x16x32_bf16 v[78:81], v[156:159], v[210:213], v[78:81]
	s_setprio 0
	s_setprio 1
	v_mfma_f32_16x16x32_bf16 v[114:117], v[160:163], v[176:179], v[114:117]
	v_mfma_f32_16x16x32_bf16 v[106:109], v[168:171], v[176:179], v[106:109]
	v_mfma_f32_16x16x32_bf16 v[98:101], v[160:163], v[184:187], v[98:101]
	v_mfma_f32_16x16x32_bf16 v[90:93], v[168:171], v[184:187], v[90:93]
	v_mfma_f32_16x16x32_bf16 v[82:85], v[160:163], v[192:195], v[82:85]
	v_mfma_f32_16x16x32_bf16 v[74:77], v[168:171], v[192:195], v[74:77]
	v_mfma_f32_16x16x32_bf16 v[70:73], v[160:163], v[206:209], v[70:73]
	v_mfma_f32_16x16x32_bf16 v[66:69], v[168:171], v[206:209], v[66:69]
	v_mfma_f32_16x16x32_bf16 v[114:117], v[164:167], v[180:183], v[114:117]
	v_mfma_f32_16x16x32_bf16 v[106:109], v[172:175], v[180:183], v[106:109]
	v_mfma_f32_16x16x32_bf16 v[98:101], v[164:167], v[188:191], v[98:101]
	v_mfma_f32_16x16x32_bf16 v[90:93], v[172:175], v[188:191], v[90:93]
	v_mfma_f32_16x16x32_bf16 v[82:85], v[164:167], v[202:205], v[82:85]
	v_mfma_f32_16x16x32_bf16 v[74:77], v[172:175], v[202:205], v[74:77]
	v_mfma_f32_16x16x32_bf16 v[70:73], v[164:167], v[210:213], v[70:73]
	v_mfma_f32_16x16x32_bf16 v[66:69], v[172:175], v[210:213], v[66:69]
	s_setprio 0
	s_barrier
	s_add_i32 s29, s29, s24
	v_lshl_add_u64 v[138:139], s[18:19], 0, v[132:133]
	s_mov_b32 m0, s29
	ds_read_b128 v[176:179], v142 offset:16384
	ds_read_b128 v[180:183], v142 offset:17408
	ds_read_b128 v[184:187], v142 offset:18432
	ds_read_b128 v[188:191], v142 offset:19456
	ds_read_b128 v[192:195], v142 offset:20480
	ds_read_b128 v[202:205], v142 offset:21504
	ds_read_b128 v[206:209], v142 offset:22528
	ds_read_b128 v[210:213], v142 offset:23552
	global_load_lds_dwordx4 v[138:139], off
	s_add_i32 m0, s29, 0x2000
	s_add_u32 s30, s18, 0x80000
	v_lshl_add_u64 v[214:215], s[18:19], 0, v[130:131]
	s_addc_u32 s31, s19, 0
	s_add_i32 s29, s33, s24
	global_load_lds_dwordx4 v[214:215], off
	v_lshl_add_u64 v[216:217], s[30:31], 0, v[132:133]
	s_mov_b32 m0, s29
	v_lshl_add_u64 v[218:219], s[20:21], 0, v[130:131]
	global_load_lds_dwordx4 v[216:217], off
	v_lshl_add_u64 v[216:217], s[30:31], 0, v[130:131]
	s_add_i32 m0, s29, 0x2000
	s_nop 0
	global_load_lds_dwordx4 v[216:217], off
	v_lshl_add_u64 v[216:217], s[20:21], 0, v[132:133]
	s_mov_b32 m0, s25
	s_nop 0
	global_load_lds_dwordx4 v[216:217], off
	s_mov_b32 m0, s26
	s_nop 0
	global_load_lds_dwordx4 v[218:219], off
	s_waitcnt vmcnt(8)
	s_waitcnt lgkmcnt(0)
	s_barrier
; #define PG8_STAGE(bufoff, gbase, voff) do { _Pragma("unroll") for (int _i = 0; _i < 2; ++_i) \
;         __builtin_amdgcn_global_load_lds((const unsigned*)((const char*)(gbase) + (voff)[_i]), (LAS unsigned*)(lds + (bufoff) + ldsw + _i * 8192), 16, 0, 0); } while (0)
; #define PG8_WAIT_V(n) asm volatile("s_waitcnt vmcnt(" #n ")" ::: "memory")
; #define PG8_WAIT_L(n) asm volatile("s_waitcnt lgkmcnt(" #n ")" ::: "memory")
; #define PG8_BAR __builtin_amdgcn_s_barrier()
; #define PG8_SCHED __builtin_amdgcn_sched_barrier(0)
; template <bool F8 = false, class Epi, class Sched>
; __device__ __forceinline__ void gemm_phase(LAS unsigned char* lds, const int lda, const int ldb, const int K, const Sched& S, const Epi& E) {
;     ...
;             PG8_WAIT_V(8); PG8_WAIT_L(0); PG8_BAR; PG8_MMA(0, 0, At, B0); PG8_MMA(0, 1, At, B1); PG8_BAR; PG8_SCHED;
;             PG8_LDA(At, 0, 1); PG8_STAGE(PG8_SB(0, 0), b2, voffB); PG8_STAGE(PG8_SB(0, 1), b2 + hstepB, voffB); PG8_STAGE(PG8_SA(0, 0), a2, voffA);
;             PG8_WAIT_V(8); PG8_WAIT_L(0); PG8_BAR; PG8_MMA(1, 0, At, B0); PG8_MMA(1, 1, At, B1); PG8_BAR; PG8_SCHED;
;             PG8_LDB(B0, 1, 0); PG8_LDB(B1, 1, 1); PG8_SCHED; PG8_LDA(At, 1, 0); PG8_STAGE(PG8_SA(0, 1), a2 + hstepA, voffA);
;             PG8_WAIT_V(8); PG8_WAIT_L(0); PG8_BAR; PG8_MMA(0, 0, At, B0); PG8_MMA(0, 1, At, B1); PG8_BAR; PG8_SCHED;
;             PG8_LDA(At, 1, 1); PG8_STAGE(PG8_SB(1, 0), b3, voffB); PG8_STAGE(PG8_SB(1, 1), b3 + hstepB, voffB); PG8_STAGE(PG8_SA(1, 0), a3, voffA);
;             PG8_WAIT_V(8); PG8_WAIT_L(0); PG8_BAR; PG8_MMA(1, 0, At, B0); PG8_MMA(1, 1, At, B1); PG8_BAR; PG8_SCHED;
	s_setprio 1
	v_mfma_f32_16x16x32_bf16 v[62:65], v[144:147], v[176:179], v[62:65]
	v_mfma_f32_16x16x32_bf16 v[58:61], v[152:155], v[176:179], v[58:61]
	v_mfma_f32_16x16x32_bf16 v[54:57], v[144:147], v[184:187], v[54:57]
	v_mfma_f32_16x16x32_bf16 v[42:45], v[152:155], v[184:187], v[42:45]
	v_mfma_f32_16x16x32_bf16 v[38:41], v[144:147], v[192:195], v[38:41]
	v_mfma_f32_16x16x32_bf16 v[26:29], v[152:155], v[192:195], v[26:29]
	v_mfma_f32_16x16x32_bf16 v[22:25], v[144:147], v[206:209], v[22:25]
	v_mfma_f32_16x16x32_bf16 v[10:13], v[152:155], v[206:209], v[10:13]
	v_mfma_f32_16x16x32_bf16 v[62:65], v[148:151], v[180:183], v[62:65]
	v_mfma_f32_16x16x32_bf16 v[58:61], v[156:159], v[180:183], v[58:61]
	v_mfma_f32_16x16x32_bf16 v[54:57], v[148:151], v[188:191], v[54:57]
	v_mfma_f32_16x16x32_bf16 v[42:45], v[156:159], v[188:191], v[42:45]
	v_mfma_f32_16x16x32_bf16 v[38:41], v[148:151], v[202:205], v[38:41]
	v_mfma_f32_16x16x32_bf16 v[26:29], v[156:159], v[202:205], v[26:29]
	v_mfma_f32_16x16x32_bf16 v[22:25], v[148:151], v[210:213], v[22:25]
	v_mfma_f32_16x16x32_bf16 v[10:13], v[156:159], v[210:213], v[10:13]
	s_setprio 0
	s_setprio 1
	v_mfma_f32_16x16x32_bf16 v[50:53], v[160:163], v[176:179], v[50:53]
	v_mfma_f32_16x16x32_bf16 v[46:49], v[168:171], v[176:179], v[46:49]
	v_mfma_f32_16x16x32_bf16 v[34:37], v[160:163], v[184:187], v[34:37]
	v_mfma_f32_16x16x32_bf16 v[30:33], v[168:171], v[184:187], v[30:33]
	v_mfma_f32_16x16x32_bf16 v[18:21], v[160:163], v[192:195], v[18:21]
	v_mfma_f32_16x16x32_bf16 v[14:17], v[168:171], v[192:195], v[14:17]
	v_mfma_f32_16x16x32_bf16 v[6:9], v[160:163], v[206:209], v[6:9]
	v_mfma_f32_16x16x32_bf16 v[2:5], v[168:171], v[206:209], v[2:5]
	v_mfma_f32_16x16x32_bf16 v[50:53], v[164:167], v[180:183], v[50:53]
	v_mfma_f32_16x16x32_bf16 v[46:49], v[172:175], v[180:183], v[46:49]
	v_mfma_f32_16x16x32_bf16 v[34:37], v[164:167], v[188:191], v[34:37]
	v_mfma_f32_16x16x32_bf16 v[30:33], v[172:175], v[188:191], v[30:33]
	v_mfma_f32_16x16x32_bf16 v[18:21], v[164:167], v[202:205], v[18:21]
	v_mfma_f32_16x16x32_bf16 v[14:17], v[172:175], v[202:205], v[14:17]
	v_mfma_f32_16x16x32_bf16 v[6:9], v[164:167], v[210:213], v[6:9]
	v_mfma_f32_16x16x32_bf16 v[2:5], v[172:175], v[210:213], v[2:5]
	s_setprio 0
	s_barrier
	s_add_i32 s29, 0, 0x18000
	v_add_u32_e32 v0, s29, v140
	s_add_i32 s30, 0, 0x1c000
	ds_read_b128 v[144:147], v0
	ds_read_b128 v[148:151], v0 offset:1024
	ds_read_b128 v[152:155], v0 offset:2048
	ds_read_b128 v[156:159], v0 offset:3072
	v_add_u32_e32 v0, s30, v140
	ds_read_b128 v[160:163], v0
	ds_read_b128 v[164:167], v0 offset:1024
	ds_read_b128 v[168:171], v0 offset:2048
	ds_read_b128 v[172:175], v0 offset:3072
	s_add_u32 s20, s20, 0x80000
	s_addc_u32 s21, s21, 0
	s_mov_b32 m0, s27
	v_lshl_add_u64 v[220:221], s[20:21], 0, v[132:133]
	ds_read_b128 v[176:179], v142 offset:32768
	ds_read_b128 v[180:183], v142 offset:33792
	ds_read_b128 v[184:187], v142 offset:34816
	ds_read_b128 v[188:191], v142 offset:35840
	ds_read_b128 v[192:195], v142 offset:36864
	ds_read_b128 v[202:205], v142 offset:37888
	ds_read_b128 v[206:209], v142 offset:38912
	ds_read_b128 v[210:213], v142 offset:39936
	global_load_lds_dwordx4 v[220:221], off
	v_lshl_add_u64 v[220:221], s[20:21], 0, v[130:131]
	s_mov_b32 m0, s44
	s_nop 0
	global_load_lds_dwordx4 v[220:221], off
	s_waitcnt vmcnt(8)
	s_waitcnt lgkmcnt(0)
	s_barrier
	s_setprio 1
	v_mfma_f32_16x16x32_bf16 v[126:129], v[144:147], v[176:179], v[126:129]
	v_mfma_f32_16x16x32_bf16 v[122:125], v[152:155], v[176:179], v[122:125]
	v_mfma_f32_16x16x32_bf16 v[118:121], v[144:147], v[184:187], v[118:121]
	v_mfma_f32_16x16x32_bf16 v[110:113], v[152:155], v[184:187], v[110:113]
	v_mfma_f32_16x16x32_bf16 v[102:105], v[144:147], v[192:195], v[102:105]
	v_mfma_f32_16x16x32_bf16 v[94:97], v[152:155], v[192:195], v[94:97]
	v_mfma_f32_16x16x32_bf16 v[86:89], v[144:147], v[206:209], v[86:89]
	v_mfma_f32_16x16x32_bf16 v[78:81], v[152:155], v[206:209], v[78:81]
	v_mfma_f32_16x16x32_bf16 v[126:129], v[148:151], v[180:183], v[126:129]
	v_mfma_f32_16x16x32_bf16 v[122:125], v[156:159], v[180:183], v[122:125]
	v_mfma_f32_16x16x32_bf16 v[118:121], v[148:151], v[188:191], v[118:121]
	v_mfma_f32_16x16x32_bf16 v[110:113], v[156:159], v[188:191], v[110:113]
	v_mfma_f32_16x16x32_bf16 v[102:105], v[148:151], v[202:205], v[102:105]
	v_mfma_f32_16x16x32_bf16 v[94:97], v[156:159], v[202:205], v[94:97]
	v_mfma_f32_16x16x32_bf16 v[86:89], v[148:151], v[210:213], v[86:89]
	v_mfma_f32_16x16x32_bf16 v[78:81], v[156:159], v[210:213], v[78:81]
	s_setprio 0
	s_setprio 1
	v_mfma_f32_16x16x32_bf16 v[114:117], v[160:163], v[176:179], v[114:117]
	v_mfma_f32_16x16x32_bf16 v[106:109], v[168:171], v[176:179], v[106:109]
	v_mfma_f32_16x16x32_bf16 v[98:101], v[160:163], v[184:187], v[98:101]
	v_mfma_f32_16x16x32_bf16 v[90:93], v[168:171], v[184:187], v[90:93]
	v_mfma_f32_16x16x32_bf16 v[82:85], v[160:163], v[192:195], v[82:85]
	v_mfma_f32_16x16x32_bf16 v[74:77], v[168:171], v[192:195], v[74:77]
	v_mfma_f32_16x16x32_bf16 v[70:73], v[160:163], v[206:209], v[70:73]
	v_mfma_f32_16x16x32_bf16 v[66:69], v[168:171], v[206:209], v[66:69]
	v_mfma_f32_16x16x32_bf16 v[114:117], v[164:167], v[180:183], v[114:117]
	v_mfma_f32_16x16x32_bf16 v[106:109], v[172:175], v[180:183], v[106:109]
	v_mfma_f32_16x16x32_bf16 v[98:101], v[164:167], v[188:191], v[98:101]
	v_mfma_f32_16x16x32_bf16 v[90:93], v[172:175], v[188:191], v[90:93]
	v_mfma_f32_16x16x32_bf16 v[82:85], v[164:167], v[202:205], v[82:85]
	v_mfma_f32_16x16x32_bf16 v[74:77], v[172:175], v[202:205], v[74:77]
	v_mfma_f32_16x16x32_bf16 v[70:73], v[164:167], v[210:213], v[70:73]
	v_mfma_f32_16x16x32_bf16 v[66:69], v[172:175], v[210:213], v[66:69]
	s_setprio 0
	s_barrier
; #define PG8_STAGE(bufoff, gbase, voff) do { _Pragma("unroll") for (int _i = 0; _i < 2; ++_i) \
;         __builtin_amdgcn_global_load_lds((const unsigned*)((const char*)(gbase) + (voff)[_i]), (LAS unsigned*)(lds + (bufoff) + ldsw + _i * 8192), 16, 0, 0); } while (0)
; #define PG8_WAIT_V(n) asm volatile("s_waitcnt vmcnt(" #n ")" ::: "memory")
; #define PG8_WAIT_L(n) asm volatile("s_waitcnt lgkmcnt(" #n ")" ::: "memory")
; #define PG8_BAR __builtin_amdgcn_s_barrier()
; #define PG8_SCHED __builtin_amdgcn_sched_barrier(0)
; template <bool F8 = false, class Epi, class Sched>
; __device__ __forceinline__ void gemm_phase(LAS unsigned char* lds, const int lda, const int ldb, const int K, const Sched& S, const Epi& E) {
;     ...
;             PG8_LDB(B0, 1, 0); PG8_LDB(B1, 1, 1); PG8_SCHED; PG8_LDA(At, 1, 0); PG8_STAGE(PG8_SA(0, 1), a2 + hstepA, voffA);
;             PG8_WAIT_V(8); PG8_WAIT_L(0); PG8_BAR; PG8_MMA(0, 0, At, B0); PG8_MMA(0, 1, At, B1); PG8_BAR; PG8_SCHED;
;             PG8_LDA(At, 1, 1); PG8_STAGE(PG8_SB(1, 0), b3, voffB); PG8_STAGE(PG8_SB(1, 1), b3 + hstepB, voffB); PG8_STAGE(PG8_SA(1, 0), a3, voffA);
;             PG8_WAIT_V(8); PG8_WAIT_L(0); PG8_BAR; PG8_MMA(1, 0, At, B0); PG8_MMA(1, 1, At, B1); PG8_BAR; PG8_SCHED;
;         }
;         if (wr == 0) PG8_BAR;
;         E(acc, cur, wr, wc, fr, fq);
;         if (!has_next) break;
	s_add_i32 s20, s29, s24
	v_lshl_add_u64 v[138:139], v[138:139], 0, s[40:41]
	s_mov_b32 m0, s20
	ds_read_b128 v[176:179], v142 offset:49152
	ds_read_b128 v[180:183], v142 offset:50176
	ds_read_b128 v[184:187], v142 offset:51200
	ds_read_b128 v[188:191], v142 offset:52224
	ds_read_b128 v[192:195], v142 offset:53248
	ds_read_b128 v[202:205], v142 offset:54272
	ds_read_b128 v[206:209], v142 offset:55296
	ds_read_b128 v[210:213], v142 offset:56320
	global_load_lds_dwordx4 v[138:139], off
	s_add_i32 m0, s20, 0x2000
	s_add_u32 s18, s18, 0x80080
	v_lshl_add_u64 v[138:139], v[214:215], 0, s[40:41]
	s_addc_u32 s19, s19, 0
	s_add_i32 s20, s30, s24
	global_load_lds_dwordx4 v[138:139], off
	v_lshl_add_u64 v[138:139], s[18:19], 0, v[132:133]
	s_mov_b32 m0, s20
	s_nop 0
	global_load_lds_dwordx4 v[138:139], off
	v_lshl_add_u64 v[138:139], s[18:19], 0, v[130:131]
	s_add_i32 m0, s20, 0x2000
	s_nop 0
	global_load_lds_dwordx4 v[138:139], off
	v_lshl_add_u64 v[138:139], v[216:217], 0, s[40:41]
	s_mov_b32 m0, s52
	s_nop 0
	global_load_lds_dwordx4 v[138:139], off
	v_lshl_add_u64 v[138:139], v[218:219], 0, s[40:41]
	s_mov_b32 m0, s53
	s_nop 0
	global_load_lds_dwordx4 v[138:139], off
	s_waitcnt vmcnt(8)
	s_waitcnt lgkmcnt(0)
	s_barrier
	s_setprio 1
	v_mfma_f32_16x16x32_bf16 v[62:65], v[144:147], v[176:179], v[62:65]
	v_mfma_f32_16x16x32_bf16 v[58:61], v[152:155], v[176:179], v[58:61]
	v_mfma_f32_16x16x32_bf16 v[54:57], v[144:147], v[184:187], v[54:57]
	v_mfma_f32_16x16x32_bf16 v[42:45], v[152:155], v[184:187], v[42:45]
	v_mfma_f32_16x16x32_bf16 v[38:41], v[144:147], v[192:195], v[38:41]
	v_mfma_f32_16x16x32_bf16 v[26:29], v[152:155], v[192:195], v[26:29]
	v_mfma_f32_16x16x32_bf16 v[22:25], v[144:147], v[206:209], v[22:25]
	v_mfma_f32_16x16x32_bf16 v[10:13], v[152:155], v[206:209], v[10:13]
	v_mfma_f32_16x16x32_bf16 v[62:65], v[148:151], v[180:183], v[62:65]
	v_mfma_f32_16x16x32_bf16 v[58:61], v[156:159], v[180:183], v[58:61]
	v_mfma_f32_16x16x32_bf16 v[54:57], v[148:151], v[188:191], v[54:57]
	v_mfma_f32_16x16x32_bf16 v[42:45], v[156:159], v[188:191], v[42:45]
	v_mfma_f32_16x16x32_bf16 v[38:41], v[148:151], v[202:205], v[38:41]
	v_mfma_f32_16x16x32_bf16 v[26:29], v[156:159], v[202:205], v[26:29]
	v_mfma_f32_16x16x32_bf16 v[22:25], v[148:151], v[210:213], v[22:25]
	v_mfma_f32_16x16x32_bf16 v[10:13], v[156:159], v[210:213], v[10:13]
	s_setprio 0
	s_setprio 1
	v_mfma_f32_16x16x32_bf16 v[50:53], v[160:163], v[176:179], v[50:53]
	v_mfma_f32_16x16x32_bf16 v[46:49], v[168:171], v[176:179], v[46:49]
	v_mfma_f32_16x16x32_bf16 v[34:37], v[160:163], v[184:187], v[34:37]
	v_mfma_f32_16x16x32_bf16 v[30:33], v[168:171], v[184:187], v[30:33]
	v_mfma_f32_16x16x32_bf16 v[18:21], v[160:163], v[192:195], v[18:21]
	v_mfma_f32_16x16x32_bf16 v[14:17], v[168:171], v[192:195], v[14:17]
	v_mfma_f32_16x16x32_bf16 v[6:9], v[160:163], v[206:209], v[6:9]
	v_mfma_f32_16x16x32_bf16 v[2:5], v[168:171], v[206:209], v[2:5]
	v_mfma_f32_16x16x32_bf16 v[50:53], v[164:167], v[180:183], v[50:53]
	v_mfma_f32_16x16x32_bf16 v[46:49], v[172:175], v[180:183], v[46:49]
	v_mfma_f32_16x16x32_bf16 v[34:37], v[164:167], v[188:191], v[34:37]
	v_mfma_f32_16x16x32_bf16 v[30:33], v[172:175], v[188:191], v[30:33]
	v_mfma_f32_16x16x32_bf16 v[18:21], v[164:167], v[202:205], v[18:21]
	v_mfma_f32_16x16x32_bf16 v[14:17], v[172:175], v[202:205], v[14:17]
	v_mfma_f32_16x16x32_bf16 v[6:9], v[164:167], v[210:213], v[6:9]
	v_mfma_f32_16x16x32_bf16 v[2:5], v[172:175], v[210:213], v[2:5]
	s_setprio 0
	s_barrier
	s_add_i32 s28, s28, 2
	s_add_u32 s16, s16, 0x100
	s_addc_u32 s17, s17, 0
	s_add_u32 s95, s95, 0x100
	s_addc_u32 s96, s96, 0
	s_cmp_gt_u32 s28, 5
	s_cbranch_scc0 .LBB0_835
	s_and_b64 vcc, exec, s[6:7]
	s_cbranch_vccz .LBB0_838
	s_barrier

;     __device__ __forceinline__ const char* ptrA(const Unit& u) const { return (u.sub ? A1 : A0) + (size_t)u.pm * aT; }
;     __device__ __forceinline__ const char* ptrB(const Unit& u) const { return (u.sub ? B1 : B0) + (size_t)u.pn * bT; }
;     __device__ __forceinline__ bool next(int i, Unit& u) const { const int L = i * G + c; if (L >= 256) return false; u.sub = L & 3; const int t = L >> 2; u.pm = 64 + (t >> 3); u.pn = t & 7; return true; }
; #define PG8_STAGE(bufoff, gbase, voff) do { _Pragma("unroll") for (int _i = 0; _i < 2; ++_i) \
;         __builtin_amdgcn_global_load_lds((const unsigned*)((const char*)(gbase) + (voff)[_i]), (LAS unsigned*)(lds + (bufoff) + ldsw + _i * 8192), 16, 0, 0); } while (0)
; #define PG8_WAIT_V(n) asm volatile("s_waitcnt vmcnt(" #n ")" ::: "memory")
; #define PG8_WAIT_L(n) asm volatile("s_waitcnt lgkmcnt(" #n ")" ::: "memory")
; #define PG8_BAR __builtin_amdgcn_s_barrier()
; #define PG8_SCHED __builtin_amdgcn_sched_barrier(0)
; template <bool F8 = false, class Epi, class Sched>
; __device__ __forceinline__ void gemm_phase(LAS unsigned char* lds, const int lda, const int ldb, const int K, const Sched& S, const Epi& E) {
;     ...
;         const bool has_next = S.next(ui + 1, nxt);
;         const char* nA = has_next ? S.ptrA(nxt) : cA; const char* nB = has_next ? S.ptrB(nxt) : cB;
;         for (int t = 0; t < nt; t += 2) {
;             const bool last = (t == nt - 2);
;             const char* a1 = cA + (size_t)(t + 1) * kstep;
;             const char* a2 = last ? nA : cA + (size_t)(t + 2) * kstep; const char* b2 = last ? nB : cB + (size_t)(t + 2) * kstep;
;             const char* a3 = a2 + kstep; const char* b3 = b2 + kstep;
;             PG8_LDB(B0, 0, 0); PG8_LDB(B1, 0, 1); PG8_SCHED; PG8_LDA(At, 0, 0); PG8_STAGE(PG8_SA(1, 1), a1 + hstepA, voffA);
;             PG8_WAIT_V(8); PG8_WAIT_L(0); PG8_BAR; PG8_MMA(0, 0, At, B0); PG8_MMA(0, 1, At, B1); PG8_BAR; PG8_SCHED;
;             PG8_LDA(At, 0, 1); PG8_STAGE(PG8_SB(0, 0), b2, voffB); PG8_STAGE(PG8_SB(0, 1), b2 + hstepB, voffB); PG8_STAGE(PG8_SA(0, 0), a2, voffA);
;             PG8_WAIT_V(8); PG8_WAIT_L(0); PG8_BAR; PG8_MMA(1, 0, At, B0); PG8_MMA(1, 1, At, B1); PG8_BAR; PG8_SCHED;
.LBB0_1062:
	s_add_u32 s30, vcc_lo, 0xfff80080
	s_addc_u32 s31, vcc_hi, -1
	s_add_i32 s33, 0, 0x10000
	s_cmp_eq_u32 s29, 28
	s_cselect_b32 s75, s13, s31
	s_cselect_b32 s74, s26, s30
	s_cselect_b32 s53, s9, s28
	s_cselect_b32 s52, s27, s73
	s_add_i32 s93, 0, 0x14000
	v_add_u32_e32 v152, s33, v141
	v_add_u32_e32 v168, s93, v141
	ds_read_b128 v[136:139], v152
	ds_read_b128 v[144:147], v152 offset:1024
	ds_read_b128 v[148:151], v152 offset:2048
	ds_read_b128 v[152:155], v152 offset:3072
	ds_read_b128 v[156:159], v168
	ds_read_b128 v[160:163], v168 offset:1024
	ds_read_b128 v[164:167], v168 offset:2048
	ds_read_b128 v[168:171], v168 offset:3072
	v_lshl_add_u64 v[210:211], vcc, 0, v[132:133]
	s_add_i32 m0, s19, 0xc000
	ds_read_b128 v[172:175], v143
	ds_read_b128 v[176:179], v143 offset:1024
	ds_read_b128 v[180:183], v143 offset:2048
	ds_read_b128 v[184:187], v143 offset:3072
	ds_read_b128 v[188:191], v143 offset:4096
	ds_read_b128 v[192:195], v143 offset:5120
	ds_read_b128 v[202:205], v143 offset:6144
	ds_read_b128 v[206:209], v143 offset:7168
	global_load_lds_dwordx4 v[210:211], off
	v_lshl_add_u64 v[210:211], vcc, 0, v[134:135]
	s_add_i32 m0, s19, 0xe000
	s_nop 0
	global_load_lds_dwordx4 v[210:211], off
	s_waitcnt vmcnt(8)
	s_waitcnt lgkmcnt(0)
	s_barrier
	s_setprio 1
	v_mfma_f32_16x16x32_bf16 v[126:129], v[136:139], v[172:175], v[126:129]
	v_mfma_f32_16x16x32_bf16 v[122:125], v[148:151], v[172:175], v[122:125]
	v_mfma_f32_16x16x32_bf16 v[110:113], v[136:139], v[180:183], v[110:113]
	v_mfma_f32_16x16x32_bf16 v[106:109], v[148:151], v[180:183], v[106:109]
	v_mfma_f32_16x16x32_bf16 v[94:97], v[136:139], v[188:191], v[94:97]
	v_mfma_f32_16x16x32_bf16 v[90:93], v[148:151], v[188:191], v[90:93]
	v_mfma_f32_16x16x32_bf16 v[78:81], v[136:139], v[202:205], v[78:81]
	v_mfma_f32_16x16x32_bf16 v[74:77], v[148:151], v[202:205], v[74:77]
	v_mfma_f32_16x16x32_bf16 v[126:129], v[144:147], v[176:179], v[126:129]
	v_mfma_f32_16x16x32_bf16 v[122:125], v[152:155], v[176:179], v[122:125]
	v_mfma_f32_16x16x32_bf16 v[110:113], v[144:147], v[184:187], v[110:113]
	v_mfma_f32_16x16x32_bf16 v[106:109], v[152:155], v[184:187], v[106:109]
	v_mfma_f32_16x16x32_bf16 v[94:97], v[144:147], v[192:195], v[94:97]
	v_mfma_f32_16x16x32_bf16 v[90:93], v[152:155], v[192:195], v[90:93]
	v_mfma_f32_16x16x32_bf16 v[78:81], v[144:147], v[206:209], v[78:81]
	v_mfma_f32_16x16x32_bf16 v[74:77], v[152:155], v[206:209], v[74:77]
	s_setprio 0
	s_setprio 1
	v_mfma_f32_16x16x32_bf16 v[118:121], v[156:159], v[172:175], v[118:121]
	v_mfma_f32_16x16x32_bf16 v[114:117], v[164:167], v[172:175], v[114:117]
	v_mfma_f32_16x16x32_bf16 v[102:105], v[156:159], v[180:183], v[102:105]
	v_mfma_f32_16x16x32_bf16 v[98:101], v[164:167], v[180:183], v[98:101]
	v_mfma_f32_16x16x32_bf16 v[86:89], v[156:159], v[188:191], v[86:89]
	v_mfma_f32_16x16x32_bf16 v[82:85], v[164:167], v[188:191], v[82:85]
	v_mfma_f32_16x16x32_bf16 v[70:73], v[156:159], v[202:205], v[70:73]
	v_mfma_f32_16x16x32_bf16 v[66:69], v[164:167], v[202:205], v[66:69]
	v_mfma_f32_16x16x32_bf16 v[118:121], v[160:163], v[176:179], v[118:121]
	v_mfma_f32_16x16x32_bf16 v[114:117], v[168:171], v[176:179], v[114:117]
	v_mfma_f32_16x16x32_bf16 v[102:105], v[160:163], v[184:187], v[102:105]
	v_mfma_f32_16x16x32_bf16 v[98:101], v[168:171], v[184:187], v[98:101]
	v_mfma_f32_16x16x32_bf16 v[86:89], v[160:163], v[192:195], v[86:89]
	v_mfma_f32_16x16x32_bf16 v[82:85], v[168:171], v[192:195], v[82:85]
	v_mfma_f32_16x16x32_bf16 v[70:73], v[160:163], v[206:209], v[70:73]
	v_mfma_f32_16x16x32_bf16 v[66:69], v[168:171], v[206:209], v[66:69]
	s_setprio 0
	s_barrier
	s_add_i32 s30, s33, s94
	v_lshl_add_u64 v[210:211], s[52:53], 0, v[0:1]
	s_mov_b32 m0, s30
	ds_read_b128 v[172:175], v143 offset:16384
	ds_read_b128 v[176:179], v143 offset:17408
	ds_read_b128 v[180:183], v143 offset:18432
	ds_read_b128 v[184:187], v143 offset:19456
	ds_read_b128 v[188:191], v143 offset:20480
	ds_read_b128 v[192:195], v143 offset:21504
	ds_read_b128 v[202:205], v143 offset:22528
	ds_read_b128 v[206:209], v143 offset:23552
	global_load_lds_dwordx4 v[210:211], off
	s_add_i32 m0, s30, 0x2000
	s_add_u32 s30, s52, 0x80000
	v_lshl_add_u64 v[212:213], s[52:53], 0, v[130:131]
	s_addc_u32 s31, s53, 0
	s_add_i32 s33, s93, s94
	global_load_lds_dwordx4 v[212:213], off
	v_lshl_add_u64 v[214:215], s[30:31], 0, v[0:1]
	s_mov_b32 m0, s33
	v_lshl_add_u64 v[216:217], s[74:75], 0, v[130:131]
	global_load_lds_dwordx4 v[214:215], off
	v_lshl_add_u64 v[214:215], s[30:31], 0, v[130:131]
	s_add_i32 m0, s33, 0x2000
	s_nop 0
	global_load_lds_dwordx4 v[214:215], off
	v_lshl_add_u64 v[214:215], s[74:75], 0, v[0:1]
	s_mov_b32 m0, s19
	s_nop 0
	global_load_lds_dwordx4 v[214:215], off
	s_mov_b32 m0, s56
	s_nop 0
	global_load_lds_dwordx4 v[216:217], off
	s_waitcnt vmcnt(8)
	s_waitcnt lgkmcnt(0)
	s_barrier
; #define PG8_STAGE(bufoff, gbase, voff) do { _Pragma("unroll") for (int _i = 0; _i < 2; ++_i) \
;         __builtin_amdgcn_global_load_lds((const unsigned*)((const char*)(gbase) + (voff)[_i]), (LAS unsigned*)(lds + (bufoff) + ldsw + _i * 8192), 16, 0, 0); } while (0)
; #define PG8_WAIT_V(n) asm volatile("s_waitcnt vmcnt(" #n ")" ::: "memory")
; #define PG8_WAIT_L(n) asm volatile("s_waitcnt lgkmcnt(" #n ")" ::: "memory")
; #define PG8_BAR __builtin_amdgcn_s_barrier()
; #define PG8_SCHED __builtin_amdgcn_sched_barrier(0)
; template <bool F8 = false, class Epi, class Sched>
; __device__ __forceinline__ void gemm_phase(LAS unsigned char* lds, const int lda, const int ldb, const int K, const Sched& S, const Epi& E) {
;     ...
;             PG8_WAIT_V(8); PG8_WAIT_L(0); PG8_BAR; PG8_MMA(0, 0, At, B0); PG8_MMA(0, 1, At, B1); PG8_BAR; PG8_SCHED;
;             PG8_LDA(At, 0, 1); PG8_STAGE(PG8_SB(0, 0), b2, voffB); PG8_STAGE(PG8_SB(0, 1), b2 + hstepB, voffB); PG8_STAGE(PG8_SA(0, 0), a2, voffA);
;             PG8_WAIT_V(8); PG8_WAIT_L(0); PG8_BAR; PG8_MMA(1, 0, At, B0); PG8_MMA(1, 1, At, B1); PG8_BAR; PG8_SCHED;
;             PG8_LDB(B0, 1, 0); PG8_LDB(B1, 1, 1); PG8_SCHED; PG8_LDA(At, 1, 0); PG8_STAGE(PG8_SA(0, 1), a2 + hstepA, voffA);
;             PG8_WAIT_V(8); PG8_WAIT_L(0); PG8_BAR; PG8_MMA(0, 0, At, B0); PG8_MMA(0, 1, At, B1); PG8_BAR; PG8_SCHED;
;             PG8_LDA(At, 1, 1); PG8_STAGE(PG8_SB(1, 0), b3, voffB); PG8_STAGE(PG8_SB(1, 1), b3 + hstepB, voffB); PG8_STAGE(PG8_SA(1, 0), a3, voffA);
;             PG8_WAIT_V(8); PG8_WAIT_L(0); PG8_BAR; PG8_MMA(1, 0, At, B0); PG8_MMA(1, 1, At, B1); PG8_BAR; PG8_SCHED;
	s_setprio 1
	v_mfma_f32_16x16x32_bf16 v[62:65], v[136:139], v[172:175], v[62:65]
	v_mfma_f32_16x16x32_bf16 v[58:61], v[148:151], v[172:175], v[58:61]
	v_mfma_f32_16x16x32_bf16 v[46:49], v[136:139], v[180:183], v[46:49]
	v_mfma_f32_16x16x32_bf16 v[42:45], v[148:151], v[180:183], v[42:45]
	v_mfma_f32_16x16x32_bf16 v[30:33], v[136:139], v[188:191], v[30:33]
	v_mfma_f32_16x16x32_bf16 v[26:29], v[148:151], v[188:191], v[26:29]
	v_mfma_f32_16x16x32_bf16 v[14:17], v[136:139], v[202:205], v[14:17]
	v_mfma_f32_16x16x32_bf16 v[10:13], v[148:151], v[202:205], v[10:13]
	v_mfma_f32_16x16x32_bf16 v[62:65], v[144:147], v[176:179], v[62:65]
	v_mfma_f32_16x16x32_bf16 v[58:61], v[152:155], v[176:179], v[58:61]
	v_mfma_f32_16x16x32_bf16 v[46:49], v[144:147], v[184:187], v[46:49]
	v_mfma_f32_16x16x32_bf16 v[42:45], v[152:155], v[184:187], v[42:45]
	v_mfma_f32_16x16x32_bf16 v[30:33], v[144:147], v[192:195], v[30:33]
	v_mfma_f32_16x16x32_bf16 v[26:29], v[152:155], v[192:195], v[26:29]
	v_mfma_f32_16x16x32_bf16 v[14:17], v[144:147], v[206:209], v[14:17]
	v_mfma_f32_16x16x32_bf16 v[10:13], v[152:155], v[206:209], v[10:13]
	s_setprio 0
	s_setprio 1
	v_mfma_f32_16x16x32_bf16 v[54:57], v[156:159], v[172:175], v[54:57]
	v_mfma_f32_16x16x32_bf16 v[50:53], v[164:167], v[172:175], v[50:53]
	v_mfma_f32_16x16x32_bf16 v[38:41], v[156:159], v[180:183], v[38:41]
	v_mfma_f32_16x16x32_bf16 v[34:37], v[164:167], v[180:183], v[34:37]
	v_mfma_f32_16x16x32_bf16 v[22:25], v[156:159], v[188:191], v[22:25]
	v_mfma_f32_16x16x32_bf16 v[18:21], v[164:167], v[188:191], v[18:21]
	v_mfma_f32_16x16x32_bf16 v[6:9], v[156:159], v[202:205], v[6:9]
	v_mfma_f32_16x16x32_bf16 v[2:5], v[164:167], v[202:205], v[2:5]
	v_mfma_f32_16x16x32_bf16 v[54:57], v[160:163], v[176:179], v[54:57]
	v_mfma_f32_16x16x32_bf16 v[50:53], v[168:171], v[176:179], v[50:53]
	v_mfma_f32_16x16x32_bf16 v[38:41], v[160:163], v[184:187], v[38:41]
	v_mfma_f32_16x16x32_bf16 v[34:37], v[168:171], v[184:187], v[34:37]
	v_mfma_f32_16x16x32_bf16 v[22:25], v[160:163], v[192:195], v[22:25]
	v_mfma_f32_16x16x32_bf16 v[18:21], v[168:171], v[192:195], v[18:21]
	v_mfma_f32_16x16x32_bf16 v[6:9], v[160:163], v[206:209], v[6:9]
	v_mfma_f32_16x16x32_bf16 v[2:5], v[168:171], v[206:209], v[2:5]
	s_setprio 0
	s_barrier
	s_add_i32 s33, 0, 0x18000
	s_add_i32 s93, 0, 0x1c000
	v_add_u32_e32 v152, s33, v141
	v_add_u32_e32 v168, s93, v141
	ds_read_b128 v[136:139], v152
	ds_read_b128 v[144:147], v152 offset:1024
	ds_read_b128 v[148:151], v152 offset:2048
	ds_read_b128 v[152:155], v152 offset:3072
	ds_read_b128 v[156:159], v168
	ds_read_b128 v[160:163], v168 offset:1024
	ds_read_b128 v[164:167], v168 offset:2048
	ds_read_b128 v[168:171], v168 offset:3072
	s_add_u32 s30, s74, 0x80000
	s_addc_u32 s31, s75, 0
	s_mov_b32 m0, s57
	v_lshl_add_u64 v[218:219], s[30:31], 0, v[0:1]
	ds_read_b128 v[172:175], v143 offset:32768
	ds_read_b128 v[176:179], v143 offset:33792
	ds_read_b128 v[180:183], v143 offset:34816
	ds_read_b128 v[184:187], v143 offset:35840
	ds_read_b128 v[188:191], v143 offset:36864
	ds_read_b128 v[192:195], v143 offset:37888
	ds_read_b128 v[202:205], v143 offset:38912
	ds_read_b128 v[206:209], v143 offset:39936
	global_load_lds_dwordx4 v[218:219], off
	v_lshl_add_u64 v[218:219], s[30:31], 0, v[130:131]
	s_mov_b32 m0, s96
	s_nop 0
	global_load_lds_dwordx4 v[218:219], off
	s_waitcnt vmcnt(8)
	s_waitcnt lgkmcnt(0)
	s_barrier
	s_setprio 1
	v_mfma_f32_16x16x32_bf16 v[126:129], v[136:139], v[172:175], v[126:129]
	v_mfma_f32_16x16x32_bf16 v[122:125], v[148:151], v[172:175], v[122:125]
	v_mfma_f32_16x16x32_bf16 v[110:113], v[136:139], v[180:183], v[110:113]
	v_mfma_f32_16x16x32_bf16 v[106:109], v[148:151], v[180:183], v[106:109]
	v_mfma_f32_16x16x32_bf16 v[94:97], v[136:139], v[188:191], v[94:97]
	v_mfma_f32_16x16x32_bf16 v[90:93], v[148:151], v[188:191], v[90:93]
	v_mfma_f32_16x16x32_bf16 v[78:81], v[136:139], v[202:205], v[78:81]
	v_mfma_f32_16x16x32_bf16 v[74:77], v[148:151], v[202:205], v[74:77]
	v_mfma_f32_16x16x32_bf16 v[126:129], v[144:147], v[176:179], v[126:129]
	v_mfma_f32_16x16x32_bf16 v[122:125], v[152:155], v[176:179], v[122:125]
	v_mfma_f32_16x16x32_bf16 v[110:113], v[144:147], v[184:187], v[110:113]
	v_mfma_f32_16x16x32_bf16 v[106:109], v[152:155], v[184:187], v[106:109]
	v_mfma_f32_16x16x32_bf16 v[94:97], v[144:147], v[192:195], v[94:97]
	v_mfma_f32_16x16x32_bf16 v[90:93], v[152:155], v[192:195], v[90:93]
	v_mfma_f32_16x16x32_bf16 v[78:81], v[144:147], v[206:209], v[78:81]
	v_mfma_f32_16x16x32_bf16 v[74:77], v[152:155], v[206:209], v[74:77]
	s_setprio 0
	s_setprio 1
	v_mfma_f32_16x16x32_bf16 v[118:121], v[156:159], v[172:175], v[118:121]
	v_mfma_f32_16x16x32_bf16 v[114:117], v[164:167], v[172:175], v[114:117]
	v_mfma_f32_16x16x32_bf16 v[102:105], v[156:159], v[180:183], v[102:105]
	v_mfma_f32_16x16x32_bf16 v[98:101], v[164:167], v[180:183], v[98:101]
	v_mfma_f32_16x16x32_bf16 v[86:89], v[156:159], v[188:191], v[86:89]
	v_mfma_f32_16x16x32_bf16 v[82:85], v[164:167], v[188:191], v[82:85]
	v_mfma_f32_16x16x32_bf16 v[70:73], v[156:159], v[202:205], v[70:73]
	v_mfma_f32_16x16x32_bf16 v[66:69], v[164:167], v[202:205], v[66:69]
	v_mfma_f32_16x16x32_bf16 v[118:121], v[160:163], v[176:179], v[118:121]
	v_mfma_f32_16x16x32_bf16 v[114:117], v[168:171], v[176:179], v[114:117]
	v_mfma_f32_16x16x32_bf16 v[102:105], v[160:163], v[184:187], v[102:105]
	v_mfma_f32_16x16x32_bf16 v[98:101], v[168:171], v[184:187], v[98:101]
	v_mfma_f32_16x16x32_bf16 v[86:89], v[160:163], v[192:195], v[86:89]
	v_mfma_f32_16x16x32_bf16 v[82:85], v[168:171], v[192:195], v[82:85]
	v_mfma_f32_16x16x32_bf16 v[70:73], v[160:163], v[206:209], v[70:73]
	v_mfma_f32_16x16x32_bf16 v[66:69], v[168:171], v[206:209], v[66:69]
	s_setprio 0
	s_barrier
; #define PG8_STAGE(bufoff, gbase, voff) do { _Pragma("unroll") for (int _i = 0; _i < 2; ++_i) \
;         __builtin_amdgcn_global_load_lds((const unsigned*)((const char*)(gbase) + (voff)[_i]), (LAS unsigned*)(lds + (bufoff) + ldsw + _i * 8192), 16, 0, 0); } while (0)
; #define PG8_WAIT_V(n) asm volatile("s_waitcnt vmcnt(" #n ")" ::: "memory")
; #define PG8_WAIT_L(n) asm volatile("s_waitcnt lgkmcnt(" #n ")" ::: "memory")
; #define PG8_BAR __builtin_amdgcn_s_barrier()
; #define PG8_SCHED __builtin_amdgcn_sched_barrier(0)
; template <bool F8 = false, class Epi, class Sched>
; __device__ __forceinline__ void gemm_phase(LAS unsigned char* lds, const int lda, const int ldb, const int K, const Sched& S, const Epi& E) {
;     ...
;             PG8_LDB(B0, 1, 0); PG8_LDB(B1, 1, 1); PG8_SCHED; PG8_LDA(At, 1, 0); PG8_STAGE(PG8_SA(0, 1), a2 + hstepA, voffA);
;             PG8_WAIT_V(8); PG8_WAIT_L(0); PG8_BAR; PG8_MMA(0, 0, At, B0); PG8_MMA(0, 1, At, B1); PG8_BAR; PG8_SCHED;
;             PG8_LDA(At, 1, 1); PG8_STAGE(PG8_SB(1, 0), b3, voffB); PG8_STAGE(PG8_SB(1, 1), b3 + hstepB, voffB); PG8_STAGE(PG8_SA(1, 0), a3, voffA);
;             PG8_WAIT_V(8); PG8_WAIT_L(0); PG8_BAR; PG8_MMA(1, 0, At, B0); PG8_MMA(1, 1, At, B1); PG8_BAR; PG8_SCHED;
;         }
;         if (wr == 0) PG8_BAR;
;         E(acc, cur, wr, wc, fr, fq);
;         if (!has_next) break;
	s_add_i32 s30, s33, s94
	v_lshl_add_u64 v[210:211], v[210:211], 0, s[40:41]
	s_mov_b32 m0, s30
	ds_read_b128 v[172:175], v143 offset:49152
	ds_read_b128 v[176:179], v143 offset:50176
	ds_read_b128 v[180:183], v143 offset:51200
	ds_read_b128 v[184:187], v143 offset:52224
	ds_read_b128 v[188:191], v143 offset:53248
	ds_read_b128 v[192:195], v143 offset:54272
	ds_read_b128 v[202:205], v143 offset:55296
	ds_read_b128 v[206:209], v143 offset:56320
	global_load_lds_dwordx4 v[210:211], off
	s_add_i32 m0, s30, 0x2000
	s_add_u32 s30, s52, 0x80080
	v_lshl_add_u64 v[210:211], v[212:213], 0, s[40:41]
	s_addc_u32 s31, s53, 0
	s_add_i32 s33, s93, s94
	global_load_lds_dwordx4 v[210:211], off
	v_lshl_add_u64 v[210:211], s[30:31], 0, v[0:1]
	s_mov_b32 m0, s33
	s_nop 0
	global_load_lds_dwordx4 v[210:211], off
	v_lshl_add_u64 v[210:211], s[30:31], 0, v[130:131]
	s_add_i32 m0, s33, 0x2000
	s_nop 0
	global_load_lds_dwordx4 v[210:211], off
	v_lshl_add_u64 v[210:211], v[214:215], 0, s[40:41]
	s_mov_b32 m0, s24
	s_nop 0
	global_load_lds_dwordx4 v[210:211], off
	v_lshl_add_u64 v[210:211], v[216:217], 0, s[40:41]
	s_mov_b32 m0, s25
	s_nop 0
	global_load_lds_dwordx4 v[210:211], off
	s_waitcnt vmcnt(8)
	s_waitcnt lgkmcnt(0)
	s_barrier
	s_setprio 1
	v_mfma_f32_16x16x32_bf16 v[62:65], v[136:139], v[172:175], v[62:65]
	v_mfma_f32_16x16x32_bf16 v[58:61], v[148:151], v[172:175], v[58:61]
	v_mfma_f32_16x16x32_bf16 v[46:49], v[136:139], v[180:183], v[46:49]
	v_mfma_f32_16x16x32_bf16 v[42:45], v[148:151], v[180:183], v[42:45]
	v_mfma_f32_16x16x32_bf16 v[30:33], v[136:139], v[188:191], v[30:33]
	v_mfma_f32_16x16x32_bf16 v[26:29], v[148:151], v[188:191], v[26:29]
	v_mfma_f32_16x16x32_bf16 v[14:17], v[136:139], v[202:205], v[14:17]
	v_mfma_f32_16x16x32_bf16 v[10:13], v[148:151], v[202:205], v[10:13]
	v_mfma_f32_16x16x32_bf16 v[62:65], v[144:147], v[176:179], v[62:65]
	v_mfma_f32_16x16x32_bf16 v[58:61], v[152:155], v[176:179], v[58:61]
	v_mfma_f32_16x16x32_bf16 v[46:49], v[144:147], v[184:187], v[46:49]
	v_mfma_f32_16x16x32_bf16 v[42:45], v[152:155], v[184:187], v[42:45]
	v_mfma_f32_16x16x32_bf16 v[30:33], v[144:147], v[192:195], v[30:33]
	v_mfma_f32_16x16x32_bf16 v[26:29], v[152:155], v[192:195], v[26:29]
	v_mfma_f32_16x16x32_bf16 v[14:17], v[144:147], v[206:209], v[14:17]
	v_mfma_f32_16x16x32_bf16 v[10:13], v[152:155], v[206:209], v[10:13]
	s_setprio 0
	s_setprio 1
	v_mfma_f32_16x16x32_bf16 v[54:57], v[156:159], v[172:175], v[54:57]
	v_mfma_f32_16x16x32_bf16 v[50:53], v[164:167], v[172:175], v[50:53]
	v_mfma_f32_16x16x32_bf16 v[38:41], v[156:159], v[180:183], v[38:41]
	v_mfma_f32_16x16x32_bf16 v[34:37], v[164:167], v[180:183], v[34:37]
	v_mfma_f32_16x16x32_bf16 v[22:25], v[156:159], v[188:191], v[22:25]
	v_mfma_f32_16x16x32_bf16 v[18:21], v[164:167], v[188:191], v[18:21]
	v_mfma_f32_16x16x32_bf16 v[6:9], v[156:159], v[202:205], v[6:9]
	v_mfma_f32_16x16x32_bf16 v[2:5], v[164:167], v[202:205], v[2:5]
	v_mfma_f32_16x16x32_bf16 v[54:57], v[160:163], v[176:179], v[54:57]
	v_mfma_f32_16x16x32_bf16 v[50:53], v[168:171], v[176:179], v[50:53]
	v_mfma_f32_16x16x32_bf16 v[38:41], v[160:163], v[184:187], v[38:41]
	v_mfma_f32_16x16x32_bf16 v[34:37], v[168:171], v[184:187], v[34:37]
	v_mfma_f32_16x16x32_bf16 v[22:25], v[160:163], v[192:195], v[22:25]
	v_mfma_f32_16x16x32_bf16 v[18:21], v[168:171], v[192:195], v[18:21]
	v_mfma_f32_16x16x32_bf16 v[6:9], v[160:163], v[206:209], v[6:9]
	v_mfma_f32_16x16x32_bf16 v[2:5], v[168:171], v[206:209], v[2:5]
	s_setprio 0
	s_barrier
	s_add_i32 s29, s29, 2
	s_add_u32 vcc_lo, vcc_lo, 0x100
	s_addc_u32 vcc_hi, vcc_hi, 0
	s_add_u32 s73, s73, 0x100
	s_addc_u32 s28, s28, 0
	s_cmp_gt_u32 s29, 29
	s_cbranch_scc0 .LBB0_1062
	s_and_b64 vcc, exec, s[6:7]
	s_cbranch_vccz .LBB0_1065
	s_barrier

;     __device__ __forceinline__ const char* ptrA(const Unit& u) const { return (u.sub ? A1 : A0) + (size_t)u.pm * aT; }
;     __device__ __forceinline__ const char* ptrB(const Unit& u) const { return (u.sub ? B1 : B0) + (size_t)u.pn * bT; }
;     __device__ __forceinline__ bool next(int i, Unit& u) const { const int L = i * G + c; if (L >= 256) return false; u.sub = L & 3; const int t = L >> 2; u.pm = 64 + (t >> 3); u.pn = t & 7; return true; }
; #define PG8_STAGE(bufoff, gbase, voff) do { _Pragma("unroll") for (int _i = 0; _i < 2; ++_i) \
;         __builtin_amdgcn_global_load_lds((const unsigned*)((const char*)(gbase) + (voff)[_i]), (LAS unsigned*)(lds + (bufoff) + ldsw + _i * 8192), 16, 0, 0); } while (0)
; #define PG8_WAIT_V(n) asm volatile("s_waitcnt vmcnt(" #n ")" ::: "memory")
; #define PG8_WAIT_L(n) asm volatile("s_waitcnt lgkmcnt(" #n ")" ::: "memory")
; #define PG8_BAR __builtin_amdgcn_s_barrier()
; #define PG8_SCHED __builtin_amdgcn_sched_barrier(0)
; template <bool F8 = false, class Epi, class Sched>
; __device__ __forceinline__ void gemm_phase(LAS unsigned char* lds, const int lda, const int ldb, const int K, const Sched& S, const Epi& E) {
;     ...
;         const bool has_next = S.next(ui + 1, nxt);
;         const char* nA = has_next ? S.ptrA(nxt) : cA; const char* nB = has_next ? S.ptrB(nxt) : cB;
;         for (int t = 0; t < nt; t += 2) {
;             const bool last = (t == nt - 2);
;             const char* a1 = cA + (size_t)(t + 1) * kstep;
;             const char* a2 = last ? nA : cA + (size_t)(t + 2) * kstep; const char* b2 = last ? nB : cB + (size_t)(t + 2) * kstep;
;             const char* a3 = a2 + kstep; const char* b3 = b2 + kstep;
;             PG8_LDB(B0, 0, 0); PG8_LDB(B1, 0, 1); PG8_SCHED; PG8_LDA(At, 0, 0); PG8_STAGE(PG8_SA(1, 1), a1 + hstepA, voffA);
;             PG8_WAIT_V(8); PG8_WAIT_L(0); PG8_BAR; PG8_MMA(0, 0, At, B0); PG8_MMA(0, 1, At, B1); PG8_BAR; PG8_SCHED;
;             PG8_LDA(At, 0, 1); PG8_STAGE(PG8_SB(0, 0), b2, voffB); PG8_STAGE(PG8_SB(0, 1), b2 + hstepB, voffB); PG8_STAGE(PG8_SA(0, 0), a2, voffA);
;             PG8_WAIT_V(8); PG8_WAIT_L(0); PG8_BAR; PG8_MMA(1, 0, At, B0); PG8_MMA(1, 1, At, B1); PG8_BAR; PG8_SCHED;
.LBB0_1149:
	s_add_u32 s18, s16, 0x100
	s_addc_u32 s19, s17, 0
	s_add_i32 s30, 0, 0x10000
	s_cmpk_eq_i32 s94, 0x54
	s_cselect_b32 s53, s13, s19
	s_cselect_b32 s52, s12, s18
	v_add_u32_e32 v140, s30, v143
	s_cselect_b32 s21, s15, s29
	s_cselect_b32 s20, s14, s28
	s_add_i32 s31, 0, 0x14000
	ds_read_b128 v[146:149], v140
	ds_read_b128 v[150:153], v140 offset:1024
	ds_read_b128 v[154:157], v140 offset:2048
	ds_read_b128 v[158:161], v140 offset:3072
	v_add_u32_e32 v140, s31, v143
	ds_read_b128 v[162:165], v140
	ds_read_b128 v[166:169], v140 offset:1024
	ds_read_b128 v[170:173], v140 offset:2048
	ds_read_b128 v[174:177], v140 offset:3072
	v_lshl_add_u64 v[140:141], s[16:17], 0, v[136:137]
	s_add_i32 m0, s25, 0xc000
	ds_read_b128 v[178:181], v145
	ds_read_b128 v[182:185], v145 offset:1024
	ds_read_b128 v[186:189], v145 offset:2048
	ds_read_b128 v[190:193], v145 offset:3072
	ds_read_b128 v[202:205], v145 offset:4096
	ds_read_b128 v[206:209], v145 offset:5120
	ds_read_b128 v[210:213], v145 offset:6144
	ds_read_b128 v[214:217], v145 offset:7168
	global_load_lds_dwordx4 v[140:141], off
	v_lshl_add_u64 v[140:141], s[16:17], 0, v[138:139]
	s_add_i32 m0, s25, 0xe000
	s_nop 0
	global_load_lds_dwordx4 v[140:141], off
	s_waitcnt vmcnt(8)
	s_waitcnt lgkmcnt(0)
	s_barrier
	s_setprio 1
	v_mfma_f32_16x16x32_bf16 v[126:129], v[146:149], v[178:181], v[126:129]
	v_mfma_f32_16x16x32_bf16 v[122:125], v[154:157], v[178:181], v[122:125]
	v_mfma_f32_16x16x32_bf16 v[118:121], v[146:149], v[186:189], v[118:121]
	v_mfma_f32_16x16x32_bf16 v[110:113], v[154:157], v[186:189], v[110:113]
	v_mfma_f32_16x16x32_bf16 v[102:105], v[146:149], v[202:205], v[102:105]
	v_mfma_f32_16x16x32_bf16 v[94:97], v[154:157], v[202:205], v[94:97]
	v_mfma_f32_16x16x32_bf16 v[86:89], v[146:149], v[210:213], v[86:89]
	v_mfma_f32_16x16x32_bf16 v[78:81], v[154:157], v[210:213], v[78:81]
	v_mfma_f32_16x16x32_bf16 v[126:129], v[150:153], v[182:185], v[126:129]
	v_mfma_f32_16x16x32_bf16 v[122:125], v[158:161], v[182:185], v[122:125]
	v_mfma_f32_16x16x32_bf16 v[118:121], v[150:153], v[190:193], v[118:121]
	v_mfma_f32_16x16x32_bf16 v[110:113], v[158:161], v[190:193], v[110:113]
	v_mfma_f32_16x16x32_bf16 v[102:105], v[150:153], v[206:209], v[102:105]
	v_mfma_f32_16x16x32_bf16 v[94:97], v[158:161], v[206:209], v[94:97]
	v_mfma_f32_16x16x32_bf16 v[86:89], v[150:153], v[214:217], v[86:89]
	v_mfma_f32_16x16x32_bf16 v[78:81], v[158:161], v[214:217], v[78:81]
	s_setprio 0
	s_setprio 1
	v_mfma_f32_16x16x32_bf16 v[114:117], v[162:165], v[178:181], v[114:117]
	v_mfma_f32_16x16x32_bf16 v[106:109], v[170:173], v[178:181], v[106:109]
	v_mfma_f32_16x16x32_bf16 v[98:101], v[162:165], v[186:189], v[98:101]
	v_mfma_f32_16x16x32_bf16 v[90:93], v[170:173], v[186:189], v[90:93]
	v_mfma_f32_16x16x32_bf16 v[82:85], v[162:165], v[202:205], v[82:85]
	v_mfma_f32_16x16x32_bf16 v[74:77], v[170:173], v[202:205], v[74:77]
	v_mfma_f32_16x16x32_bf16 v[70:73], v[162:165], v[210:213], v[70:73]
	v_mfma_f32_16x16x32_bf16 v[66:69], v[170:173], v[210:213], v[66:69]
	v_mfma_f32_16x16x32_bf16 v[114:117], v[166:169], v[182:185], v[114:117]
	v_mfma_f32_16x16x32_bf16 v[106:109], v[174:177], v[182:185], v[106:109]
	v_mfma_f32_16x16x32_bf16 v[98:101], v[166:169], v[190:193], v[98:101]
	v_mfma_f32_16x16x32_bf16 v[90:93], v[174:177], v[190:193], v[90:93]
	v_mfma_f32_16x16x32_bf16 v[82:85], v[166:169], v[206:209], v[82:85]
	v_mfma_f32_16x16x32_bf16 v[74:77], v[174:177], v[206:209], v[74:77]
	v_mfma_f32_16x16x32_bf16 v[70:73], v[166:169], v[214:217], v[70:73]
	v_mfma_f32_16x16x32_bf16 v[66:69], v[174:177], v[214:217], v[66:69]
	s_setprio 0
	s_barrier
	s_add_i32 s16, s30, s24
	v_lshl_add_u64 v[140:141], s[20:21], 0, v[0:1]
	s_mov_b32 m0, s16
	ds_read_b128 v[178:181], v145 offset:16384
	ds_read_b128 v[182:185], v145 offset:17408
	ds_read_b128 v[186:189], v145 offset:18432
	ds_read_b128 v[190:193], v145 offset:19456
	ds_read_b128 v[202:205], v145 offset:20480
	ds_read_b128 v[206:209], v145 offset:21504
	ds_read_b128 v[210:213], v145 offset:22528
	ds_read_b128 v[214:217], v145 offset:23552
	global_load_lds_dwordx4 v[140:141], off
	s_add_i32 m0, s16, 0x2000
	s_add_u32 s16, s20, 0x160000
	v_lshl_add_u64 v[194:195], s[20:21], 0, v[130:131]
	s_addc_u32 s17, s21, 0
	s_add_i32 s30, s31, s24
	global_load_lds_dwordx4 v[194:195], off
	v_lshl_add_u64 v[218:219], s[16:17], 0, v[0:1]
	s_mov_b32 m0, s30
	v_lshl_add_u64 v[220:221], s[52:53], 0, v[132:133]
	global_load_lds_dwordx4 v[218:219], off
	v_lshl_add_u64 v[218:219], s[16:17], 0, v[130:131]
	s_add_i32 m0, s30, 0x2000
	s_nop 0
	global_load_lds_dwordx4 v[218:219], off
	v_lshl_add_u64 v[218:219], s[52:53], 0, v[134:135]
	s_mov_b32 m0, s25
	s_nop 0
	global_load_lds_dwordx4 v[218:219], off
	s_mov_b32 m0, s26
	s_nop 0
	global_load_lds_dwordx4 v[220:221], off
	s_waitcnt vmcnt(8)
	s_waitcnt lgkmcnt(0)
	s_barrier
; #define PG8_STAGE(bufoff, gbase, voff) do { _Pragma("unroll") for (int _i = 0; _i < 2; ++_i) \
;         __builtin_amdgcn_global_load_lds((const unsigned*)((const char*)(gbase) + (voff)[_i]), (LAS unsigned*)(lds + (bufoff) + ldsw + _i * 8192), 16, 0, 0); } while (0)
; #define PG8_WAIT_V(n) asm volatile("s_waitcnt vmcnt(" #n ")" ::: "memory")
; #define PG8_WAIT_L(n) asm volatile("s_waitcnt lgkmcnt(" #n ")" ::: "memory")
; #define PG8_BAR __builtin_amdgcn_s_barrier()
; #define PG8_SCHED __builtin_amdgcn_sched_barrier(0)
; template <bool F8 = false, class Epi, class Sched>
; __device__ __forceinline__ void gemm_phase(LAS unsigned char* lds, const int lda, const int ldb, const int K, const Sched& S, const Epi& E) {
;     ...
;             PG8_WAIT_V(8); PG8_WAIT_L(0); PG8_BAR; PG8_MMA(0, 0, At, B0); PG8_MMA(0, 1, At, B1); PG8_BAR; PG8_SCHED;
;             PG8_LDA(At, 0, 1); PG8_STAGE(PG8_SB(0, 0), b2, voffB); PG8_STAGE(PG8_SB(0, 1), b2 + hstepB, voffB); PG8_STAGE(PG8_SA(0, 0), a2, voffA);
;             PG8_WAIT_V(8); PG8_WAIT_L(0); PG8_BAR; PG8_MMA(1, 0, At, B0); PG8_MMA(1, 1, At, B1); PG8_BAR; PG8_SCHED;
;             PG8_LDB(B0, 1, 0); PG8_LDB(B1, 1, 1); PG8_SCHED; PG8_LDA(At, 1, 0); PG8_STAGE(PG8_SA(0, 1), a2 + hstepA, voffA);
;             PG8_WAIT_V(8); PG8_WAIT_L(0); PG8_BAR; PG8_MMA(0, 0, At, B0); PG8_MMA(0, 1, At, B1); PG8_BAR; PG8_SCHED;
;             PG8_LDA(At, 1, 1); PG8_STAGE(PG8_SB(1, 0), b3, voffB); PG8_STAGE(PG8_SB(1, 1), b3 + hstepB, voffB); PG8_STAGE(PG8_SA(1, 0), a3, voffA);
;             PG8_WAIT_V(8); PG8_WAIT_L(0); PG8_BAR; PG8_MMA(1, 0, At, B0); PG8_MMA(1, 1, At, B1); PG8_BAR; PG8_SCHED;
	s_setprio 1
	v_mfma_f32_16x16x32_bf16 v[62:65], v[146:149], v[178:181], v[62:65]
	v_mfma_f32_16x16x32_bf16 v[58:61], v[154:157], v[178:181], v[58:61]
	v_mfma_f32_16x16x32_bf16 v[54:57], v[146:149], v[186:189], v[54:57]
	v_mfma_f32_16x16x32_bf16 v[46:49], v[154:157], v[186:189], v[46:49]
	v_mfma_f32_16x16x32_bf16 v[38:41], v[146:149], v[202:205], v[38:41]
	v_mfma_f32_16x16x32_bf16 v[30:33], v[154:157], v[202:205], v[30:33]
	v_mfma_f32_16x16x32_bf16 v[22:25], v[146:149], v[210:213], v[22:25]
	v_mfma_f32_16x16x32_bf16 v[14:17], v[154:157], v[210:213], v[14:17]
	v_mfma_f32_16x16x32_bf16 v[62:65], v[150:153], v[182:185], v[62:65]
	v_mfma_f32_16x16x32_bf16 v[58:61], v[158:161], v[182:185], v[58:61]
	v_mfma_f32_16x16x32_bf16 v[54:57], v[150:153], v[190:193], v[54:57]
	v_mfma_f32_16x16x32_bf16 v[46:49], v[158:161], v[190:193], v[46:49]
	v_mfma_f32_16x16x32_bf16 v[38:41], v[150:153], v[206:209], v[38:41]
	v_mfma_f32_16x16x32_bf16 v[30:33], v[158:161], v[206:209], v[30:33]
	v_mfma_f32_16x16x32_bf16 v[22:25], v[150:153], v[214:217], v[22:25]
	v_mfma_f32_16x16x32_bf16 v[14:17], v[158:161], v[214:217], v[14:17]
	s_setprio 0
	s_setprio 1
	v_mfma_f32_16x16x32_bf16 v[50:53], v[162:165], v[178:181], v[50:53]
	v_mfma_f32_16x16x32_bf16 v[42:45], v[170:173], v[178:181], v[42:45]
	v_mfma_f32_16x16x32_bf16 v[34:37], v[162:165], v[186:189], v[34:37]
	v_mfma_f32_16x16x32_bf16 v[26:29], v[170:173], v[186:189], v[26:29]
	v_mfma_f32_16x16x32_bf16 v[18:21], v[162:165], v[202:205], v[18:21]
	v_mfma_f32_16x16x32_bf16 v[10:13], v[170:173], v[202:205], v[10:13]
	v_mfma_f32_16x16x32_bf16 v[6:9], v[162:165], v[210:213], v[6:9]
	v_mfma_f32_16x16x32_bf16 v[2:5], v[170:173], v[210:213], v[2:5]
	v_mfma_f32_16x16x32_bf16 v[50:53], v[166:169], v[182:185], v[50:53]
	v_mfma_f32_16x16x32_bf16 v[42:45], v[174:177], v[182:185], v[42:45]
	v_mfma_f32_16x16x32_bf16 v[34:37], v[166:169], v[190:193], v[34:37]
	v_mfma_f32_16x16x32_bf16 v[26:29], v[174:177], v[190:193], v[26:29]
	v_mfma_f32_16x16x32_bf16 v[18:21], v[166:169], v[206:209], v[18:21]
	v_mfma_f32_16x16x32_bf16 v[10:13], v[174:177], v[206:209], v[10:13]
	v_mfma_f32_16x16x32_bf16 v[6:9], v[166:169], v[214:217], v[6:9]
	v_mfma_f32_16x16x32_bf16 v[2:5], v[174:177], v[214:217], v[2:5]
	s_setprio 0
	s_barrier
	s_add_i32 s30, 0, 0x18000
	s_add_i32 s31, 0, 0x1c000
	v_add_u32_e32 v158, s30, v143
	v_add_u32_e32 v174, s31, v143
	ds_read_b128 v[146:149], v158
	ds_read_b128 v[150:153], v158 offset:1024
	ds_read_b128 v[154:157], v158 offset:2048
	ds_read_b128 v[158:161], v158 offset:3072
	ds_read_b128 v[162:165], v174
	ds_read_b128 v[166:169], v174 offset:1024
	ds_read_b128 v[170:173], v174 offset:2048
	ds_read_b128 v[174:177], v174 offset:3072
	s_add_u32 s16, s52, 0x160000
	s_addc_u32 s17, s53, 0
	s_mov_b32 m0, s27
	v_lshl_add_u64 v[222:223], s[16:17], 0, v[134:135]
	ds_read_b128 v[178:181], v145 offset:32768
	ds_read_b128 v[182:185], v145 offset:33792
	ds_read_b128 v[186:189], v145 offset:34816
	ds_read_b128 v[190:193], v145 offset:35840
	ds_read_b128 v[202:205], v145 offset:36864
	ds_read_b128 v[206:209], v145 offset:37888
	ds_read_b128 v[210:213], v145 offset:38912
	ds_read_b128 v[214:217], v145 offset:39936
	global_load_lds_dwordx4 v[222:223], off
	v_lshl_add_u64 v[222:223], s[16:17], 0, v[132:133]
	s_mov_b32 m0, s44
	s_nop 0
	global_load_lds_dwordx4 v[222:223], off
	s_waitcnt vmcnt(8)
	s_waitcnt lgkmcnt(0)
	s_barrier
	s_setprio 1
	v_mfma_f32_16x16x32_bf16 v[126:129], v[146:149], v[178:181], v[126:129]
	v_mfma_f32_16x16x32_bf16 v[122:125], v[154:157], v[178:181], v[122:125]
	v_mfma_f32_16x16x32_bf16 v[118:121], v[146:149], v[186:189], v[118:121]
	v_mfma_f32_16x16x32_bf16 v[110:113], v[154:157], v[186:189], v[110:113]
	v_mfma_f32_16x16x32_bf16 v[102:105], v[146:149], v[202:205], v[102:105]
	v_mfma_f32_16x16x32_bf16 v[94:97], v[154:157], v[202:205], v[94:97]
	v_mfma_f32_16x16x32_bf16 v[86:89], v[146:149], v[210:213], v[86:89]
	v_mfma_f32_16x16x32_bf16 v[78:81], v[154:157], v[210:213], v[78:81]
	v_mfma_f32_16x16x32_bf16 v[126:129], v[150:153], v[182:185], v[126:129]
	v_mfma_f32_16x16x32_bf16 v[122:125], v[158:161], v[182:185], v[122:125]
	v_mfma_f32_16x16x32_bf16 v[118:121], v[150:153], v[190:193], v[118:121]
	v_mfma_f32_16x16x32_bf16 v[110:113], v[158:161], v[190:193], v[110:113]
	v_mfma_f32_16x16x32_bf16 v[102:105], v[150:153], v[206:209], v[102:105]
	v_mfma_f32_16x16x32_bf16 v[94:97], v[158:161], v[206:209], v[94:97]
	v_mfma_f32_16x16x32_bf16 v[86:89], v[150:153], v[214:217], v[86:89]
	v_mfma_f32_16x16x32_bf16 v[78:81], v[158:161], v[214:217], v[78:81]
	s_setprio 0
	s_setprio 1
	v_mfma_f32_16x16x32_bf16 v[114:117], v[162:165], v[178:181], v[114:117]
	v_mfma_f32_16x16x32_bf16 v[106:109], v[170:173], v[178:181], v[106:109]
	v_mfma_f32_16x16x32_bf16 v[98:101], v[162:165], v[186:189], v[98:101]
	v_mfma_f32_16x16x32_bf16 v[90:93], v[170:173], v[186:189], v[90:93]
	v_mfma_f32_16x16x32_bf16 v[82:85], v[162:165], v[202:205], v[82:85]
	v_mfma_f32_16x16x32_bf16 v[74:77], v[170:173], v[202:205], v[74:77]
	v_mfma_f32_16x16x32_bf16 v[70:73], v[162:165], v[210:213], v[70:73]
	v_mfma_f32_16x16x32_bf16 v[66:69], v[170:173], v[210:213], v[66:69]
	v_mfma_f32_16x16x32_bf16 v[114:117], v[166:169], v[182:185], v[114:117]
	v_mfma_f32_16x16x32_bf16 v[106:109], v[174:177], v[182:185], v[106:109]
	v_mfma_f32_16x16x32_bf16 v[98:101], v[166:169], v[190:193], v[98:101]
	v_mfma_f32_16x16x32_bf16 v[90:93], v[174:177], v[190:193], v[90:93]
	v_mfma_f32_16x16x32_bf16 v[82:85], v[166:169], v[206:209], v[82:85]
	v_mfma_f32_16x16x32_bf16 v[74:77], v[174:177], v[206:209], v[74:77]
	v_mfma_f32_16x16x32_bf16 v[70:73], v[166:169], v[214:217], v[70:73]
	v_mfma_f32_16x16x32_bf16 v[66:69], v[174:177], v[214:217], v[66:69]
	s_setprio 0
	s_barrier
; #define PG8_STAGE(bufoff, gbase, voff) do { _Pragma("unroll") for (int _i = 0; _i < 2; ++_i) \
;         __builtin_amdgcn_global_load_lds((const unsigned*)((const char*)(gbase) + (voff)[_i]), (LAS unsigned*)(lds + (bufoff) + ldsw + _i * 8192), 16, 0, 0); } while (0)
; #define PG8_WAIT_V(n) asm volatile("s_waitcnt vmcnt(" #n ")" ::: "memory")
; #define PG8_WAIT_L(n) asm volatile("s_waitcnt lgkmcnt(" #n ")" ::: "memory")
; #define PG8_BAR __builtin_amdgcn_s_barrier()
; #define PG8_SCHED __builtin_amdgcn_sched_barrier(0)
; template <bool F8 = false, class Epi, class Sched>
; __device__ __forceinline__ void gemm_phase(LAS unsigned char* lds, const int lda, const int ldb, const int K, const Sched& S, const Epi& E) {
;     ...
;             PG8_LDB(B0, 1, 0); PG8_LDB(B1, 1, 1); PG8_SCHED; PG8_LDA(At, 1, 0); PG8_STAGE(PG8_SA(0, 1), a2 + hstepA, voffA);
;             PG8_WAIT_V(8); PG8_WAIT_L(0); PG8_BAR; PG8_MMA(0, 0, At, B0); PG8_MMA(0, 1, At, B1); PG8_BAR; PG8_SCHED;
;             PG8_LDA(At, 1, 1); PG8_STAGE(PG8_SB(1, 0), b3, voffB); PG8_STAGE(PG8_SB(1, 1), b3 + hstepB, voffB); PG8_STAGE(PG8_SA(1, 0), a3, voffA);
;             PG8_WAIT_V(8); PG8_WAIT_L(0); PG8_BAR; PG8_MMA(1, 0, At, B0); PG8_MMA(1, 1, At, B1); PG8_BAR; PG8_SCHED;
;         }
;         if (wr == 0) PG8_BAR;
;         E(acc, cur, wr, wc, fr, fq);
;         if (!has_next) break;
	s_add_i32 s16, s30, s24
	v_lshl_add_u64 v[140:141], v[140:141], 0, s[40:41]
	s_mov_b32 m0, s16
	ds_read_b128 v[178:181], v145 offset:49152
	ds_read_b128 v[182:185], v145 offset:50176
	ds_read_b128 v[186:189], v145 offset:51200
	ds_read_b128 v[190:193], v145 offset:52224
	ds_read_b128 v[202:205], v145 offset:53248
	ds_read_b128 v[206:209], v145 offset:54272
	ds_read_b128 v[210:213], v145 offset:55296
	ds_read_b128 v[214:217], v145 offset:56320
	global_load_lds_dwordx4 v[140:141], off
	s_add_i32 m0, s16, 0x2000
	s_add_u32 s16, s20, 0x160080
	v_lshl_add_u64 v[140:141], v[194:195], 0, s[40:41]
	s_addc_u32 s17, s21, 0
	s_add_i32 s20, s31, s24
	global_load_lds_dwordx4 v[140:141], off
	v_lshl_add_u64 v[140:141], s[16:17], 0, v[0:1]
	s_mov_b32 m0, s20
	s_nop 0
	global_load_lds_dwordx4 v[140:141], off
	v_lshl_add_u64 v[140:141], s[16:17], 0, v[130:131]
	s_add_i32 m0, s20, 0x2000
	s_nop 0
	global_load_lds_dwordx4 v[140:141], off
	v_lshl_add_u64 v[140:141], v[218:219], 0, s[40:41]
	s_mov_b32 m0, s56
	s_nop 0
	global_load_lds_dwordx4 v[140:141], off
	v_lshl_add_u64 v[140:141], v[220:221], 0, s[40:41]
	s_mov_b32 m0, s57
	s_nop 0
	global_load_lds_dwordx4 v[140:141], off
	s_waitcnt vmcnt(8)
	s_waitcnt lgkmcnt(0)
	s_barrier
	s_setprio 1
	v_mfma_f32_16x16x32_bf16 v[62:65], v[146:149], v[178:181], v[62:65]
	v_mfma_f32_16x16x32_bf16 v[58:61], v[154:157], v[178:181], v[58:61]
	v_mfma_f32_16x16x32_bf16 v[54:57], v[146:149], v[186:189], v[54:57]
	v_mfma_f32_16x16x32_bf16 v[46:49], v[154:157], v[186:189], v[46:49]
	v_mfma_f32_16x16x32_bf16 v[38:41], v[146:149], v[202:205], v[38:41]
	v_mfma_f32_16x16x32_bf16 v[30:33], v[154:157], v[202:205], v[30:33]
	v_mfma_f32_16x16x32_bf16 v[22:25], v[146:149], v[210:213], v[22:25]
	v_mfma_f32_16x16x32_bf16 v[14:17], v[154:157], v[210:213], v[14:17]
	v_mfma_f32_16x16x32_bf16 v[62:65], v[150:153], v[182:185], v[62:65]
	v_mfma_f32_16x16x32_bf16 v[58:61], v[158:161], v[182:185], v[58:61]
	v_mfma_f32_16x16x32_bf16 v[54:57], v[150:153], v[190:193], v[54:57]
	v_mfma_f32_16x16x32_bf16 v[46:49], v[158:161], v[190:193], v[46:49]
	v_mfma_f32_16x16x32_bf16 v[38:41], v[150:153], v[206:209], v[38:41]
	v_mfma_f32_16x16x32_bf16 v[30:33], v[158:161], v[206:209], v[30:33]
	v_mfma_f32_16x16x32_bf16 v[22:25], v[150:153], v[214:217], v[22:25]
	v_mfma_f32_16x16x32_bf16 v[14:17], v[158:161], v[214:217], v[14:17]
	s_setprio 0
	s_setprio 1
	v_mfma_f32_16x16x32_bf16 v[50:53], v[162:165], v[178:181], v[50:53]
	v_mfma_f32_16x16x32_bf16 v[42:45], v[170:173], v[178:181], v[42:45]
	v_mfma_f32_16x16x32_bf16 v[34:37], v[162:165], v[186:189], v[34:37]
	v_mfma_f32_16x16x32_bf16 v[26:29], v[170:173], v[186:189], v[26:29]
	v_mfma_f32_16x16x32_bf16 v[18:21], v[162:165], v[202:205], v[18:21]
	v_mfma_f32_16x16x32_bf16 v[10:13], v[170:173], v[202:205], v[10:13]
	v_mfma_f32_16x16x32_bf16 v[6:9], v[162:165], v[210:213], v[6:9]
	v_mfma_f32_16x16x32_bf16 v[2:5], v[170:173], v[210:213], v[2:5]
	v_mfma_f32_16x16x32_bf16 v[50:53], v[166:169], v[182:185], v[50:53]
	v_mfma_f32_16x16x32_bf16 v[42:45], v[174:177], v[182:185], v[42:45]
	v_mfma_f32_16x16x32_bf16 v[34:37], v[166:169], v[190:193], v[34:37]
	v_mfma_f32_16x16x32_bf16 v[26:29], v[174:177], v[190:193], v[26:29]
	v_mfma_f32_16x16x32_bf16 v[18:21], v[166:169], v[206:209], v[18:21]
	v_mfma_f32_16x16x32_bf16 v[10:13], v[174:177], v[206:209], v[10:13]
	v_mfma_f32_16x16x32_bf16 v[6:9], v[166:169], v[214:217], v[6:9]
	v_mfma_f32_16x16x32_bf16 v[2:5], v[174:177], v[214:217], v[2:5]
	s_setprio 0
	s_barrier
	s_add_i32 s94, s94, 2
	s_add_u32 s28, s28, 0x100
	s_addc_u32 s29, s29, 0
	s_cmpk_gt_u32 s94, 0x55
	s_mov_b64 s[16:17], s[18:19]
	s_cbranch_scc0 .LBB0_1149
	s_and_b64 vcc, exec, s[6:7]
	s_cbranch_vccz .LBB0_1152
	s_barrier

;     __device__ __forceinline__ const char* ptrA(const Unit& u) const { return (u.sub ? A1 : A0) + (size_t)u.pm * aT; }
;     __device__ __forceinline__ const char* ptrB(const Unit& u) const { return (u.sub ? B1 : B0) + (size_t)u.pn * bT; }
;     __device__ __forceinline__ bool next(int i, Unit& u) const { const int L = i * G + c; if (L >= 256) return false; u.sub = L & 3; const int t = L >> 2; u.pm = 64 + (t >> 3); u.pn = t & 7; return true; }
; #define PG8_STAGE(bufoff, gbase, voff) do { _Pragma("unroll") for (int _i = 0; _i < 2; ++_i) \
;         __builtin_amdgcn_global_load_lds((const unsigned*)((const char*)(gbase) + (voff)[_i]), (LAS unsigned*)(lds + (bufoff) + ldsw + _i * 8192), 16, 0, 0); } while (0)
; #define PG8_WAIT_V(n) asm volatile("s_waitcnt vmcnt(" #n ")" ::: "memory")
; #define PG8_WAIT_L(n) asm volatile("s_waitcnt lgkmcnt(" #n ")" ::: "memory")
; #define PG8_BAR __builtin_amdgcn_s_barrier()
; #define PG8_SCHED __builtin_amdgcn_sched_barrier(0)
; template <bool F8 = false, class Epi, class Sched>
; __device__ __forceinline__ void gemm_phase(LAS unsigned char* lds, const int lda, const int ldb, const int K, const Sched& S, const Epi& E) {
;     ...
;         const bool has_next = S.next(ui + 1, nxt);
;         const char* nA = has_next ? S.ptrA(nxt) : cA; const char* nB = has_next ? S.ptrB(nxt) : cB;
;         for (int t = 0; t < nt; t += 2) {
;             const bool last = (t == nt - 2);
;             const char* a1 = cA + (size_t)(t + 1) * kstep;
;             const char* a2 = last ? nA : cA + (size_t)(t + 2) * kstep; const char* b2 = last ? nB : cB + (size_t)(t + 2) * kstep;
;             const char* a3 = a2 + kstep; const char* b3 = b2 + kstep;
;             PG8_LDB(B0, 0, 0); PG8_LDB(B1, 0, 1); PG8_SCHED; PG8_LDA(At, 0, 0); PG8_STAGE(PG8_SA(1, 1), a1 + hstepA, voffA);
;             PG8_WAIT_V(8); PG8_WAIT_L(0); PG8_BAR; PG8_MMA(0, 0, At, B0); PG8_MMA(0, 1, At, B1); PG8_BAR; PG8_SCHED;
;             PG8_LDA(At, 0, 1); PG8_STAGE(PG8_SB(0, 0), b2, voffB); PG8_STAGE(PG8_SB(0, 1), b2 + hstepB, voffB); PG8_STAGE(PG8_SA(0, 0), a2, voffA);
;             PG8_WAIT_V(8); PG8_WAIT_L(0); PG8_BAR; PG8_MMA(1, 0, At, B0); PG8_MMA(1, 1, At, B1); PG8_BAR; PG8_SCHED;
.LBB0_1177:
	s_add_u32 s18, s16, 0x100
	s_addc_u32 s19, s17, 0
	s_add_i32 s30, 0, 0x10000
	s_cmp_eq_u32 s96, 18
	s_cselect_b32 s53, s13, s19
	s_cselect_b32 s52, s12, s18
	v_add_u32_e32 v0, s30, v140
	s_cselect_b32 s21, s15, s29
	s_cselect_b32 s20, s14, s28
	s_add_i32 s31, 0, 0x14000
	ds_read_b128 v[144:147], v0
	ds_read_b128 v[148:151], v0 offset:1024
	ds_read_b128 v[152:155], v0 offset:2048
	ds_read_b128 v[156:159], v0 offset:3072
	v_add_u32_e32 v0, s31, v140
	ds_read_b128 v[160:163], v0
	ds_read_b128 v[164:167], v0 offset:1024
	ds_read_b128 v[168:171], v0 offset:2048
	ds_read_b128 v[172:175], v0 offset:3072
	v_lshl_add_u64 v[138:139], s[16:17], 0, v[134:135]
	s_add_i32 m0, s25, 0xc000
	ds_read_b128 v[176:179], v142
	ds_read_b128 v[180:183], v142 offset:1024
	ds_read_b128 v[184:187], v142 offset:2048
	ds_read_b128 v[188:191], v142 offset:3072
	ds_read_b128 v[192:195], v142 offset:4096
	ds_read_b128 v[202:205], v142 offset:5120
	ds_read_b128 v[206:209], v142 offset:6144
	ds_read_b128 v[210:213], v142 offset:7168
	global_load_lds_dwordx4 v[138:139], off
	v_lshl_add_u64 v[138:139], s[16:17], 0, v[136:137]
	s_add_i32 m0, s25, 0xe000
	s_nop 0
	global_load_lds_dwordx4 v[138:139], off
	s_waitcnt vmcnt(8)
	s_waitcnt lgkmcnt(0)
	s_barrier
	s_setprio 1
	v_mfma_f32_16x16x32_bf16 v[126:129], v[144:147], v[176:179], v[126:129]
	v_mfma_f32_16x16x32_bf16 v[122:125], v[152:155], v[176:179], v[122:125]
	v_mfma_f32_16x16x32_bf16 v[118:121], v[144:147], v[184:187], v[118:121]
	v_mfma_f32_16x16x32_bf16 v[110:113], v[152:155], v[184:187], v[110:113]
	v_mfma_f32_16x16x32_bf16 v[102:105], v[144:147], v[192:195], v[102:105]
	v_mfma_f32_16x16x32_bf16 v[94:97], v[152:155], v[192:195], v[94:97]
	v_mfma_f32_16x16x32_bf16 v[86:89], v[144:147], v[206:209], v[86:89]
	v_mfma_f32_16x16x32_bf16 v[78:81], v[152:155], v[206:209], v[78:81]
	v_mfma_f32_16x16x32_bf16 v[126:129], v[148:151], v[180:183], v[126:129]
	v_mfma_f32_16x16x32_bf16 v[122:125], v[156:159], v[180:183], v[122:125]
	v_mfma_f32_16x16x32_bf16 v[118:121], v[148:151], v[188:191], v[118:121]
	v_mfma_f32_16x16x32_bf16 v[110:113], v[156:159], v[188:191], v[110:113]
	v_mfma_f32_16x16x32_bf16 v[102:105], v[148:151], v[202:205], v[102:105]
	v_mfma_f32_16x16x32_bf16 v[94:97], v[156:159], v[202:205], v[94:97]
	v_mfma_f32_16x16x32_bf16 v[86:89], v[148:151], v[210:213], v[86:89]
	v_mfma_f32_16x16x32_bf16 v[78:81], v[156:159], v[210:213], v[78:81]
	s_setprio 0
	s_setprio 1
	v_mfma_f32_16x16x32_bf16 v[114:117], v[160:163], v[176:179], v[114:117]
	v_mfma_f32_16x16x32_bf16 v[106:109], v[168:171], v[176:179], v[106:109]
	v_mfma_f32_16x16x32_bf16 v[98:101], v[160:163], v[184:187], v[98:101]
	v_mfma_f32_16x16x32_bf16 v[90:93], v[168:171], v[184:187], v[90:93]
	v_mfma_f32_16x16x32_bf16 v[82:85], v[160:163], v[192:195], v[82:85]
	v_mfma_f32_16x16x32_bf16 v[74:77], v[168:171], v[192:195], v[74:77]
	v_mfma_f32_16x16x32_bf16 v[70:73], v[160:163], v[206:209], v[70:73]
	v_mfma_f32_16x16x32_bf16 v[66:69], v[168:171], v[206:209], v[66:69]
	v_mfma_f32_16x16x32_bf16 v[114:117], v[164:167], v[180:183], v[114:117]
	v_mfma_f32_16x16x32_bf16 v[106:109], v[172:175], v[180:183], v[106:109]
	v_mfma_f32_16x16x32_bf16 v[98:101], v[164:167], v[188:191], v[98:101]
	v_mfma_f32_16x16x32_bf16 v[90:93], v[172:175], v[188:191], v[90:93]
	v_mfma_f32_16x16x32_bf16 v[82:85], v[164:167], v[202:205], v[82:85]
	v_mfma_f32_16x16x32_bf16 v[74:77], v[172:175], v[202:205], v[74:77]
	v_mfma_f32_16x16x32_bf16 v[70:73], v[164:167], v[210:213], v[70:73]
	v_mfma_f32_16x16x32_bf16 v[66:69], v[172:175], v[210:213], v[66:69]
	s_setprio 0
	s_barrier
	s_add_i32 s16, s30, s24
	v_lshl_add_u64 v[138:139], s[20:21], 0, v[132:133]
	s_mov_b32 m0, s16
	ds_read_b128 v[176:179], v142 offset:16384
	ds_read_b128 v[180:183], v142 offset:17408
	ds_read_b128 v[184:187], v142 offset:18432
	ds_read_b128 v[188:191], v142 offset:19456
	ds_read_b128 v[192:195], v142 offset:20480
	ds_read_b128 v[202:205], v142 offset:21504
	ds_read_b128 v[206:209], v142 offset:22528
	ds_read_b128 v[210:213], v142 offset:23552
	global_load_lds_dwordx4 v[138:139], off
	s_add_i32 m0, s16, 0x2000
	s_add_u32 s16, s20, 0x160000
	v_lshl_add_u64 v[214:215], s[20:21], 0, v[130:131]
	s_addc_u32 s17, s21, 0
	s_add_i32 s30, s31, s24
	global_load_lds_dwordx4 v[214:215], off
	v_lshl_add_u64 v[216:217], s[16:17], 0, v[132:133]
	s_mov_b32 m0, s30
	v_lshl_add_u64 v[218:219], s[52:53], 0, v[130:131]
	global_load_lds_dwordx4 v[216:217], off
	v_lshl_add_u64 v[216:217], s[16:17], 0, v[130:131]
	s_add_i32 m0, s30, 0x2000
	s_nop 0
	global_load_lds_dwordx4 v[216:217], off
	v_lshl_add_u64 v[216:217], s[52:53], 0, v[132:133]
	s_mov_b32 m0, s25
	s_nop 0
	global_load_lds_dwordx4 v[216:217], off
	s_mov_b32 m0, s26
	s_nop 0
	global_load_lds_dwordx4 v[218:219], off
	s_waitcnt vmcnt(8)
	s_waitcnt lgkmcnt(0)
	s_barrier
; #define PG8_STAGE(bufoff, gbase, voff) do { _Pragma("unroll") for (int _i = 0; _i < 2; ++_i) \
;         __builtin_amdgcn_global_load_lds((const unsigned*)((const char*)(gbase) + (voff)[_i]), (LAS unsigned*)(lds + (bufoff) + ldsw + _i * 8192), 16, 0, 0); } while (0)
; #define PG8_WAIT_V(n) asm volatile("s_waitcnt vmcnt(" #n ")" ::: "memory")
; #define PG8_WAIT_L(n) asm volatile("s_waitcnt lgkmcnt(" #n ")" ::: "memory")
; #define PG8_BAR __builtin_amdgcn_s_barrier()
; #define PG8_SCHED __builtin_amdgcn_sched_barrier(0)
; template <bool F8 = false, class Epi, class Sched>
; __device__ __forceinline__ void gemm_phase(LAS unsigned char* lds, const int lda, const int ldb, const int K, const Sched& S, const Epi& E) {
;     ...
;             PG8_WAIT_V(8); PG8_WAIT_L(0); PG8_BAR; PG8_MMA(0, 0, At, B0); PG8_MMA(0, 1, At, B1); PG8_BAR; PG8_SCHED;
;             PG8_LDA(At, 0, 1); PG8_STAGE(PG8_SB(0, 0), b2, voffB); PG8_STAGE(PG8_SB(0, 1), b2 + hstepB, voffB); PG8_STAGE(PG8_SA(0, 0), a2, voffA);
;             PG8_WAIT_V(8); PG8_WAIT_L(0); PG8_BAR; PG8_MMA(1, 0, At, B0); PG8_MMA(1, 1, At, B1); PG8_BAR; PG8_SCHED;
;             PG8_LDB(B0, 1, 0); PG8_LDB(B1, 1, 1); PG8_SCHED; PG8_LDA(At, 1, 0); PG8_STAGE(PG8_SA(0, 1), a2 + hstepA, voffA);
;             PG8_WAIT_V(8); PG8_WAIT_L(0); PG8_BAR; PG8_MMA(0, 0, At, B0); PG8_MMA(0, 1, At, B1); PG8_BAR; PG8_SCHED;
;             PG8_LDA(At, 1, 1); PG8_STAGE(PG8_SB(1, 0), b3, voffB); PG8_STAGE(PG8_SB(1, 1), b3 + hstepB, voffB); PG8_STAGE(PG8_SA(1, 0), a3, voffA);
;             PG8_WAIT_V(8); PG8_WAIT_L(0); PG8_BAR; PG8_MMA(1, 0, At, B0); PG8_MMA(1, 1, At, B1); PG8_BAR; PG8_SCHED;
	s_setprio 1
	v_mfma_f32_16x16x32_bf16 v[62:65], v[144:147], v[176:179], v[62:65]
	v_mfma_f32_16x16x32_bf16 v[58:61], v[152:155], v[176:179], v[58:61]
	v_mfma_f32_16x16x32_bf16 v[54:57], v[144:147], v[184:187], v[54:57]
	v_mfma_f32_16x16x32_bf16 v[42:45], v[152:155], v[184:187], v[42:45]
	v_mfma_f32_16x16x32_bf16 v[38:41], v[144:147], v[192:195], v[38:41]
	v_mfma_f32_16x16x32_bf16 v[26:29], v[152:155], v[192:195], v[26:29]
	v_mfma_f32_16x16x32_bf16 v[22:25], v[144:147], v[206:209], v[22:25]
	v_mfma_f32_16x16x32_bf16 v[10:13], v[152:155], v[206:209], v[10:13]
	v_mfma_f32_16x16x32_bf16 v[62:65], v[148:151], v[180:183], v[62:65]
	v_mfma_f32_16x16x32_bf16 v[58:61], v[156:159], v[180:183], v[58:61]
	v_mfma_f32_16x16x32_bf16 v[54:57], v[148:151], v[188:191], v[54:57]
	v_mfma_f32_16x16x32_bf16 v[42:45], v[156:159], v[188:191], v[42:45]
	v_mfma_f32_16x16x32_bf16 v[38:41], v[148:151], v[202:205], v[38:41]
	v_mfma_f32_16x16x32_bf16 v[26:29], v[156:159], v[202:205], v[26:29]
	v_mfma_f32_16x16x32_bf16 v[22:25], v[148:151], v[210:213], v[22:25]
	v_mfma_f32_16x16x32_bf16 v[10:13], v[156:159], v[210:213], v[10:13]
	s_setprio 0
	s_setprio 1
	v_mfma_f32_16x16x32_bf16 v[50:53], v[160:163], v[176:179], v[50:53]
	v_mfma_f32_16x16x32_bf16 v[46:49], v[168:171], v[176:179], v[46:49]
	v_mfma_f32_16x16x32_bf16 v[34:37], v[160:163], v[184:187], v[34:37]
	v_mfma_f32_16x16x32_bf16 v[30:33], v[168:171], v[184:187], v[30:33]
	v_mfma_f32_16x16x32_bf16 v[18:21], v[160:163], v[192:195], v[18:21]
	v_mfma_f32_16x16x32_bf16 v[14:17], v[168:171], v[192:195], v[14:17]
	v_mfma_f32_16x16x32_bf16 v[6:9], v[160:163], v[206:209], v[6:9]
	v_mfma_f32_16x16x32_bf16 v[2:5], v[168:171], v[206:209], v[2:5]
	v_mfma_f32_16x16x32_bf16 v[50:53], v[164:167], v[180:183], v[50:53]
	v_mfma_f32_16x16x32_bf16 v[46:49], v[172:175], v[180:183], v[46:49]
	v_mfma_f32_16x16x32_bf16 v[34:37], v[164:167], v[188:191], v[34:37]
	v_mfma_f32_16x16x32_bf16 v[30:33], v[172:175], v[188:191], v[30:33]
	v_mfma_f32_16x16x32_bf16 v[18:21], v[164:167], v[202:205], v[18:21]
	v_mfma_f32_16x16x32_bf16 v[14:17], v[172:175], v[202:205], v[14:17]
	v_mfma_f32_16x16x32_bf16 v[6:9], v[164:167], v[210:213], v[6:9]
	v_mfma_f32_16x16x32_bf16 v[2:5], v[172:175], v[210:213], v[2:5]
	s_setprio 0
	s_barrier
	s_add_i32 s30, 0, 0x18000
	v_add_u32_e32 v0, s30, v140
	s_add_i32 s31, 0, 0x1c000
	ds_read_b128 v[144:147], v0
	ds_read_b128 v[148:151], v0 offset:1024
	ds_read_b128 v[152:155], v0 offset:2048
	ds_read_b128 v[156:159], v0 offset:3072
	v_add_u32_e32 v0, s31, v140
	ds_read_b128 v[160:163], v0
	ds_read_b128 v[164:167], v0 offset:1024
	ds_read_b128 v[168:171], v0 offset:2048
	ds_read_b128 v[172:175], v0 offset:3072
	s_add_u32 s16, s52, 0x160000
	s_addc_u32 s17, s53, 0
	s_mov_b32 m0, s27
	v_lshl_add_u64 v[220:221], s[16:17], 0, v[132:133]
	ds_read_b128 v[176:179], v142 offset:32768
	ds_read_b128 v[180:183], v142 offset:33792
	ds_read_b128 v[184:187], v142 offset:34816
	ds_read_b128 v[188:191], v142 offset:35840
	ds_read_b128 v[192:195], v142 offset:36864
	ds_read_b128 v[202:205], v142 offset:37888
	ds_read_b128 v[206:209], v142 offset:38912
	ds_read_b128 v[210:213], v142 offset:39936
	global_load_lds_dwordx4 v[220:221], off
	v_lshl_add_u64 v[220:221], s[16:17], 0, v[130:131]
	s_mov_b32 m0, s44
	s_nop 0
	global_load_lds_dwordx4 v[220:221], off
	s_waitcnt vmcnt(8)
	s_waitcnt lgkmcnt(0)
	s_barrier
	s_setprio 1
	v_mfma_f32_16x16x32_bf16 v[126:129], v[144:147], v[176:179], v[126:129]
	v_mfma_f32_16x16x32_bf16 v[122:125], v[152:155], v[176:179], v[122:125]
	v_mfma_f32_16x16x32_bf16 v[118:121], v[144:147], v[184:187], v[118:121]
	v_mfma_f32_16x16x32_bf16 v[110:113], v[152:155], v[184:187], v[110:113]
	v_mfma_f32_16x16x32_bf16 v[102:105], v[144:147], v[192:195], v[102:105]
	v_mfma_f32_16x16x32_bf16 v[94:97], v[152:155], v[192:195], v[94:97]
	v_mfma_f32_16x16x32_bf16 v[86:89], v[144:147], v[206:209], v[86:89]
	v_mfma_f32_16x16x32_bf16 v[78:81], v[152:155], v[206:209], v[78:81]
	v_mfma_f32_16x16x32_bf16 v[126:129], v[148:151], v[180:183], v[126:129]
	v_mfma_f32_16x16x32_bf16 v[122:125], v[156:159], v[180:183], v[122:125]
	v_mfma_f32_16x16x32_bf16 v[118:121], v[148:151], v[188:191], v[118:121]
	v_mfma_f32_16x16x32_bf16 v[110:113], v[156:159], v[188:191], v[110:113]
	v_mfma_f32_16x16x32_bf16 v[102:105], v[148:151], v[202:205], v[102:105]
	v_mfma_f32_16x16x32_bf16 v[94:97], v[156:159], v[202:205], v[94:97]
	v_mfma_f32_16x16x32_bf16 v[86:89], v[148:151], v[210:213], v[86:89]
	v_mfma_f32_16x16x32_bf16 v[78:81], v[156:159], v[210:213], v[78:81]
	s_setprio 0
	s_setprio 1
	v_mfma_f32_16x16x32_bf16 v[114:117], v[160:163], v[176:179], v[114:117]
	v_mfma_f32_16x16x32_bf16 v[106:109], v[168:171], v[176:179], v[106:109]
	v_mfma_f32_16x16x32_bf16 v[98:101], v[160:163], v[184:187], v[98:101]
	v_mfma_f32_16x16x32_bf16 v[90:93], v[168:171], v[184:187], v[90:93]
	v_mfma_f32_16x16x32_bf16 v[82:85], v[160:163], v[192:195], v[82:85]
	v_mfma_f32_16x16x32_bf16 v[74:77], v[168:171], v[192:195], v[74:77]
	v_mfma_f32_16x16x32_bf16 v[70:73], v[160:163], v[206:209], v[70:73]
	v_mfma_f32_16x16x32_bf16 v[66:69], v[168:171], v[206:209], v[66:69]
	v_mfma_f32_16x16x32_bf16 v[114:117], v[164:167], v[180:183], v[114:117]
	v_mfma_f32_16x16x32_bf16 v[106:109], v[172:175], v[180:183], v[106:109]
	v_mfma_f32_16x16x32_bf16 v[98:101], v[164:167], v[188:191], v[98:101]
	v_mfma_f32_16x16x32_bf16 v[90:93], v[172:175], v[188:191], v[90:93]
	v_mfma_f32_16x16x32_bf16 v[82:85], v[164:167], v[202:205], v[82:85]
	v_mfma_f32_16x16x32_bf16 v[74:77], v[172:175], v[202:205], v[74:77]
	v_mfma_f32_16x16x32_bf16 v[70:73], v[164:167], v[210:213], v[70:73]
	v_mfma_f32_16x16x32_bf16 v[66:69], v[172:175], v[210:213], v[66:69]
	s_setprio 0
	s_barrier
; #define PG8_STAGE(bufoff, gbase, voff) do { _Pragma("unroll") for (int _i = 0; _i < 2; ++_i) \
;         __builtin_amdgcn_global_load_lds((const unsigned*)((const char*)(gbase) + (voff)[_i]), (LAS unsigned*)(lds + (bufoff) + ldsw + _i * 8192), 16, 0, 0); } while (0)
; #define PG8_WAIT_V(n) asm volatile("s_waitcnt vmcnt(" #n ")" ::: "memory")
; #define PG8_WAIT_L(n) asm volatile("s_waitcnt lgkmcnt(" #n ")" ::: "memory")
; #define PG8_BAR __builtin_amdgcn_s_barrier()
; #define PG8_SCHED __builtin_amdgcn_sched_barrier(0)
; template <bool F8 = false, class Epi, class Sched>
; __device__ __forceinline__ void gemm_phase(LAS unsigned char* lds, const int lda, const int ldb, const int K, const Sched& S, const Epi& E) {
;     ...
;             PG8_LDB(B0, 1, 0); PG8_LDB(B1, 1, 1); PG8_SCHED; PG8_LDA(At, 1, 0); PG8_STAGE(PG8_SA(0, 1), a2 + hstepA, voffA);
;             PG8_WAIT_V(8); PG8_WAIT_L(0); PG8_BAR; PG8_MMA(0, 0, At, B0); PG8_MMA(0, 1, At, B1); PG8_BAR; PG8_SCHED;
;             PG8_LDA(At, 1, 1); PG8_STAGE(PG8_SB(1, 0), b3, voffB); PG8_STAGE(PG8_SB(1, 1), b3 + hstepB, voffB); PG8_STAGE(PG8_SA(1, 0), a3, voffA);
;             PG8_WAIT_V(8); PG8_WAIT_L(0); PG8_BAR; PG8_MMA(1, 0, At, B0); PG8_MMA(1, 1, At, B1); PG8_BAR; PG8_SCHED;
;         }
;         if (wr == 0) PG8_BAR;
;         E(acc, cur, wr, wc, fr, fq);
;         if (!has_next) break;
	s_add_i32 s16, s30, s24
	v_lshl_add_u64 v[138:139], v[138:139], 0, s[40:41]
	s_mov_b32 m0, s16
	ds_read_b128 v[176:179], v142 offset:49152
	ds_read_b128 v[180:183], v142 offset:50176
	ds_read_b128 v[184:187], v142 offset:51200
	ds_read_b128 v[188:191], v142 offset:52224
	ds_read_b128 v[192:195], v142 offset:53248
	ds_read_b128 v[202:205], v142 offset:54272
	ds_read_b128 v[206:209], v142 offset:55296
	ds_read_b128 v[210:213], v142 offset:56320
	global_load_lds_dwordx4 v[138:139], off
	s_add_i32 m0, s16, 0x2000
	s_add_u32 s16, s20, 0x160080
	v_lshl_add_u64 v[138:139], v[214:215], 0, s[40:41]
	s_addc_u32 s17, s21, 0
	s_add_i32 s20, s31, s24
	global_load_lds_dwordx4 v[138:139], off
	v_lshl_add_u64 v[138:139], s[16:17], 0, v[132:133]
	s_mov_b32 m0, s20
	s_nop 0
	global_load_lds_dwordx4 v[138:139], off
	v_lshl_add_u64 v[138:139], s[16:17], 0, v[130:131]
	s_add_i32 m0, s20, 0x2000
	s_nop 0
	global_load_lds_dwordx4 v[138:139], off
	v_lshl_add_u64 v[138:139], v[216:217], 0, s[40:41]
	s_mov_b32 m0, s56
	s_nop 0
	global_load_lds_dwordx4 v[138:139], off
	v_lshl_add_u64 v[138:139], v[218:219], 0, s[40:41]
	s_mov_b32 m0, s57
	s_nop 0
	global_load_lds_dwordx4 v[138:139], off
	s_waitcnt vmcnt(8)
	s_waitcnt lgkmcnt(0)
	s_barrier
	s_setprio 1
	v_mfma_f32_16x16x32_bf16 v[62:65], v[144:147], v[176:179], v[62:65]
	v_mfma_f32_16x16x32_bf16 v[58:61], v[152:155], v[176:179], v[58:61]
	v_mfma_f32_16x16x32_bf16 v[54:57], v[144:147], v[184:187], v[54:57]
	v_mfma_f32_16x16x32_bf16 v[42:45], v[152:155], v[184:187], v[42:45]
	v_mfma_f32_16x16x32_bf16 v[38:41], v[144:147], v[192:195], v[38:41]
	v_mfma_f32_16x16x32_bf16 v[26:29], v[152:155], v[192:195], v[26:29]
	v_mfma_f32_16x16x32_bf16 v[22:25], v[144:147], v[206:209], v[22:25]
	v_mfma_f32_16x16x32_bf16 v[10:13], v[152:155], v[206:209], v[10:13]
	v_mfma_f32_16x16x32_bf16 v[62:65], v[148:151], v[180:183], v[62:65]
	v_mfma_f32_16x16x32_bf16 v[58:61], v[156:159], v[180:183], v[58:61]
	v_mfma_f32_16x16x32_bf16 v[54:57], v[148:151], v[188:191], v[54:57]
	v_mfma_f32_16x16x32_bf16 v[42:45], v[156:159], v[188:191], v[42:45]
	v_mfma_f32_16x16x32_bf16 v[38:41], v[148:151], v[202:205], v[38:41]
	v_mfma_f32_16x16x32_bf16 v[26:29], v[156:159], v[202:205], v[26:29]
	v_mfma_f32_16x16x32_bf16 v[22:25], v[148:151], v[210:213], v[22:25]
	v_mfma_f32_16x16x32_bf16 v[10:13], v[156:159], v[210:213], v[10:13]
	s_setprio 0
	s_setprio 1
	v_mfma_f32_16x16x32_bf16 v[50:53], v[160:163], v[176:179], v[50:53]
	v_mfma_f32_16x16x32_bf16 v[46:49], v[168:171], v[176:179], v[46:49]
	v_mfma_f32_16x16x32_bf16 v[34:37], v[160:163], v[184:187], v[34:37]
	v_mfma_f32_16x16x32_bf16 v[30:33], v[168:171], v[184:187], v[30:33]
	v_mfma_f32_16x16x32_bf16 v[18:21], v[160:163], v[192:195], v[18:21]
	v_mfma_f32_16x16x32_bf16 v[14:17], v[168:171], v[192:195], v[14:17]
	v_mfma_f32_16x16x32_bf16 v[6:9], v[160:163], v[206:209], v[6:9]
	v_mfma_f32_16x16x32_bf16 v[2:5], v[168:171], v[206:209], v[2:5]
	v_mfma_f32_16x16x32_bf16 v[50:53], v[164:167], v[180:183], v[50:53]
	v_mfma_f32_16x16x32_bf16 v[46:49], v[172:175], v[180:183], v[46:49]
	v_mfma_f32_16x16x32_bf16 v[34:37], v[164:167], v[188:191], v[34:37]
	v_mfma_f32_16x16x32_bf16 v[30:33], v[172:175], v[188:191], v[30:33]
	v_mfma_f32_16x16x32_bf16 v[18:21], v[164:167], v[202:205], v[18:21]
	v_mfma_f32_16x16x32_bf16 v[14:17], v[172:175], v[202:205], v[14:17]
	v_mfma_f32_16x16x32_bf16 v[6:9], v[164:167], v[210:213], v[6:9]
	v_mfma_f32_16x16x32_bf16 v[2:5], v[172:175], v[210:213], v[2:5]
	s_setprio 0
	s_barrier
	s_add_i32 s96, s96, 2
	s_add_u32 s28, s28, 0x100
	s_addc_u32 s29, s29, 0
	s_cmp_gt_u32 s96, 19
	s_mov_b64 s[16:17], s[18:19]
	s_cbranch_scc0 .LBB0_1177
	s_and_b64 vcc, exec, s[8:9]
	s_cbranch_vccz .LBB0_1180
	s_barrier
